# attention far-path: exp interleaved in PV MFMA shadow, no rot stagger, permlane max; EpiZ residual loads hoisted ahead of stores
# speedup vs baseline: 1.0076x; 1.0076x over previous
.LBB0_576:
	s_nop 3
	ds_bpermute_b32 v0, v214, v65
	s_lshl_b32 s80, s9, 7
	s_waitcnt lgkmcnt(0)
	v_max3_f32 v250, v65, v0, s77
	v_sub_f32_e32 v1, v64, v250
	v_fmamk_f32 v2, v32, 0x3fb8aa3b, v1
	v_exp_f32_e32 v80, v2
	v_fmamk_f32 v2, v34, 0x3fb8aa3b, v1
	v_exp_f32_e32 v82, v2
	v_fmamk_f32 v2, v35, 0x3fb8aa3b, v1
	v_exp_f32_e32 v83, v2
	v_fmamk_f32 v2, v36, 0x3fb8aa3b, v1
	v_exp_f32_e32 v84, v2
	v_fmamk_f32 v2, v37, 0x3fb8aa3b, v1
	v_exp_f32_e32 v85, v2
	v_fmamk_f32 v2, v38, 0x3fb8aa3b, v1
	v_exp_f32_e32 v86, v2
	v_fmamk_f32 v2, v39, 0x3fb8aa3b, v1
	v_exp_f32_e32 v87, v2
	v_fmamk_f32 v2, v40, 0x3fb8aa3b, v1
	v_exp_f32_e32 v88, v2
	v_fmamk_f32 v2, v41, 0x3fb8aa3b, v1
	v_exp_f32_e32 v89, v2
	v_fmamk_f32 v2, v42, 0x3fb8aa3b, v1
	v_exp_f32_e32 v90, v2
	v_fmamk_f32 v2, v43, 0x3fb8aa3b, v1
	v_exp_f32_e32 v91, v2
	v_fmamk_f32 v2, v44, 0x3fb8aa3b, v1
	v_exp_f32_e32 v92, v2
	v_fmamk_f32 v2, v45, 0x3fb8aa3b, v1
	v_exp_f32_e32 v93, v2
	v_fmamk_f32 v2, v46, 0x3fb8aa3b, v1
	v_exp_f32_e32 v94, v2
	v_fmamk_f32 v2, v47, 0x3fb8aa3b, v1
	v_exp_f32_e32 v95, v2
	v_fmamk_f32 v2, v48, 0x3fb8aa3b, v1
	v_exp_f32_e32 v125, v2
	v_fmamk_f32 v2, v49, 0x3fb8aa3b, v1
	v_exp_f32_e32 v133, v2
	v_fmamk_f32 v2, v50, 0x3fb8aa3b, v1
	v_exp_f32_e32 v134, v2
	v_fmamk_f32 v2, v51, 0x3fb8aa3b, v1
	v_exp_f32_e32 v135, v2
	v_fmamk_f32 v2, v52, 0x3fb8aa3b, v1
	v_exp_f32_e32 v154, v2
	v_fmamk_f32 v2, v53, 0x3fb8aa3b, v1
	v_exp_f32_e32 v155, v2
	v_fmamk_f32 v2, v54, 0x3fb8aa3b, v1
	v_exp_f32_e32 v156, v2
	v_fmamk_f32 v2, v55, 0x3fb8aa3b, v1
	v_exp_f32_e32 v157, v2
	v_fmamk_f32 v2, v56, 0x3fb8aa3b, v1
	v_exp_f32_e32 v158, v2
	v_fmamk_f32 v2, v57, 0x3fb8aa3b, v1
	v_exp_f32_e32 v159, v2
	v_fmamk_f32 v2, v58, 0x3fb8aa3b, v1
	v_sub_f32_e32 v0, 0xf149f2ca, v250
	v_exp_f32_e32 v160, v2
	v_fmamk_f32 v2, v59, 0x3fb8aa3b, v1
	v_exp_f32_e32 v0, v0
	v_exp_f32_e32 v161, v2
	v_fmamk_f32 v2, v60, 0x3fb8aa3b, v1
	v_exp_f32_e32 v162, v2
	v_fmamk_f32 v2, v61, 0x3fb8aa3b, v1
	v_fmamk_f32 v3, v33, 0x3fb8aa3b, v1
	v_exp_f32_e32 v163, v2
	v_fmamk_f32 v2, v62, 0x3fb8aa3b, v1
	v_fmac_f32_e32 v1, 0x3fb8aa3b, v63
	v_cmp_lt_f32_e32 vcc, s77, v250
	v_exp_f32_e32 v81, v3
	v_exp_f32_e32 v164, v2
	v_exp_f32_e32 v166, v1
	s_cmp_lg_u64 vcc, 0
	v_mul_f32_e32 v165, 0, v0
	s_cselect_b64 vcc, -1, 0
	v_cndmask_b32_e32 v0, 0, v165, vcc
	v_mov_b32_e32 v1, v0
	v_mov_b32_e32 v2, v0
	v_mov_b32_e32 v3, v0
	v_mov_b32_e32 v4, v0
	v_mov_b32_e32 v5, v0
	v_mov_b32_e32 v6, v0
	v_mov_b32_e32 v7, v0
	v_mov_b32_e32 v8, v0
	v_mov_b32_e32 v9, v0
	v_mov_b32_e32 v10, v0
	v_mov_b32_e32 v11, v0
	v_mov_b32_e32 v12, v0
	v_mov_b32_e32 v13, v0
	v_mov_b32_e32 v14, v0
	v_mov_b32_e32 v15, v0
	v_cvt_pk_bf16_f32 v76, v80, v81
	v_cvt_pk_bf16_f32 v77, v82, v83
	v_cvt_pk_bf16_f32 v78, v84, v85
	v_cvt_pk_bf16_f32 v79, v86, v87
	v_cvt_pk_bf16_f32 v72, v88, v89
	v_cvt_pk_bf16_f32 v73, v90, v91
	v_cvt_pk_bf16_f32 v74, v92, v93
	v_cvt_pk_bf16_f32 v75, v94, v95
	v_cvt_pk_bf16_f32 v68, v125, v133
	v_cvt_pk_bf16_f32 v69, v134, v135
	v_cvt_pk_bf16_f32 v70, v154, v155
	v_cvt_pk_bf16_f32 v71, v156, v157
	v_cvt_pk_bf16_f32 v64, v158, v159
	v_cvt_pk_bf16_f32 v65, v160, v161
	v_cvt_pk_bf16_f32 v66, v162, v163
	v_cvt_pk_bf16_f32 v67, v164, v166
	v_cndmask_b32_e64 v16, 0, 1, s[16:17]
	v_cmp_ne_u32_e64 s[4:5], 1, v16
	v_mov_b64_e32 v[30:31], v[14:15]
	v_mov_b64_e32 v[46:47], v[14:15]
	v_mov_b64_e32 v[62:63], v[14:15]
	s_andn2_b64 vcc, exec, s[16:17]
	v_mov_b64_e32 v[28:29], v[12:13]
	v_mov_b64_e32 v[26:27], v[10:11]
	v_mov_b64_e32 v[24:25], v[8:9]
	v_mov_b64_e32 v[22:23], v[6:7]
	v_mov_b64_e32 v[20:21], v[4:5]
	v_mov_b64_e32 v[18:19], v[2:3]
	v_mov_b64_e32 v[16:17], v[0:1]
	v_mov_b64_e32 v[44:45], v[12:13]
	v_mov_b64_e32 v[42:43], v[10:11]
	v_mov_b64_e32 v[40:41], v[8:9]
	v_mov_b64_e32 v[38:39], v[6:7]
	v_mov_b64_e32 v[36:37], v[4:5]
	v_mov_b64_e32 v[34:35], v[2:3]
	v_mov_b64_e32 v[32:33], v[0:1]
	v_mov_b64_e32 v[60:61], v[12:13]
	v_mov_b64_e32 v[58:59], v[10:11]
	v_mov_b64_e32 v[56:57], v[8:9]
	v_mov_b64_e32 v[54:55], v[6:7]
	v_mov_b64_e32 v[52:53], v[4:5]
	v_mov_b64_e32 v[50:51], v[2:3]
	v_mov_b64_e32 v[48:49], v[0:1]
	ds_read_b64_tr_b16 v[16:17], v230 offset:34816
	ds_read_b64_tr_b16 v[20:21], v230 offset:34880
	ds_read_b64_tr_b16 v[140:141], v230 offset:34944
	ds_read_b64_tr_b16 v[144:145], v230 offset:35008
	ds_read_b64_tr_b16 v[18:19], v230 offset:37376
	ds_read_b64_tr_b16 v[22:23], v230 offset:37440
	ds_read_b64_tr_b16 v[142:143], v230 offset:37504
	ds_read_b64_tr_b16 v[146:147], v230 offset:37568
	s_waitcnt lgkmcnt(3)
	v_mfma_f32_32x32x16_bf16 v[48:63], v[16:19], v[76:79], v[0:15]
	s_waitcnt lgkmcnt(2)
	v_mfma_f32_32x32x16_bf16 v[32:47], v[20:23], v[76:79], v[0:15]
	s_waitcnt lgkmcnt(1)
	v_mfma_f32_32x32x16_bf16 v[16:31], v[140:143], v[76:79], v[0:15]
	ds_read_b64_tr_b16 v[140:141], v230 offset:39936
	ds_read_b64_tr_b16 v[148:149], v230 offset:40000
	ds_read_b64_tr_b16 v[168:169], v230 offset:40064
	ds_read_b64_tr_b16 v[172:173], v230 offset:40128
	ds_read_b64_tr_b16 v[142:143], v230 offset:42496
	ds_read_b64_tr_b16 v[150:151], v230 offset:42560
	ds_read_b64_tr_b16 v[170:171], v230 offset:42624
	ds_read_b64_tr_b16 v[174:175], v230 offset:42688
	s_waitcnt lgkmcnt(8)
	v_mfma_f32_32x32x16_bf16 v[0:15], v[144:147], v[76:79], v[0:15]
	s_waitcnt lgkmcnt(3)
	v_mfma_f32_32x32x16_bf16 v[48:63], v[140:143], v[72:75], v[48:63]
	s_waitcnt lgkmcnt(2)
	v_mfma_f32_32x32x16_bf16 v[32:47], v[148:151], v[72:75], v[32:47]
	s_waitcnt lgkmcnt(1)
	v_mfma_f32_32x32x16_bf16 v[16:31], v[168:171], v[72:75], v[16:31]
	ds_read_b64_tr_b16 v[140:141], v230 offset:45056
	ds_read_b64_tr_b16 v[144:145], v230 offset:45120
	ds_read_b64_tr_b16 v[148:149], v230 offset:45184
	ds_read_b64_tr_b16 v[168:169], v230 offset:45248
	ds_read_b64_tr_b16 v[142:143], v230 offset:47616
	ds_read_b64_tr_b16 v[146:147], v230 offset:47680
	ds_read_b64_tr_b16 v[150:151], v230 offset:47744
	ds_read_b64_tr_b16 v[170:171], v230 offset:47808
	s_waitcnt lgkmcnt(8)
	v_mfma_f32_32x32x16_bf16 v[0:15], v[172:175], v[72:75], v[0:15]
	s_waitcnt lgkmcnt(3)
	v_mfma_f32_32x32x16_bf16 v[48:63], v[140:143], v[68:71], v[48:63]
	s_waitcnt lgkmcnt(2)
	v_mfma_f32_32x32x16_bf16 v[32:47], v[144:147], v[68:71], v[32:47]
	s_waitcnt lgkmcnt(1)
	v_mfma_f32_32x32x16_bf16 v[16:31], v[148:151], v[68:71], v[16:31]
	ds_read_b64_tr_b16 v[140:141], v230 offset:50176
	ds_read_b64_tr_b16 v[144:145], v230 offset:50240
	ds_read_b64_tr_b16 v[148:149], v230 offset:50304
	ds_read_b64_tr_b16 v[172:173], v230 offset:50368
	ds_read_b64_tr_b16 v[142:143], v230 offset:52736
	ds_read_b64_tr_b16 v[146:147], v230 offset:52800
	ds_read_b64_tr_b16 v[150:151], v230 offset:52864
	ds_read_b64_tr_b16 v[174:175], v230 offset:52928
	s_waitcnt lgkmcnt(8)
	v_mfma_f32_32x32x16_bf16 v[0:15], v[168:171], v[68:71], v[0:15]
	s_waitcnt lgkmcnt(3)
	v_mfma_f32_32x32x16_bf16 v[48:63], v[140:143], v[64:67], v[48:63]
	s_waitcnt lgkmcnt(2)
	v_mfma_f32_32x32x16_bf16 v[32:47], v[144:147], v[64:67], v[32:47]
	s_waitcnt lgkmcnt(1)
	v_mfma_f32_32x32x16_bf16 v[16:31], v[148:151], v[64:67], v[16:31]
	s_waitcnt lgkmcnt(0)
	v_mfma_f32_32x32x16_bf16 v[0:15], v[172:175], v[64:67], v[0:15]

.LBB0_582:
	v_cndmask_b32_e64 v80, 0, 1, s[14:15]
	v_cmp_ne_u32_e64 s[6:7], 1, v80
	s_andn2_b64 vcc, exec, s[14:15]
	s_branch .LBB0_584
	s_mulk_i32 s9, 0x5000
	v_add_u32_e32 v184, s9, v230
	ds_read_b64_tr_b16 v[80:81], v184 offset:34816
	ds_read_b64_tr_b16 v[84:85], v184 offset:34880
	ds_read_b64_tr_b16 v[88:89], v184 offset:34944
	ds_read_b64_tr_b16 v[92:93], v184 offset:35008
	ds_read_b64_tr_b16 v[82:83], v184 offset:37376
	ds_read_b64_tr_b16 v[86:87], v184 offset:37440
	ds_read_b64_tr_b16 v[90:91], v184 offset:37504
	ds_read_b64_tr_b16 v[94:95], v184 offset:37568
	s_waitcnt lgkmcnt(3)
	v_mfma_f32_32x32x16_bf16 v[48:63], v[80:83], v[76:79], v[48:63]
	s_waitcnt lgkmcnt(2)
	v_mfma_f32_32x32x16_bf16 v[32:47], v[84:87], v[76:79], v[32:47]
	s_waitcnt lgkmcnt(1)
	v_mfma_f32_32x32x16_bf16 v[16:31], v[88:91], v[76:79], v[16:31]
	ds_read_b64_tr_b16 v[80:81], v184 offset:39936
	ds_read_b64_tr_b16 v[84:85], v184 offset:40000
	ds_read_b64_tr_b16 v[88:89], v184 offset:40064
	ds_read_b64_tr_b16 v[180:181], v184 offset:40128
	ds_read_b64_tr_b16 v[82:83], v184 offset:42496
	ds_read_b64_tr_b16 v[86:87], v184 offset:42560
	ds_read_b64_tr_b16 v[90:91], v184 offset:42624
	ds_read_b64_tr_b16 v[182:183], v184 offset:42688
	s_waitcnt lgkmcnt(8)
	v_mfma_f32_32x32x16_bf16 v[0:15], v[92:95], v[76:79], v[0:15]
	s_waitcnt lgkmcnt(3)
	v_mfma_f32_32x32x16_bf16 v[48:63], v[80:83], v[72:75], v[48:63]
	s_waitcnt lgkmcnt(2)
	v_mfma_f32_32x32x16_bf16 v[32:47], v[84:87], v[72:75], v[32:47]
	s_waitcnt lgkmcnt(1)
	v_mfma_f32_32x32x16_bf16 v[16:31], v[88:91], v[72:75], v[16:31]
	ds_read_b64_tr_b16 v[76:77], v184 offset:45056
	ds_read_b64_tr_b16 v[80:81], v184 offset:45120
	ds_read_b64_tr_b16 v[84:85], v184 offset:45184
	ds_read_b64_tr_b16 v[88:89], v184 offset:45248
	ds_read_b64_tr_b16 v[78:79], v184 offset:47616
	ds_read_b64_tr_b16 v[82:83], v184 offset:47680
	ds_read_b64_tr_b16 v[86:87], v184 offset:47744
	ds_read_b64_tr_b16 v[90:91], v184 offset:47808
	s_waitcnt lgkmcnt(8)
	v_mfma_f32_32x32x16_bf16 v[0:15], v[180:183], v[72:75], v[0:15]
	s_waitcnt lgkmcnt(3)
	v_mfma_f32_32x32x16_bf16 v[48:63], v[76:79], v[68:71], v[48:63]
	s_waitcnt lgkmcnt(2)
	v_mfma_f32_32x32x16_bf16 v[32:47], v[80:83], v[68:71], v[32:47]
	s_waitcnt lgkmcnt(1)
	v_mfma_f32_32x32x16_bf16 v[16:31], v[84:87], v[68:71], v[16:31]
	ds_read_b64_tr_b16 v[72:73], v184 offset:50176
	ds_read_b64_tr_b16 v[76:77], v184 offset:50240
	ds_read_b64_tr_b16 v[80:81], v184 offset:50304
	ds_read_b64_tr_b16 v[84:85], v184 offset:50368
	ds_read_b64_tr_b16 v[74:75], v184 offset:52736
	ds_read_b64_tr_b16 v[78:79], v184 offset:52800
	ds_read_b64_tr_b16 v[82:83], v184 offset:52864
	ds_read_b64_tr_b16 v[86:87], v184 offset:52928
	s_waitcnt lgkmcnt(8)
	v_mfma_f32_32x32x16_bf16 v[0:15], v[88:91], v[68:71], v[0:15]
	s_waitcnt lgkmcnt(3)
	v_mfma_f32_32x32x16_bf16 v[48:63], v[72:75], v[64:67], v[48:63]
	s_waitcnt lgkmcnt(2)
	v_mfma_f32_32x32x16_bf16 v[32:47], v[76:79], v[64:67], v[32:47]
	s_waitcnt lgkmcnt(1)
	v_mfma_f32_32x32x16_bf16 v[16:31], v[80:83], v[64:67], v[16:31]
	s_waitcnt lgkmcnt(0)
	v_mfma_f32_32x32x16_bf16 v[0:15], v[84:87], v[64:67], v[0:15]

.LBB0_586:
	s_andn2_b64 vcc, exec, s[8:9]
	v_mov_b32_e32 v251, 0
	s_cbranch_vccnz .LBB0_588
	v_max3_f32 v188, v64, v65, s77
	v_max3_f32 v188, v66, v67, v188
	v_max3_f32 v188, v68, v69, v188
	v_max3_f32 v188, v70, v71, v188
	v_max3_f32 v188, v72, v73, v188
	v_max3_f32 v188, v74, v75, v188
	v_max3_f32 v188, v76, v77, v188
	v_max3_f32 v188, v78, v79, v188
	v_max3_f32 v188, v80, v81, v188
	v_max3_f32 v188, v82, v83, v188
	v_max3_f32 v188, v84, v85, v188
	v_max3_f32 v188, v86, v87, v188
	v_max3_f32 v188, v88, v89, v188
	v_max3_f32 v188, v90, v91, v188
	v_max3_f32 v188, v92, v93, v188
	v_max3_f32 v188, v94, v95, v188
	v_fmamk_f32 v189, v188, 0x3fb8aa3b, v247
	v_mov_b32_e32 v190, v189
	s_nop 1
	v_permlane32_swap_b32_e32 v190, v189
	s_nop 0
	v_max3_f32 v191, v250, v189, v190
	v_sub_f32_e32 v192, v250, v191
	v_exp_f32_e32 v194, v192
	v_cmp_gt_f32_e32 vcc, v191, v250
	v_sub_f32_e32 v192, v247, v191
	s_mul_i32 s8, s87, 0x5000
	v_add_u32_e32 v210, s8, v230
	ds_read_b64_tr_b16 v[198:199], v210 offset:34816
	ds_read_b64_tr_b16 v[200:201], v210 offset:37376
	ds_read_b64_tr_b16 v[202:203], v210 offset:34880
	ds_read_b64_tr_b16 v[204:205], v210 offset:37440
	ds_read_b64_tr_b16 v[206:207], v210 offset:34944
	ds_read_b64_tr_b16 v[208:209], v210 offset:37504
	ds_read_b64_tr_b16 v[250:251], v210 offset:35008
	ds_read_b64_tr_b16 v[252:253], v210 offset:37568
	s_cbranch_vccz .Lfar1_noresc
	v_pk_mul_f32 v[62:63], v[62:63], v[194:195] op_sel_hi:[1,0]
	v_pk_mul_f32 v[60:61], v[60:61], v[194:195] op_sel_hi:[1,0]
	v_pk_mul_f32 v[58:59], v[58:59], v[194:195] op_sel_hi:[1,0]
	v_pk_mul_f32 v[56:57], v[56:57], v[194:195] op_sel_hi:[1,0]
	v_pk_mul_f32 v[54:55], v[54:55], v[194:195] op_sel_hi:[1,0]
	v_pk_mul_f32 v[52:53], v[52:53], v[194:195] op_sel_hi:[1,0]
	v_pk_mul_f32 v[50:51], v[50:51], v[194:195] op_sel_hi:[1,0]
	v_pk_mul_f32 v[48:49], v[48:49], v[194:195] op_sel_hi:[1,0]
	v_pk_mul_f32 v[46:47], v[46:47], v[194:195] op_sel_hi:[1,0]
	v_pk_mul_f32 v[44:45], v[44:45], v[194:195] op_sel_hi:[1,0]
	v_pk_mul_f32 v[42:43], v[42:43], v[194:195] op_sel_hi:[1,0]
	v_pk_mul_f32 v[40:41], v[40:41], v[194:195] op_sel_hi:[1,0]
	v_pk_mul_f32 v[38:39], v[38:39], v[194:195] op_sel_hi:[1,0]
	v_pk_mul_f32 v[36:37], v[36:37], v[194:195] op_sel_hi:[1,0]
	v_pk_mul_f32 v[34:35], v[34:35], v[194:195] op_sel_hi:[1,0]
	v_pk_mul_f32 v[32:33], v[32:33], v[194:195] op_sel_hi:[1,0]
	v_pk_mul_f32 v[30:31], v[30:31], v[194:195] op_sel_hi:[1,0]
	v_pk_mul_f32 v[28:29], v[28:29], v[194:195] op_sel_hi:[1,0]
	v_pk_mul_f32 v[26:27], v[26:27], v[194:195] op_sel_hi:[1,0]
	v_pk_mul_f32 v[24:25], v[24:25], v[194:195] op_sel_hi:[1,0]
	v_pk_mul_f32 v[22:23], v[22:23], v[194:195] op_sel_hi:[1,0]
	v_pk_mul_f32 v[20:21], v[20:21], v[194:195] op_sel_hi:[1,0]
	v_pk_mul_f32 v[18:19], v[18:19], v[194:195] op_sel_hi:[1,0]
	v_pk_mul_f32 v[16:17], v[16:17], v[194:195] op_sel_hi:[1,0]
	v_pk_mul_f32 v[14:15], v[14:15], v[194:195] op_sel_hi:[1,0]
	v_pk_mul_f32 v[12:13], v[12:13], v[194:195] op_sel_hi:[1,0]
	v_pk_mul_f32 v[10:11], v[10:11], v[194:195] op_sel_hi:[1,0]
	v_pk_mul_f32 v[8:9], v[8:9], v[194:195] op_sel_hi:[1,0]
	v_pk_mul_f32 v[6:7], v[6:7], v[194:195] op_sel_hi:[1,0]
	v_pk_mul_f32 v[4:5], v[4:5], v[194:195] op_sel_hi:[1,0]
	v_pk_mul_f32 v[2:3], v[2:3], v[194:195] op_sel_hi:[1,0]
	v_pk_mul_f32 v[0:1], v[0:1], v[194:195] op_sel_hi:[1,0]
.Lfar1_noresc:
	v_fmamk_f32 v189, v64, 0x3fb8aa3b, v192
	v_exp_f32_e32 v180, v189
	v_fmamk_f32 v189, v65, 0x3fb8aa3b, v192
	v_exp_f32_e32 v181, v189
	v_fmamk_f32 v189, v66, 0x3fb8aa3b, v192
	v_exp_f32_e32 v182, v189
	v_fmamk_f32 v189, v67, 0x3fb8aa3b, v192
	v_exp_f32_e32 v183, v189
	v_fmamk_f32 v189, v68, 0x3fb8aa3b, v192
	v_exp_f32_e32 v184, v189
	v_fmamk_f32 v189, v69, 0x3fb8aa3b, v192
	v_exp_f32_e32 v185, v189
	v_fmamk_f32 v189, v70, 0x3fb8aa3b, v192
	v_exp_f32_e32 v186, v189
	v_fmamk_f32 v189, v71, 0x3fb8aa3b, v192
	v_exp_f32_e32 v187, v189
	v_cvt_pk_bf16_f32 v64, v180, v181
	v_cvt_pk_bf16_f32 v65, v182, v183
	v_cvt_pk_bf16_f32 v66, v184, v185
	v_cvt_pk_bf16_f32 v67, v186, v187
	s_nop 1
	s_waitcnt lgkmcnt(6)
	v_mfma_f32_32x32x16_bf16 v[48:63], v[198:201], v[64:67], v[48:63]
	ds_read_b64_tr_b16 v[198:199], v210 offset:39936
	ds_read_b64_tr_b16 v[200:201], v210 offset:42496
	v_pk_add_f32 v[196:197], v[180:181], v[182:183]
	v_pk_add_f32 v[184:185], v[184:185], v[186:187]
	v_pk_add_f32 v[196:197], v[196:197], v[184:185]
	v_fmamk_f32 v189, v72, 0x3fb8aa3b, v192
	v_exp_f32_e32 v180, v189
	v_fmamk_f32 v189, v73, 0x3fb8aa3b, v192
	v_exp_f32_e32 v181, v189
	s_waitcnt lgkmcnt(6)
	v_mfma_f32_32x32x16_bf16 v[32:47], v[202:205], v[64:67], v[32:47]
	ds_read_b64_tr_b16 v[202:203], v210 offset:40000
	ds_read_b64_tr_b16 v[204:205], v210 offset:42560
	v_fmamk_f32 v189, v74, 0x3fb8aa3b, v192
	v_exp_f32_e32 v182, v189
	v_fmamk_f32 v189, v75, 0x3fb8aa3b, v192
	v_exp_f32_e32 v183, v189
	s_waitcnt lgkmcnt(6)
	v_mfma_f32_32x32x16_bf16 v[16:31], v[206:209], v[64:67], v[16:31]
	ds_read_b64_tr_b16 v[206:207], v210 offset:40064
	ds_read_b64_tr_b16 v[208:209], v210 offset:42624
	v_fmamk_f32 v189, v76, 0x3fb8aa3b, v192
	v_exp_f32_e32 v184, v189
	v_fmamk_f32 v189, v77, 0x3fb8aa3b, v192
	v_exp_f32_e32 v185, v189
	s_waitcnt lgkmcnt(6)
	v_mfma_f32_32x32x16_bf16 v[0:15], v[250:253], v[64:67], v[0:15]
	ds_read_b64_tr_b16 v[250:251], v210 offset:40128
	ds_read_b64_tr_b16 v[252:253], v210 offset:42688
	v_fmamk_f32 v189, v78, 0x3fb8aa3b, v192
	v_exp_f32_e32 v186, v189
	v_fmamk_f32 v189, v79, 0x3fb8aa3b, v192
	v_exp_f32_e32 v187, v189
	v_cvt_pk_bf16_f32 v72, v180, v181
	v_cvt_pk_bf16_f32 v73, v182, v183
	v_cvt_pk_bf16_f32 v74, v184, v185
	v_cvt_pk_bf16_f32 v75, v186, v187
	s_nop 1
	s_waitcnt lgkmcnt(6)
	v_mfma_f32_32x32x16_bf16 v[48:63], v[198:201], v[72:75], v[48:63]
	ds_read_b64_tr_b16 v[198:199], v210 offset:45056
	ds_read_b64_tr_b16 v[200:201], v210 offset:47616
	v_pk_add_f32 v[180:181], v[180:181], v[182:183]
	v_pk_add_f32 v[184:185], v[184:185], v[186:187]
	v_pk_add_f32 v[196:197], v[196:197], v[180:181]
	v_pk_add_f32 v[196:197], v[196:197], v[184:185]
	v_fmamk_f32 v189, v80, 0x3fb8aa3b, v192
	v_exp_f32_e32 v180, v189
	v_fmamk_f32 v189, v81, 0x3fb8aa3b, v192
	v_exp_f32_e32 v181, v189
	s_waitcnt lgkmcnt(6)
	v_mfma_f32_32x32x16_bf16 v[32:47], v[202:205], v[72:75], v[32:47]
	ds_read_b64_tr_b16 v[202:203], v210 offset:45120
	ds_read_b64_tr_b16 v[204:205], v210 offset:47680
	v_fmamk_f32 v189, v82, 0x3fb8aa3b, v192
	v_exp_f32_e32 v182, v189
	v_fmamk_f32 v189, v83, 0x3fb8aa3b, v192
	v_exp_f32_e32 v183, v189
	s_waitcnt lgkmcnt(6)
	v_mfma_f32_32x32x16_bf16 v[16:31], v[206:209], v[72:75], v[16:31]
	ds_read_b64_tr_b16 v[206:207], v210 offset:45184
	ds_read_b64_tr_b16 v[208:209], v210 offset:47744
	v_fmamk_f32 v189, v84, 0x3fb8aa3b, v192
	v_exp_f32_e32 v184, v189
	v_fmamk_f32 v189, v85, 0x3fb8aa3b, v192
	v_exp_f32_e32 v185, v189
	s_waitcnt lgkmcnt(6)
	v_mfma_f32_32x32x16_bf16 v[0:15], v[250:253], v[72:75], v[0:15]
	ds_read_b64_tr_b16 v[250:251], v210 offset:45248
	ds_read_b64_tr_b16 v[252:253], v210 offset:47808
	v_fmamk_f32 v189, v86, 0x3fb8aa3b, v192
	v_exp_f32_e32 v186, v189
	v_fmamk_f32 v189, v87, 0x3fb8aa3b, v192
	v_exp_f32_e32 v187, v189
	v_cvt_pk_bf16_f32 v80, v180, v181
	v_cvt_pk_bf16_f32 v81, v182, v183
	v_cvt_pk_bf16_f32 v82, v184, v185
	v_cvt_pk_bf16_f32 v83, v186, v187
	s_nop 1
	s_waitcnt lgkmcnt(6)
	v_mfma_f32_32x32x16_bf16 v[48:63], v[198:201], v[80:83], v[48:63]
	ds_read_b64_tr_b16 v[198:199], v210 offset:50176
	ds_read_b64_tr_b16 v[200:201], v210 offset:52736
	v_pk_add_f32 v[180:181], v[180:181], v[182:183]
	v_pk_add_f32 v[184:185], v[184:185], v[186:187]
	v_pk_add_f32 v[196:197], v[196:197], v[180:181]
	v_pk_add_f32 v[196:197], v[196:197], v[184:185]
	v_fmamk_f32 v189, v88, 0x3fb8aa3b, v192
	v_exp_f32_e32 v180, v189
	v_fmamk_f32 v189, v89, 0x3fb8aa3b, v192
	v_exp_f32_e32 v181, v189
	s_waitcnt lgkmcnt(6)
	v_mfma_f32_32x32x16_bf16 v[32:47], v[202:205], v[80:83], v[32:47]
	ds_read_b64_tr_b16 v[202:203], v210 offset:50240
	ds_read_b64_tr_b16 v[204:205], v210 offset:52800
	v_fmamk_f32 v189, v90, 0x3fb8aa3b, v192
	v_exp_f32_e32 v182, v189
	v_fmamk_f32 v189, v91, 0x3fb8aa3b, v192
	v_exp_f32_e32 v183, v189
	s_waitcnt lgkmcnt(6)
	v_mfma_f32_32x32x16_bf16 v[16:31], v[206:209], v[80:83], v[16:31]
	ds_read_b64_tr_b16 v[206:207], v210 offset:50304
	ds_read_b64_tr_b16 v[208:209], v210 offset:52864
	v_fmamk_f32 v189, v92, 0x3fb8aa3b, v192
	v_exp_f32_e32 v184, v189
	v_fmamk_f32 v189, v93, 0x3fb8aa3b, v192
	v_exp_f32_e32 v185, v189
	s_waitcnt lgkmcnt(6)
	v_mfma_f32_32x32x16_bf16 v[0:15], v[250:253], v[80:83], v[0:15]
	ds_read_b64_tr_b16 v[250:251], v210 offset:50368
	ds_read_b64_tr_b16 v[252:253], v210 offset:52928
	v_fmamk_f32 v189, v94, 0x3fb8aa3b, v192
	v_exp_f32_e32 v186, v189
	v_fmamk_f32 v189, v95, 0x3fb8aa3b, v192
	v_exp_f32_e32 v187, v189
	v_cvt_pk_bf16_f32 v88, v180, v181
	v_cvt_pk_bf16_f32 v89, v182, v183
	v_cvt_pk_bf16_f32 v90, v184, v185
	v_cvt_pk_bf16_f32 v91, v186, v187
	s_nop 1
	s_waitcnt lgkmcnt(6)
	v_mfma_f32_32x32x16_bf16 v[48:63], v[198:201], v[88:91], v[48:63]
	v_pk_add_f32 v[180:181], v[180:181], v[182:183]
	v_pk_add_f32 v[184:185], v[184:185], v[186:187]
	v_pk_add_f32 v[196:197], v[196:197], v[180:181]
	v_pk_add_f32 v[196:197], v[196:197], v[184:185]
	s_waitcnt lgkmcnt(4)
	v_mfma_f32_32x32x16_bf16 v[32:47], v[202:205], v[88:91], v[32:47]
	s_waitcnt lgkmcnt(2)
	v_mfma_f32_32x32x16_bf16 v[16:31], v[206:209], v[88:91], v[16:31]
	s_waitcnt lgkmcnt(0)
	v_mfma_f32_32x32x16_bf16 v[0:15], v[250:253], v[88:91], v[0:15]
	v_add_f32_e32 v82, v196, v197
	v_mov_b32_e32 v80, v194
	v_mov_b32_e32 v81, v191
	s_branch .Lattn1_tail

.LBB0_590:
	v_sub_f32_e32 v64, v251, v81
	v_fmamk_f32 v65, v180, 0x3fb8aa3b, v64
	v_exp_f32_e32 v82, v65
	v_fmamk_f32 v65, v181, 0x3fb8aa3b, v64
	v_exp_f32_e32 v83, v65
	v_fmamk_f32 v65, v182, 0x3fb8aa3b, v64
	v_exp_f32_e32 v84, v65
	v_fmamk_f32 v65, v183, 0x3fb8aa3b, v64
	v_exp_f32_e32 v85, v65
	v_fmamk_f32 v65, v184, 0x3fb8aa3b, v64
	v_exp_f32_e32 v86, v65
	v_fmamk_f32 v65, v185, 0x3fb8aa3b, v64
	v_exp_f32_e32 v87, v65
	v_fmamk_f32 v65, v186, 0x3fb8aa3b, v64
	v_exp_f32_e32 v88, v65
	v_fmamk_f32 v65, v187, 0x3fb8aa3b, v64
	v_exp_f32_e32 v89, v65
	v_fmamk_f32 v65, v188, 0x3fb8aa3b, v64
	v_exp_f32_e32 v90, v65
	v_fmamk_f32 v65, v189, 0x3fb8aa3b, v64
	v_exp_f32_e32 v91, v65
	v_fmamk_f32 v65, v190, 0x3fb8aa3b, v64
	v_exp_f32_e32 v92, v65
	v_fmamk_f32 v65, v191, 0x3fb8aa3b, v64
	v_exp_f32_e32 v93, v65
	v_fmamk_f32 v65, v192, 0x3fb8aa3b, v64
	v_exp_f32_e32 v94, v65
	v_fmamk_f32 v65, v193, 0x3fb8aa3b, v64
	v_exp_f32_e32 v95, v65
	v_fmamk_f32 v65, v194, 0x3fb8aa3b, v64
	v_exp_f32_e32 v180, v65
	v_fmamk_f32 v65, v195, 0x3fb8aa3b, v64
	v_exp_f32_e32 v181, v65
	v_fmamk_f32 v65, v196, 0x3fb8aa3b, v64
	v_exp_f32_e32 v182, v65
	v_fmamk_f32 v65, v197, 0x3fb8aa3b, v64
	v_exp_f32_e32 v183, v65
	v_fmamk_f32 v65, v198, 0x3fb8aa3b, v64
	v_exp_f32_e32 v184, v65
	v_fmamk_f32 v65, v199, 0x3fb8aa3b, v64
	v_exp_f32_e32 v185, v65
	v_fmamk_f32 v65, v200, 0x3fb8aa3b, v64
	v_exp_f32_e32 v186, v65
	v_fmamk_f32 v65, v201, 0x3fb8aa3b, v64
	v_exp_f32_e32 v187, v65
	v_fmamk_f32 v65, v202, 0x3fb8aa3b, v64
	v_exp_f32_e32 v188, v65
	v_fmamk_f32 v65, v203, 0x3fb8aa3b, v64
	v_exp_f32_e32 v189, v65
	v_fmamk_f32 v65, v204, 0x3fb8aa3b, v64
	v_exp_f32_e32 v190, v65
	v_fmamk_f32 v65, v205, 0x3fb8aa3b, v64
	v_exp_f32_e32 v191, v65
	v_fmamk_f32 v65, v206, 0x3fb8aa3b, v64
	v_exp_f32_e32 v192, v65
	v_fmamk_f32 v65, v207, 0x3fb8aa3b, v64
	v_exp_f32_e32 v193, v65
	v_fmamk_f32 v65, v208, 0x3fb8aa3b, v64
	v_exp_f32_e32 v194, v65
	v_fmamk_f32 v65, v209, 0x3fb8aa3b, v64
	v_exp_f32_e32 v195, v65
	v_fmamk_f32 v65, v210, 0x3fb8aa3b, v64
	v_fmac_f32_e32 v64, 0x3fb8aa3b, v211
	v_exp_f32_e32 v196, v65
	v_exp_f32_e32 v197, v64
	s_mul_i32 s8, s87, 0x5000
	v_cvt_pk_bf16_f32 v76, v82, v83
	v_cvt_pk_bf16_f32 v77, v84, v85
	v_cvt_pk_bf16_f32 v78, v86, v87
	v_cvt_pk_bf16_f32 v79, v88, v89
	v_cvt_pk_bf16_f32 v72, v90, v91
	v_cvt_pk_bf16_f32 v73, v92, v93
	v_cvt_pk_bf16_f32 v74, v94, v95
	v_cvt_pk_bf16_f32 v75, v180, v181
	v_cvt_pk_bf16_f32 v68, v182, v183
	v_cvt_pk_bf16_f32 v69, v184, v185
	v_cvt_pk_bf16_f32 v70, v186, v187
	v_cvt_pk_bf16_f32 v71, v188, v189
	v_cvt_pk_bf16_f32 v64, v190, v191
	v_cvt_pk_bf16_f32 v65, v192, v193
	v_cvt_pk_bf16_f32 v66, v194, v195
	v_cvt_pk_bf16_f32 v67, v196, v197
	s_and_b64 vcc, exec, s[4:5]
	v_add_u32_e32 v210, s8, v230
	ds_read_b64_tr_b16 v[198:199], v210 offset:34816
	ds_read_b64_tr_b16 v[202:203], v210 offset:34880
	ds_read_b64_tr_b16 v[206:207], v210 offset:34944
	ds_read_b64_tr_b16 v[250:251], v210 offset:35008
	ds_read_b64_tr_b16 v[200:201], v210 offset:37376
	ds_read_b64_tr_b16 v[204:205], v210 offset:37440
	ds_read_b64_tr_b16 v[208:209], v210 offset:37504
	ds_read_b64_tr_b16 v[252:253], v210 offset:37568
	s_waitcnt lgkmcnt(3)
	v_mfma_f32_32x32x16_bf16 v[48:63], v[198:201], v[76:79], v[48:63]
	s_waitcnt lgkmcnt(2)
	v_mfma_f32_32x32x16_bf16 v[32:47], v[202:205], v[76:79], v[32:47]
	s_waitcnt lgkmcnt(1)
	v_mfma_f32_32x32x16_bf16 v[16:31], v[206:209], v[76:79], v[16:31]
	s_waitcnt lgkmcnt(0)
	v_mfma_f32_32x32x16_bf16 v[0:15], v[250:253], v[76:79], v[0:15]
	ds_read_b64_tr_b16 v[198:199], v210 offset:39936
	ds_read_b64_tr_b16 v[200:201], v210 offset:42496
	ds_read_b64_tr_b16 v[202:203], v210 offset:40000
	ds_read_b64_tr_b16 v[204:205], v210 offset:42560
	ds_read_b64_tr_b16 v[206:207], v210 offset:40064
	ds_read_b64_tr_b16 v[208:209], v210 offset:42624
	ds_read_b64_tr_b16 v[250:251], v210 offset:40128
	ds_read_b64_tr_b16 v[252:253], v210 offset:42688
	s_waitcnt lgkmcnt(6)
	v_mfma_f32_32x32x16_bf16 v[48:63], v[198:201], v[72:75], v[48:63]
	s_waitcnt lgkmcnt(4)
	v_mfma_f32_32x32x16_bf16 v[32:47], v[202:205], v[72:75], v[32:47]
	s_waitcnt lgkmcnt(2)
	v_mfma_f32_32x32x16_bf16 v[16:31], v[206:209], v[72:75], v[16:31]
	s_waitcnt lgkmcnt(0)
	v_mfma_f32_32x32x16_bf16 v[0:15], v[250:253], v[72:75], v[0:15]
	ds_read_b64_tr_b16 v[198:199], v210 offset:45056
	ds_read_b64_tr_b16 v[200:201], v210 offset:47616
	ds_read_b64_tr_b16 v[202:203], v210 offset:45120
	ds_read_b64_tr_b16 v[204:205], v210 offset:47680
	ds_read_b64_tr_b16 v[206:207], v210 offset:45184
	ds_read_b64_tr_b16 v[208:209], v210 offset:47744
	ds_read_b64_tr_b16 v[250:251], v210 offset:45248
	ds_read_b64_tr_b16 v[252:253], v210 offset:47808
	s_waitcnt lgkmcnt(6)
	v_mfma_f32_32x32x16_bf16 v[48:63], v[198:201], v[68:71], v[48:63]
	s_waitcnt lgkmcnt(4)
	v_mfma_f32_32x32x16_bf16 v[32:47], v[202:205], v[68:71], v[32:47]
	s_waitcnt lgkmcnt(2)
	v_mfma_f32_32x32x16_bf16 v[16:31], v[206:209], v[68:71], v[16:31]
	s_waitcnt lgkmcnt(0)
	v_mfma_f32_32x32x16_bf16 v[0:15], v[250:253], v[68:71], v[0:15]
	ds_read_b64_tr_b16 v[198:199], v210 offset:50176
	ds_read_b64_tr_b16 v[200:201], v210 offset:52736
	ds_read_b64_tr_b16 v[202:203], v210 offset:50240
	ds_read_b64_tr_b16 v[204:205], v210 offset:52800
	ds_read_b64_tr_b16 v[206:207], v210 offset:50304
	ds_read_b64_tr_b16 v[208:209], v210 offset:52864
	ds_read_b64_tr_b16 v[250:251], v210 offset:50368
	ds_read_b64_tr_b16 v[252:253], v210 offset:52928
	s_waitcnt lgkmcnt(6)
	v_mfma_f32_32x32x16_bf16 v[48:63], v[198:201], v[64:67], v[48:63]
	s_waitcnt lgkmcnt(4)
	v_mfma_f32_32x32x16_bf16 v[32:47], v[202:205], v[64:67], v[32:47]
	s_waitcnt lgkmcnt(2)
	v_mfma_f32_32x32x16_bf16 v[16:31], v[206:209], v[64:67], v[16:31]
	s_waitcnt lgkmcnt(0)
	v_mfma_f32_32x32x16_bf16 v[0:15], v[250:253], v[64:67], v[0:15]

.Lattn1_tail:
	s_add_i32 s82, s82, 1
	v_fmac_f32_e32 v82, v248, v80
	v_subrev_u32_e32 v249, 64, v249
	s_cmp_eq_u32 s86, s33
	v_lshl_add_u64 v[178:179], v[178:179], 0, s[50:51]
	s_cbranch_scc1 .LBB0_594
	s_mov_b32 s76, s33
	v_mov_b32_e32 v248, v82
	v_mov_b32_e32 v250, v81
	s_mov_b32 s9, s87
	s_branch .LBB0_579
.LBB0_594:
	s_and_b64 vcc, exec, s[14:15]
	s_branch .LBB0_596
	v_add_u32_e32 v80, s8, v230
	ds_read_b64_tr_b16 v[84:85], v80 offset:34816
	ds_read_b64_tr_b16 v[88:89], v80 offset:34880
	ds_read_b64_tr_b16 v[92:93], v80 offset:34944
	s_waitcnt vmcnt(3)
	ds_read_b64_tr_b16 v[96:97], v80 offset:35008
	ds_read_b64_tr_b16 v[86:87], v80 offset:37376
	ds_read_b64_tr_b16 v[90:91], v80 offset:37440
	ds_read_b64_tr_b16 v[94:95], v80 offset:37504
	ds_read_b64_tr_b16 v[98:99], v80 offset:37568
	s_waitcnt lgkmcnt(3)
	v_mfma_f32_32x32x16_bf16 v[48:63], v[84:87], v[76:79], v[48:63]
	s_waitcnt lgkmcnt(2)
	v_mfma_f32_32x32x16_bf16 v[32:47], v[88:91], v[76:79], v[32:47]
	s_waitcnt lgkmcnt(1)
	v_mfma_f32_32x32x16_bf16 v[16:31], v[92:95], v[76:79], v[16:31]
	ds_read_b64_tr_b16 v[84:85], v80 offset:39936
	ds_read_b64_tr_b16 v[88:89], v80 offset:40000
	ds_read_b64_tr_b16 v[92:93], v80 offset:40064
	s_waitcnt vmcnt(2)
	ds_read_b64_tr_b16 v[100:101], v80 offset:40128
	ds_read_b64_tr_b16 v[86:87], v80 offset:42496
	ds_read_b64_tr_b16 v[90:91], v80 offset:42560
	ds_read_b64_tr_b16 v[94:95], v80 offset:42624
	ds_read_b64_tr_b16 v[102:103], v80 offset:42688
	s_waitcnt lgkmcnt(8)
	v_mfma_f32_32x32x16_bf16 v[0:15], v[96:99], v[76:79], v[0:15]
	s_waitcnt lgkmcnt(3)
	v_mfma_f32_32x32x16_bf16 v[48:63], v[84:87], v[72:75], v[48:63]
	s_waitcnt lgkmcnt(2)
	v_mfma_f32_32x32x16_bf16 v[32:47], v[88:91], v[72:75], v[32:47]
	s_waitcnt lgkmcnt(1)
	v_mfma_f32_32x32x16_bf16 v[16:31], v[92:95], v[72:75], v[16:31]
	ds_read_b64_tr_b16 v[76:77], v80 offset:45056
	ds_read_b64_tr_b16 v[84:85], v80 offset:45120
	ds_read_b64_tr_b16 v[88:89], v80 offset:45184
	ds_read_b64_tr_b16 v[92:93], v80 offset:45248
	ds_read_b64_tr_b16 v[78:79], v80 offset:47616
	ds_read_b64_tr_b16 v[86:87], v80 offset:47680
	ds_read_b64_tr_b16 v[90:91], v80 offset:47744
	ds_read_b64_tr_b16 v[94:95], v80 offset:47808
	s_waitcnt lgkmcnt(8)
	v_mfma_f32_32x32x16_bf16 v[0:15], v[100:103], v[72:75], v[0:15]
	s_waitcnt lgkmcnt(3)
	v_mfma_f32_32x32x16_bf16 v[48:63], v[76:79], v[68:71], v[48:63]
	s_waitcnt lgkmcnt(2)
	v_mfma_f32_32x32x16_bf16 v[32:47], v[84:87], v[68:71], v[32:47]
	s_waitcnt lgkmcnt(1)
	v_mfma_f32_32x32x16_bf16 v[16:31], v[88:91], v[68:71], v[16:31]
	ds_read_b64_tr_b16 v[72:73], v80 offset:50176
	ds_read_b64_tr_b16 v[76:77], v80 offset:50240
	ds_read_b64_tr_b16 v[84:85], v80 offset:50304
	ds_read_b64_tr_b16 v[88:89], v80 offset:50368
	ds_read_b64_tr_b16 v[74:75], v80 offset:52736
	ds_read_b64_tr_b16 v[78:79], v80 offset:52800
	ds_read_b64_tr_b16 v[86:87], v80 offset:52864
	ds_read_b64_tr_b16 v[90:91], v80 offset:52928
	s_waitcnt lgkmcnt(8)
	v_mfma_f32_32x32x16_bf16 v[0:15], v[92:95], v[68:71], v[0:15]
	s_waitcnt lgkmcnt(3)
	v_mfma_f32_32x32x16_bf16 v[48:63], v[72:75], v[64:67], v[48:63]
	s_waitcnt lgkmcnt(2)
	v_mfma_f32_32x32x16_bf16 v[32:47], v[76:79], v[64:67], v[32:47]
	s_waitcnt lgkmcnt(1)
	v_mfma_f32_32x32x16_bf16 v[16:31], v[84:87], v[64:67], v[16:31]
	s_waitcnt lgkmcnt(0)
	v_mfma_f32_32x32x16_bf16 v[0:15], v[88:91], v[64:67], v[0:15]

.LBB0_602:
	s_or_b64 exec, exec, s[56:57]
	s_xor_b32 s56, s81, 63
	s_lshl_b32 s33, s56, 7
	s_or_b32 s52, s52, s33
	v_lshl_add_u64 v[0:1], s[52:53], 0, v[112:113]
	v_mov_b64_e32 v[2:3], s[20:21]
	v_mad_u64_u32 v[2:3], s[82:83], v0, s62, v[2:3]
	v_mad_i32_i24 v3, v1, s62, v3
	s_lshl_b32 s22, s80, 1
	v_lshl_add_u64 v[0:1], v[2:3], 0, s[22:23]
	v_lshl_add_u64 v[12:13], v[0:1], 0, v[116:117]
	global_load_dwordx4 v[0:3], v[12:13], off
	global_load_dwordx4 v[4:7], v[12:13], off offset:16
	global_load_dwordx4 v[8:11], v[12:13], off offset:32
	s_nop 0
	global_load_dwordx4 v[12:15], v[12:13], off offset:48
	s_nop 0
	global_load_dwordx4 v[16:19], v[136:137], off offset:2048
	global_load_dwordx4 v[20:23], v[148:149], off
	global_load_dwordx4 v[24:27], v[150:151], off
	global_load_dwordx4 v[28:31], v[152:153], off
	global_load_dword v48, v117, s[54:55] offset:992
	global_load_dwordx4 v[32:35], v[140:141], off
	global_load_dwordx4 v[36:39], v[142:143], off
	global_load_dwordx4 v[40:43], v[144:145], off
	global_load_dwordx4 v[44:47], v[146:147], off
	v_add_co_u32_e32 v50, vcc, s72, v136
	s_waitcnt vmcnt(12)
	ds_write_b128 v236, v[0:3]
	s_waitcnt vmcnt(11)
	ds_write_b128 v236, v[4:7] offset:16
	s_waitcnt vmcnt(10)
	ds_write_b128 v236, v[8:11] offset:32
	s_waitcnt vmcnt(9)
	ds_write_b128 v236, v[12:15] offset:48
	s_waitcnt vmcnt(8)
	ds_write_b128 v244, v[16:19]
	s_waitcnt vmcnt(7)
	ds_write_b128 v246, v[20:23] offset:34816
	s_waitcnt vmcnt(6)
	ds_write_b128 v244, v[24:27] offset:8704
	s_waitcnt vmcnt(5)
	ds_write_b128 v245, v[28:31] offset:34816
	v_addc_co_u32_e32 v51, vcc, 0, v137, vcc
	v_add_co_u32_e32 v52, vcc, s73, v136
	s_waitcnt lgkmcnt(0)
	s_nop 0
	v_addc_co_u32_e32 v53, vcc, 0, v137, vcc
	v_add_co_u32_e32 v54, vcc, s74, v136
	s_barrier
	s_nop 0
	v_addc_co_u32_e32 v55, vcc, 0, v137, vcc
	v_add_co_u32_e32 v56, vcc, s75, v136
	s_nop 1
	v_addc_co_u32_e32 v57, vcc, 0, v137, vcc
	global_load_dwordx4 v[108:111], v[50:51], off offset:2048
	global_load_dwordx4 v[104:107], v[52:53], off
	global_load_dwordx4 v[100:103], v[54:55], off offset:2048
	global_load_dwordx4 v[96:99], v[56:57], off
	s_waitcnt vmcnt(7)
	ds_write_b128 v177, v[32:35] offset:17408
	s_waitcnt vmcnt(6)
	ds_write_b128 v237, v[36:39] offset:55296
	s_waitcnt vmcnt(5)
	ds_write_b128 v243, v[40:43] offset:17408
	s_waitcnt vmcnt(4)
	ds_write_b128 v238, v[44:47] offset:55296
	ds_read_b128 v[0:3], v229
	ds_read_b128 v[4:7], v239
	ds_read_b128 v[8:11], v229 offset:32
	ds_read_b128 v[32:35], v239 offset:32
	s_waitcnt lgkmcnt(2)
	v_mfma_f32_32x32x16_bf16 v[16:31], v[0:3], v[4:7], 0
	s_waitcnt lgkmcnt(0)
	v_mfma_f32_32x32x16_bf16 v[16:31], v[8:11], v[32:35], v[16:31]
	ds_read_b128 v[0:3], v229 offset:64
	ds_read_b128 v[36:39], v239 offset:64
	ds_read_b128 v[8:11], v229 offset:96
	ds_read_b128 v[40:43], v239 offset:96
	s_waitcnt lgkmcnt(2)
	v_mfma_f32_32x32x16_bf16 v[16:31], v[0:3], v[36:39], v[16:31]
	ds_read_b128 v[0:3], v229 offset:8704
	ds_read_b128 v[44:47], v229 offset:8736
	s_waitcnt lgkmcnt(2)
	v_mfma_f32_32x32x16_bf16 v[16:31], v[8:11], v[40:43], v[16:31]
	s_waitcnt lgkmcnt(1)
	v_mfma_f32_32x32x16_bf16 v[0:15], v[0:3], v[4:7], 0
	s_waitcnt lgkmcnt(0)
	v_mfma_f32_32x32x16_bf16 v[0:15], v[44:47], v[32:35], v[0:15]
	ds_read_b128 v[32:35], v229 offset:8768
	ds_read_b128 v[44:47], v229 offset:8800
	s_waitcnt lgkmcnt(1)
	v_mfma_f32_32x32x16_bf16 v[0:15], v[32:35], v[36:39], v[0:15]
	s_waitcnt lgkmcnt(0)
	v_mfma_f32_32x32x16_bf16 v[0:15], v[44:47], v[40:43], v[0:15]
	s_nop 1
	v_max3_f32 v32, v16, v17, s77
	v_max3_f32 v32, v18, v19, v32
	v_max3_f32 v32, v20, v21, v32
	v_max3_f32 v32, v22, v23, v32
	v_max3_f32 v32, v24, v25, v32
	v_max3_f32 v32, v26, v27, v32
	v_max3_f32 v32, v28, v29, v32
	v_max3_f32 v32, v30, v31, v32
	s_nop 1
	v_max3_f32 v32, v0, v1, v32
	v_max3_f32 v32, v2, v3, v32
	v_max3_f32 v32, v4, v5, v32
	v_max3_f32 v32, v6, v7, v32
	v_max3_f32 v32, v8, v9, v32
	v_max3_f32 v32, v10, v11, v32
	v_max3_f32 v32, v12, v13, v32
	v_max3_f32 v49, v14, v15, v32
	v_pk_mul_f32 v[136:137], v[48:49], s[28:29] op_sel_hi:[1,0]
	s_nop 0
	v_add_f32_e32 v32, v136, v137
	ds_bpermute_b32 v33, v214, v32
	s_waitcnt lgkmcnt(0)
	v_max3_f32 v194, v32, v33, s77
	v_sub_f32_e32 v33, v136, v194
	v_fmamk_f32 v16, v16, 0x3fb8aa3b, v33
	v_fmamk_f32 v0, v0, 0x3fb8aa3b, v33
	v_exp_f32_e32 v80, v16
	v_fmamk_f32 v16, v18, 0x3fb8aa3b, v33
	v_exp_f32_e32 v116, v0
	v_fmamk_f32 v0, v1, 0x3fb8aa3b, v33
	v_exp_f32_e32 v82, v16
	v_fmamk_f32 v16, v19, 0x3fb8aa3b, v33
	v_exp_f32_e32 v125, v0
	v_fmamk_f32 v0, v2, 0x3fb8aa3b, v33
	v_exp_f32_e32 v83, v16
	v_fmamk_f32 v16, v20, 0x3fb8aa3b, v33
	v_exp_f32_e32 v126, v0
	v_fmamk_f32 v0, v3, 0x3fb8aa3b, v33
	v_exp_f32_e32 v84, v16
	v_fmamk_f32 v16, v21, 0x3fb8aa3b, v33
	v_exp_f32_e32 v133, v0
	v_fmamk_f32 v0, v4, 0x3fb8aa3b, v33
	v_exp_f32_e32 v85, v16
	v_fmamk_f32 v16, v22, 0x3fb8aa3b, v33
	v_exp_f32_e32 v137, v0
	v_fmamk_f32 v0, v5, 0x3fb8aa3b, v33
	v_exp_f32_e32 v86, v16
	v_fmamk_f32 v16, v23, 0x3fb8aa3b, v33
	v_exp_f32_e32 v138, v0
	v_fmamk_f32 v0, v6, 0x3fb8aa3b, v33
	v_exp_f32_e32 v87, v16
	v_fmamk_f32 v16, v24, 0x3fb8aa3b, v33
	v_exp_f32_e32 v139, v0
	v_fmamk_f32 v0, v7, 0x3fb8aa3b, v33
	v_exp_f32_e32 v88, v16
	v_fmamk_f32 v16, v25, 0x3fb8aa3b, v33
	v_exp_f32_e32 v140, v0
	v_fmamk_f32 v0, v8, 0x3fb8aa3b, v33
	v_exp_f32_e32 v89, v16
	v_fmamk_f32 v16, v26, 0x3fb8aa3b, v33
	v_exp_f32_e32 v141, v0
	v_fmamk_f32 v0, v9, 0x3fb8aa3b, v33
	v_exp_f32_e32 v90, v16
	v_fmamk_f32 v16, v27, 0x3fb8aa3b, v33
	v_exp_f32_e32 v142, v0
	v_fmamk_f32 v0, v10, 0x3fb8aa3b, v33
	v_sub_f32_e32 v32, 0xf149f2ca, v194
	v_exp_f32_e32 v91, v16
	v_fmamk_f32 v16, v28, 0x3fb8aa3b, v33
	v_exp_f32_e32 v143, v0
	v_fmamk_f32 v0, v11, 0x3fb8aa3b, v33
	v_exp_f32_e32 v32, v32
	v_exp_f32_e32 v92, v16
	v_fmamk_f32 v16, v29, 0x3fb8aa3b, v33
	v_exp_f32_e32 v144, v0
	v_fmamk_f32 v0, v12, 0x3fb8aa3b, v33
	v_exp_f32_e32 v93, v16
	v_fmamk_f32 v16, v30, 0x3fb8aa3b, v33
	v_exp_f32_e32 v145, v0
	v_fmamk_f32 v0, v13, 0x3fb8aa3b, v33
	v_fmamk_f32 v17, v17, 0x3fb8aa3b, v33
	v_exp_f32_e32 v94, v16
	v_fmamk_f32 v16, v31, 0x3fb8aa3b, v33
	v_exp_f32_e32 v146, v0
	v_fmamk_f32 v0, v14, 0x3fb8aa3b, v33
	v_fmac_f32_e32 v33, 0x3fb8aa3b, v15
	v_cmp_lt_f32_e32 vcc, s77, v194
	v_exp_f32_e32 v81, v17
	v_exp_f32_e32 v95, v16
	v_exp_f32_e32 v147, v0
	v_exp_f32_e32 v149, v33
	s_cmp_lg_u64 vcc, 0
	v_mul_f32_e32 v148, 0, v32
	s_cselect_b64 vcc, -1, 0
	v_cndmask_b32_e32 v0, 0, v148, vcc
	v_mov_b32_e32 v1, v0
	v_mov_b32_e32 v2, v0
	v_mov_b32_e32 v3, v0
	v_mov_b32_e32 v4, v0
	v_mov_b32_e32 v5, v0
	v_mov_b32_e32 v6, v0
	v_mov_b32_e32 v7, v0
	v_mov_b32_e32 v8, v0
	v_mov_b32_e32 v9, v0
	v_mov_b32_e32 v10, v0
	v_mov_b32_e32 v11, v0
	v_mov_b32_e32 v12, v0
	v_mov_b32_e32 v13, v0
	v_mov_b32_e32 v14, v0
	v_mov_b32_e32 v15, v0
	v_cvt_pk_bf16_f32 v76, v80, v81
	v_cvt_pk_bf16_f32 v77, v82, v83
	v_cvt_pk_bf16_f32 v78, v84, v85
	v_cvt_pk_bf16_f32 v79, v86, v87
	v_cvt_pk_bf16_f32 v72, v88, v89
	v_cvt_pk_bf16_f32 v73, v90, v91
	v_cvt_pk_bf16_f32 v74, v92, v93
	v_cvt_pk_bf16_f32 v75, v94, v95
	v_cvt_pk_bf16_f32 v68, v116, v125
	v_cvt_pk_bf16_f32 v69, v126, v133
	v_cvt_pk_bf16_f32 v70, v137, v138
	v_cvt_pk_bf16_f32 v71, v139, v140
	v_cvt_pk_bf16_f32 v64, v141, v142
	v_cvt_pk_bf16_f32 v65, v143, v144
	v_cvt_pk_bf16_f32 v66, v145, v146
	v_cvt_pk_bf16_f32 v67, v147, v149
	v_mov_b64_e32 v[30:31], v[14:15]
	v_mov_b64_e32 v[46:47], v[14:15]
	v_mov_b64_e32 v[62:63], v[14:15]
	s_and_b64 vcc, exec, s[4:5]
	v_mov_b64_e32 v[28:29], v[12:13]
	v_mov_b64_e32 v[26:27], v[10:11]
	v_mov_b64_e32 v[24:25], v[8:9]
	v_mov_b64_e32 v[22:23], v[6:7]
	v_mov_b64_e32 v[20:21], v[4:5]
	v_mov_b64_e32 v[18:19], v[2:3]
	v_mov_b64_e32 v[16:17], v[0:1]
	v_mov_b64_e32 v[44:45], v[12:13]
	v_mov_b64_e32 v[42:43], v[10:11]
	v_mov_b64_e32 v[40:41], v[8:9]
	v_mov_b64_e32 v[38:39], v[6:7]
	v_mov_b64_e32 v[36:37], v[4:5]
	v_mov_b64_e32 v[34:35], v[2:3]
	v_mov_b64_e32 v[32:33], v[0:1]
	v_mov_b64_e32 v[60:61], v[12:13]
	v_mov_b64_e32 v[58:59], v[10:11]
	v_mov_b64_e32 v[56:57], v[8:9]
	v_mov_b64_e32 v[54:55], v[6:7]
	v_mov_b64_e32 v[52:53], v[4:5]
	v_mov_b64_e32 v[50:51], v[2:3]
	v_mov_b64_e32 v[48:49], v[0:1]
	ds_read_b64_tr_b16 v[16:17], v230 offset:34816
	ds_read_b64_tr_b16 v[20:21], v230 offset:34880
	ds_read_b64_tr_b16 v[150:151], v230 offset:34944
	ds_read_b64_tr_b16 v[154:155], v230 offset:35008
	ds_read_b64_tr_b16 v[18:19], v230 offset:37376
	ds_read_b64_tr_b16 v[22:23], v230 offset:37440
	ds_read_b64_tr_b16 v[152:153], v230 offset:37504
	ds_read_b64_tr_b16 v[156:157], v230 offset:37568
	s_waitcnt lgkmcnt(3)
	v_mfma_f32_32x32x16_bf16 v[48:63], v[16:19], v[76:79], v[0:15]
	s_waitcnt lgkmcnt(2)
	v_mfma_f32_32x32x16_bf16 v[32:47], v[20:23], v[76:79], v[0:15]
	s_waitcnt lgkmcnt(1)
	v_mfma_f32_32x32x16_bf16 v[16:31], v[150:153], v[76:79], v[0:15]
	ds_read_b64_tr_b16 v[150:151], v230 offset:39936
	ds_read_b64_tr_b16 v[158:159], v230 offset:40000
	ds_read_b64_tr_b16 v[162:163], v230 offset:40064
	ds_read_b64_tr_b16 v[166:167], v230 offset:40128
	ds_read_b64_tr_b16 v[152:153], v230 offset:42496
	ds_read_b64_tr_b16 v[160:161], v230 offset:42560
	ds_read_b64_tr_b16 v[164:165], v230 offset:42624
	ds_read_b64_tr_b16 v[168:169], v230 offset:42688
	s_waitcnt lgkmcnt(8)
	v_mfma_f32_32x32x16_bf16 v[0:15], v[154:157], v[76:79], v[0:15]
	s_waitcnt lgkmcnt(3)
	v_mfma_f32_32x32x16_bf16 v[48:63], v[150:153], v[72:75], v[48:63]
	s_waitcnt lgkmcnt(2)
	v_mfma_f32_32x32x16_bf16 v[32:47], v[158:161], v[72:75], v[32:47]
	s_waitcnt lgkmcnt(1)
	v_mfma_f32_32x32x16_bf16 v[16:31], v[162:165], v[72:75], v[16:31]
	ds_read_b64_tr_b16 v[150:151], v230 offset:45056
	ds_read_b64_tr_b16 v[154:155], v230 offset:45120
	ds_read_b64_tr_b16 v[158:159], v230 offset:45184
	ds_read_b64_tr_b16 v[162:163], v230 offset:45248
	ds_read_b64_tr_b16 v[152:153], v230 offset:47616
	ds_read_b64_tr_b16 v[156:157], v230 offset:47680
	ds_read_b64_tr_b16 v[160:161], v230 offset:47744
	ds_read_b64_tr_b16 v[164:165], v230 offset:47808
	s_waitcnt lgkmcnt(8)
	v_mfma_f32_32x32x16_bf16 v[0:15], v[166:169], v[72:75], v[0:15]
	s_waitcnt lgkmcnt(3)
	v_mfma_f32_32x32x16_bf16 v[48:63], v[150:153], v[68:71], v[48:63]
	s_waitcnt lgkmcnt(2)
	v_mfma_f32_32x32x16_bf16 v[32:47], v[154:157], v[68:71], v[32:47]
	s_waitcnt lgkmcnt(1)
	v_mfma_f32_32x32x16_bf16 v[16:31], v[158:161], v[68:71], v[16:31]
	ds_read_b64_tr_b16 v[150:151], v230 offset:50176
	ds_read_b64_tr_b16 v[154:155], v230 offset:50240
	ds_read_b64_tr_b16 v[158:159], v230 offset:50304
	ds_read_b64_tr_b16 v[166:167], v230 offset:50368
	ds_read_b64_tr_b16 v[152:153], v230 offset:52736
	ds_read_b64_tr_b16 v[156:157], v230 offset:52800
	ds_read_b64_tr_b16 v[160:161], v230 offset:52864
	ds_read_b64_tr_b16 v[168:169], v230 offset:52928
	s_waitcnt lgkmcnt(8)
	v_mfma_f32_32x32x16_bf16 v[0:15], v[162:165], v[68:71], v[0:15]
	s_waitcnt lgkmcnt(3)
	v_mfma_f32_32x32x16_bf16 v[48:63], v[150:153], v[64:67], v[48:63]
	s_waitcnt lgkmcnt(2)
	v_mfma_f32_32x32x16_bf16 v[32:47], v[154:157], v[64:67], v[32:47]
	s_waitcnt lgkmcnt(1)
	v_mfma_f32_32x32x16_bf16 v[16:31], v[158:161], v[64:67], v[16:31]
	s_waitcnt lgkmcnt(0)
	v_mfma_f32_32x32x16_bf16 v[0:15], v[166:169], v[64:67], v[0:15]

.LBB0_605:
	s_add_i32 s33, s84, 1
	s_cmp_lg_u32 s84, 2
	s_mov_b32 s85, s84
	s_cselect_b32 s84, s33, 0
	s_add_i32 s33, s54, 1
	s_bitcmp1_b32 s33, 0
	s_cselect_b32 s76, 0x4400, 0
	s_add_i32 s83, s76, 0
	s_mul_i32 s81, s84, 0x5000
	s_add_i32 s76, s81, 0
	v_add3_u32 v80, s83, v218, v220
	s_barrier
	s_waitcnt vmcnt(3)
	ds_write_b128 v80, v[108:111]
	v_add3_u32 v80, s76, v221, v220
	s_waitcnt vmcnt(2)
	ds_write_b128 v80, v[104:107] offset:34816
	v_add3_u32 v80, s83, v223, v220
	s_waitcnt vmcnt(1)
	ds_write_b128 v80, v[100:103]
	v_add3_u32 v80, s76, v224, v220
	s_waitcnt vmcnt(0)
	ds_write_b128 v80, v[96:99] offset:34816
	v_add_co_u32_e32 v80, vcc, 0xfffa0000, v134
	s_nop 1
	v_addc_co_u32_e32 v81, vcc, -1, v135, vcc
	global_load_dwordx4 v[108:111], v[80:81], off offset:-2048
	global_load_dwordx4 v[104:107], v[80:81], off
	global_load_dwordx4 v[100:103], v[134:135], off offset:-2048
	global_load_dwordx4 v[96:99], v[134:135], off
	s_and_b64 vcc, exec, s[6:7]
	s_branch .LBB0_607
	s_mulk_i32 s55, 0x5000
	v_add_u32_e32 v164, s55, v230
	ds_read_b64_tr_b16 v[80:81], v164 offset:34816
	ds_read_b64_tr_b16 v[84:85], v164 offset:34880
	ds_read_b64_tr_b16 v[88:89], v164 offset:34944
	ds_read_b64_tr_b16 v[92:93], v164 offset:35008
	ds_read_b64_tr_b16 v[82:83], v164 offset:37376
	ds_read_b64_tr_b16 v[86:87], v164 offset:37440
	ds_read_b64_tr_b16 v[90:91], v164 offset:37504
	ds_read_b64_tr_b16 v[94:95], v164 offset:37568
	s_waitcnt lgkmcnt(3)
	v_mfma_f32_32x32x16_bf16 v[48:63], v[80:83], v[76:79], v[48:63]
	s_waitcnt lgkmcnt(2)
	v_mfma_f32_32x32x16_bf16 v[32:47], v[84:87], v[76:79], v[32:47]
	s_waitcnt lgkmcnt(1)
	v_mfma_f32_32x32x16_bf16 v[16:31], v[88:91], v[76:79], v[16:31]
	ds_read_b64_tr_b16 v[80:81], v164 offset:39936
	ds_read_b64_tr_b16 v[84:85], v164 offset:40000
	ds_read_b64_tr_b16 v[88:89], v164 offset:40064
	ds_read_b64_tr_b16 v[160:161], v164 offset:40128
	ds_read_b64_tr_b16 v[82:83], v164 offset:42496
	ds_read_b64_tr_b16 v[86:87], v164 offset:42560
	ds_read_b64_tr_b16 v[90:91], v164 offset:42624
	ds_read_b64_tr_b16 v[162:163], v164 offset:42688
	s_waitcnt lgkmcnt(8)
	v_mfma_f32_32x32x16_bf16 v[0:15], v[92:95], v[76:79], v[0:15]
	s_waitcnt lgkmcnt(3)
	v_mfma_f32_32x32x16_bf16 v[48:63], v[80:83], v[72:75], v[48:63]
	s_waitcnt lgkmcnt(2)
	v_mfma_f32_32x32x16_bf16 v[32:47], v[84:87], v[72:75], v[32:47]
	s_waitcnt lgkmcnt(1)
	v_mfma_f32_32x32x16_bf16 v[16:31], v[88:91], v[72:75], v[16:31]
	ds_read_b64_tr_b16 v[76:77], v164 offset:45056
	ds_read_b64_tr_b16 v[80:81], v164 offset:45120
	ds_read_b64_tr_b16 v[84:85], v164 offset:45184
	ds_read_b64_tr_b16 v[88:89], v164 offset:45248
	ds_read_b64_tr_b16 v[78:79], v164 offset:47616
	ds_read_b64_tr_b16 v[82:83], v164 offset:47680
	ds_read_b64_tr_b16 v[86:87], v164 offset:47744
	ds_read_b64_tr_b16 v[90:91], v164 offset:47808
	s_waitcnt lgkmcnt(8)
	v_mfma_f32_32x32x16_bf16 v[0:15], v[160:163], v[72:75], v[0:15]
	s_waitcnt lgkmcnt(3)
	v_mfma_f32_32x32x16_bf16 v[48:63], v[76:79], v[68:71], v[48:63]
	s_waitcnt lgkmcnt(2)
	v_mfma_f32_32x32x16_bf16 v[32:47], v[80:83], v[68:71], v[32:47]
	s_waitcnt lgkmcnt(1)
	v_mfma_f32_32x32x16_bf16 v[16:31], v[84:87], v[68:71], v[16:31]
	ds_read_b64_tr_b16 v[72:73], v164 offset:50176
	ds_read_b64_tr_b16 v[76:77], v164 offset:50240
	ds_read_b64_tr_b16 v[80:81], v164 offset:50304
	ds_read_b64_tr_b16 v[84:85], v164 offset:50368
	ds_read_b64_tr_b16 v[74:75], v164 offset:52736
	ds_read_b64_tr_b16 v[78:79], v164 offset:52800
	ds_read_b64_tr_b16 v[82:83], v164 offset:52864
	ds_read_b64_tr_b16 v[86:87], v164 offset:52928
	s_waitcnt lgkmcnt(8)
	v_mfma_f32_32x32x16_bf16 v[0:15], v[88:91], v[68:71], v[0:15]
	s_waitcnt lgkmcnt(3)
	v_mfma_f32_32x32x16_bf16 v[48:63], v[72:75], v[64:67], v[48:63]
	s_waitcnt lgkmcnt(2)
	v_mfma_f32_32x32x16_bf16 v[32:47], v[76:79], v[64:67], v[32:47]
	s_waitcnt lgkmcnt(1)
	v_mfma_f32_32x32x16_bf16 v[16:31], v[80:83], v[64:67], v[16:31]
	s_waitcnt lgkmcnt(0)
	v_mfma_f32_32x32x16_bf16 v[0:15], v[84:87], v[64:67], v[0:15]

.LBB0_609:
	s_andn2_b64 vcc, exec, s[54:55]
	v_mov_b32_e32 v195, 0
	s_cbranch_vccnz .LBB0_611
	v_max3_f32 v168, v64, v65, s77
	v_max3_f32 v168, v66, v67, v168
	v_max3_f32 v168, v68, v69, v168
	v_max3_f32 v168, v70, v71, v168
	v_max3_f32 v168, v72, v73, v168
	v_max3_f32 v168, v74, v75, v168
	v_max3_f32 v168, v76, v77, v168
	v_max3_f32 v168, v78, v79, v168
	v_max3_f32 v168, v80, v81, v168
	v_max3_f32 v168, v82, v83, v168
	v_max3_f32 v168, v84, v85, v168
	v_max3_f32 v168, v86, v87, v168
	v_max3_f32 v168, v88, v89, v168
	v_max3_f32 v168, v90, v91, v168
	v_max3_f32 v168, v92, v93, v168
	v_max3_f32 v168, v94, v95, v168
	v_fmamk_f32 v169, v168, 0x3fb8aa3b, v136
	v_mov_b32_e32 v170, v169
	s_nop 1
	v_permlane32_swap_b32_e32 v170, v169
	s_nop 0
	v_max3_f32 v193, v194, v169, v170
	v_sub_f32_e32 v172, v194, v193
	v_exp_f32_e32 v174, v172
	v_cmp_gt_f32_e32 vcc, v193, v194
	v_sub_f32_e32 v172, v136, v193
	s_mul_i32 s54, s85, 0x5000
	v_add_u32_e32 v177, s54, v230
	ds_read_b64_tr_b16 v[178:179], v177 offset:34816
	ds_read_b64_tr_b16 v[180:181], v177 offset:37376
	ds_read_b64_tr_b16 v[182:183], v177 offset:34880
	ds_read_b64_tr_b16 v[184:185], v177 offset:37440
	ds_read_b64_tr_b16 v[186:187], v177 offset:34944
	ds_read_b64_tr_b16 v[188:189], v177 offset:37504
	ds_read_b64_tr_b16 v[198:199], v177 offset:35008
	ds_read_b64_tr_b16 v[200:201], v177 offset:37568
	s_cbranch_vccz .Lfar2_noresc
	v_pk_mul_f32 v[62:63], v[62:63], v[174:175] op_sel_hi:[1,0]
	v_pk_mul_f32 v[60:61], v[60:61], v[174:175] op_sel_hi:[1,0]
	v_pk_mul_f32 v[58:59], v[58:59], v[174:175] op_sel_hi:[1,0]
	v_pk_mul_f32 v[56:57], v[56:57], v[174:175] op_sel_hi:[1,0]
	v_pk_mul_f32 v[54:55], v[54:55], v[174:175] op_sel_hi:[1,0]
	v_pk_mul_f32 v[52:53], v[52:53], v[174:175] op_sel_hi:[1,0]
	v_pk_mul_f32 v[50:51], v[50:51], v[174:175] op_sel_hi:[1,0]
	v_pk_mul_f32 v[48:49], v[48:49], v[174:175] op_sel_hi:[1,0]
	v_pk_mul_f32 v[46:47], v[46:47], v[174:175] op_sel_hi:[1,0]
	v_pk_mul_f32 v[44:45], v[44:45], v[174:175] op_sel_hi:[1,0]
	v_pk_mul_f32 v[42:43], v[42:43], v[174:175] op_sel_hi:[1,0]
	v_pk_mul_f32 v[40:41], v[40:41], v[174:175] op_sel_hi:[1,0]
	v_pk_mul_f32 v[38:39], v[38:39], v[174:175] op_sel_hi:[1,0]
	v_pk_mul_f32 v[36:37], v[36:37], v[174:175] op_sel_hi:[1,0]
	v_pk_mul_f32 v[34:35], v[34:35], v[174:175] op_sel_hi:[1,0]
	v_pk_mul_f32 v[32:33], v[32:33], v[174:175] op_sel_hi:[1,0]
	v_pk_mul_f32 v[30:31], v[30:31], v[174:175] op_sel_hi:[1,0]
	v_pk_mul_f32 v[28:29], v[28:29], v[174:175] op_sel_hi:[1,0]
	v_pk_mul_f32 v[26:27], v[26:27], v[174:175] op_sel_hi:[1,0]
	v_pk_mul_f32 v[24:25], v[24:25], v[174:175] op_sel_hi:[1,0]
	v_pk_mul_f32 v[22:23], v[22:23], v[174:175] op_sel_hi:[1,0]
	v_pk_mul_f32 v[20:21], v[20:21], v[174:175] op_sel_hi:[1,0]
	v_pk_mul_f32 v[18:19], v[18:19], v[174:175] op_sel_hi:[1,0]
	v_pk_mul_f32 v[16:17], v[16:17], v[174:175] op_sel_hi:[1,0]
	v_pk_mul_f32 v[14:15], v[14:15], v[174:175] op_sel_hi:[1,0]
	v_pk_mul_f32 v[12:13], v[12:13], v[174:175] op_sel_hi:[1,0]
	v_pk_mul_f32 v[10:11], v[10:11], v[174:175] op_sel_hi:[1,0]
	v_pk_mul_f32 v[8:9], v[8:9], v[174:175] op_sel_hi:[1,0]
	v_pk_mul_f32 v[6:7], v[6:7], v[174:175] op_sel_hi:[1,0]
	v_pk_mul_f32 v[4:5], v[4:5], v[174:175] op_sel_hi:[1,0]
	v_pk_mul_f32 v[2:3], v[2:3], v[174:175] op_sel_hi:[1,0]
	v_pk_mul_f32 v[0:1], v[0:1], v[174:175] op_sel_hi:[1,0]
.Lfar2_noresc:
	v_fmamk_f32 v169, v64, 0x3fb8aa3b, v172
	v_exp_f32_e32 v160, v169
	v_fmamk_f32 v169, v65, 0x3fb8aa3b, v172
	v_exp_f32_e32 v161, v169
	v_fmamk_f32 v169, v66, 0x3fb8aa3b, v172
	v_exp_f32_e32 v162, v169
	v_fmamk_f32 v169, v67, 0x3fb8aa3b, v172
	v_exp_f32_e32 v163, v169
	v_fmamk_f32 v169, v68, 0x3fb8aa3b, v172
	v_exp_f32_e32 v164, v169
	v_fmamk_f32 v169, v69, 0x3fb8aa3b, v172
	v_exp_f32_e32 v165, v169
	v_fmamk_f32 v169, v70, 0x3fb8aa3b, v172
	v_exp_f32_e32 v166, v169
	v_fmamk_f32 v169, v71, 0x3fb8aa3b, v172
	v_exp_f32_e32 v167, v169
	v_cvt_pk_bf16_f32 v64, v160, v161
	v_cvt_pk_bf16_f32 v65, v162, v163
	v_cvt_pk_bf16_f32 v66, v164, v165
	v_cvt_pk_bf16_f32 v67, v166, v167
	s_nop 1
	s_waitcnt lgkmcnt(6)
	v_mfma_f32_32x32x16_bf16 v[48:63], v[178:181], v[64:67], v[48:63]
	ds_read_b64_tr_b16 v[178:179], v177 offset:39936
	ds_read_b64_tr_b16 v[180:181], v177 offset:42496
	v_pk_add_f32 v[190:191], v[160:161], v[162:163]
	v_pk_add_f32 v[164:165], v[164:165], v[166:167]
	v_pk_add_f32 v[190:191], v[190:191], v[164:165]
	v_fmamk_f32 v169, v72, 0x3fb8aa3b, v172
	v_exp_f32_e32 v160, v169
	v_fmamk_f32 v169, v73, 0x3fb8aa3b, v172
	v_exp_f32_e32 v161, v169
	s_waitcnt lgkmcnt(6)
	v_mfma_f32_32x32x16_bf16 v[32:47], v[182:185], v[64:67], v[32:47]
	ds_read_b64_tr_b16 v[182:183], v177 offset:40000
	ds_read_b64_tr_b16 v[184:185], v177 offset:42560
	v_fmamk_f32 v169, v74, 0x3fb8aa3b, v172
	v_exp_f32_e32 v162, v169
	v_fmamk_f32 v169, v75, 0x3fb8aa3b, v172
	v_exp_f32_e32 v163, v169
	s_waitcnt lgkmcnt(6)
	v_mfma_f32_32x32x16_bf16 v[16:31], v[186:189], v[64:67], v[16:31]
	ds_read_b64_tr_b16 v[186:187], v177 offset:40064
	ds_read_b64_tr_b16 v[188:189], v177 offset:42624
	v_fmamk_f32 v169, v76, 0x3fb8aa3b, v172
	v_exp_f32_e32 v164, v169
	v_fmamk_f32 v169, v77, 0x3fb8aa3b, v172
	v_exp_f32_e32 v165, v169
	s_waitcnt lgkmcnt(6)
	v_mfma_f32_32x32x16_bf16 v[0:15], v[198:201], v[64:67], v[0:15]
	ds_read_b64_tr_b16 v[198:199], v177 offset:40128
	ds_read_b64_tr_b16 v[200:201], v177 offset:42688
	v_fmamk_f32 v169, v78, 0x3fb8aa3b, v172
	v_exp_f32_e32 v166, v169
	v_fmamk_f32 v169, v79, 0x3fb8aa3b, v172
	v_exp_f32_e32 v167, v169
	v_cvt_pk_bf16_f32 v72, v160, v161
	v_cvt_pk_bf16_f32 v73, v162, v163
	v_cvt_pk_bf16_f32 v74, v164, v165
	v_cvt_pk_bf16_f32 v75, v166, v167
	s_nop 1
	s_waitcnt lgkmcnt(6)
	v_mfma_f32_32x32x16_bf16 v[48:63], v[178:181], v[72:75], v[48:63]
	ds_read_b64_tr_b16 v[178:179], v177 offset:45056
	ds_read_b64_tr_b16 v[180:181], v177 offset:47616
	v_pk_add_f32 v[160:161], v[160:161], v[162:163]
	v_pk_add_f32 v[164:165], v[164:165], v[166:167]
	v_pk_add_f32 v[190:191], v[190:191], v[160:161]
	v_pk_add_f32 v[190:191], v[190:191], v[164:165]
	v_fmamk_f32 v169, v80, 0x3fb8aa3b, v172
	v_exp_f32_e32 v160, v169
	v_fmamk_f32 v169, v81, 0x3fb8aa3b, v172
	v_exp_f32_e32 v161, v169
	s_waitcnt lgkmcnt(6)
	v_mfma_f32_32x32x16_bf16 v[32:47], v[182:185], v[72:75], v[32:47]
	ds_read_b64_tr_b16 v[182:183], v177 offset:45120
	ds_read_b64_tr_b16 v[184:185], v177 offset:47680
	v_fmamk_f32 v169, v82, 0x3fb8aa3b, v172
	v_exp_f32_e32 v162, v169
	v_fmamk_f32 v169, v83, 0x3fb8aa3b, v172
	v_exp_f32_e32 v163, v169
	s_waitcnt lgkmcnt(6)
	v_mfma_f32_32x32x16_bf16 v[16:31], v[186:189], v[72:75], v[16:31]
	ds_read_b64_tr_b16 v[186:187], v177 offset:45184
	ds_read_b64_tr_b16 v[188:189], v177 offset:47744
	v_fmamk_f32 v169, v84, 0x3fb8aa3b, v172
	v_exp_f32_e32 v164, v169
	v_fmamk_f32 v169, v85, 0x3fb8aa3b, v172
	v_exp_f32_e32 v165, v169
	s_waitcnt lgkmcnt(6)
	v_mfma_f32_32x32x16_bf16 v[0:15], v[198:201], v[72:75], v[0:15]
	ds_read_b64_tr_b16 v[198:199], v177 offset:45248
	ds_read_b64_tr_b16 v[200:201], v177 offset:47808
	v_fmamk_f32 v169, v86, 0x3fb8aa3b, v172
	v_exp_f32_e32 v166, v169
	v_fmamk_f32 v169, v87, 0x3fb8aa3b, v172
	v_exp_f32_e32 v167, v169
	v_cvt_pk_bf16_f32 v80, v160, v161
	v_cvt_pk_bf16_f32 v81, v162, v163
	v_cvt_pk_bf16_f32 v82, v164, v165
	v_cvt_pk_bf16_f32 v83, v166, v167
	s_nop 1
	s_waitcnt lgkmcnt(6)
	v_mfma_f32_32x32x16_bf16 v[48:63], v[178:181], v[80:83], v[48:63]
	ds_read_b64_tr_b16 v[178:179], v177 offset:50176
	ds_read_b64_tr_b16 v[180:181], v177 offset:52736
	v_pk_add_f32 v[160:161], v[160:161], v[162:163]
	v_pk_add_f32 v[164:165], v[164:165], v[166:167]
	v_pk_add_f32 v[190:191], v[190:191], v[160:161]
	v_pk_add_f32 v[190:191], v[190:191], v[164:165]
	v_fmamk_f32 v169, v88, 0x3fb8aa3b, v172
	v_exp_f32_e32 v160, v169
	v_fmamk_f32 v169, v89, 0x3fb8aa3b, v172
	v_exp_f32_e32 v161, v169
	s_waitcnt lgkmcnt(6)
	v_mfma_f32_32x32x16_bf16 v[32:47], v[182:185], v[80:83], v[32:47]
	ds_read_b64_tr_b16 v[182:183], v177 offset:50240
	ds_read_b64_tr_b16 v[184:185], v177 offset:52800
	v_fmamk_f32 v169, v90, 0x3fb8aa3b, v172
	v_exp_f32_e32 v162, v169
	v_fmamk_f32 v169, v91, 0x3fb8aa3b, v172
	v_exp_f32_e32 v163, v169
	s_waitcnt lgkmcnt(6)
	v_mfma_f32_32x32x16_bf16 v[16:31], v[186:189], v[80:83], v[16:31]
	ds_read_b64_tr_b16 v[186:187], v177 offset:50304
	ds_read_b64_tr_b16 v[188:189], v177 offset:52864
	v_fmamk_f32 v169, v92, 0x3fb8aa3b, v172
	v_exp_f32_e32 v164, v169
	v_fmamk_f32 v169, v93, 0x3fb8aa3b, v172
	v_exp_f32_e32 v165, v169
	s_waitcnt lgkmcnt(6)
	v_mfma_f32_32x32x16_bf16 v[0:15], v[198:201], v[80:83], v[0:15]
	ds_read_b64_tr_b16 v[198:199], v177 offset:50368
	ds_read_b64_tr_b16 v[200:201], v177 offset:52928
	v_fmamk_f32 v169, v94, 0x3fb8aa3b, v172
	v_exp_f32_e32 v166, v169
	v_fmamk_f32 v169, v95, 0x3fb8aa3b, v172
	v_exp_f32_e32 v167, v169
	v_cvt_pk_bf16_f32 v88, v160, v161
	v_cvt_pk_bf16_f32 v89, v162, v163
	v_cvt_pk_bf16_f32 v90, v164, v165
	v_cvt_pk_bf16_f32 v91, v166, v167
	s_nop 1
	s_waitcnt lgkmcnt(6)
	v_mfma_f32_32x32x16_bf16 v[48:63], v[178:181], v[88:91], v[48:63]
	v_pk_add_f32 v[160:161], v[160:161], v[162:163]
	v_pk_add_f32 v[164:165], v[164:165], v[166:167]
	v_pk_add_f32 v[190:191], v[190:191], v[160:161]
	v_pk_add_f32 v[190:191], v[190:191], v[164:165]
	s_waitcnt lgkmcnt(4)
	v_mfma_f32_32x32x16_bf16 v[32:47], v[182:185], v[88:91], v[32:47]
	s_waitcnt lgkmcnt(2)
	v_mfma_f32_32x32x16_bf16 v[16:31], v[186:189], v[88:91], v[16:31]
	s_waitcnt lgkmcnt(0)
	v_mfma_f32_32x32x16_bf16 v[0:15], v[198:201], v[88:91], v[0:15]
	v_add_f32_e32 v176, v190, v191
	v_mov_b32_e32 v80, v174
	s_branch .Lattn2_tail

.LBB0_613:
	v_sub_f32_e32 v64, v195, v193
	v_fmamk_f32 v65, v160, 0x3fb8aa3b, v64
	v_exp_f32_e32 v81, v65
	v_fmamk_f32 v65, v161, 0x3fb8aa3b, v64
	v_exp_f32_e32 v82, v65
	v_fmamk_f32 v65, v162, 0x3fb8aa3b, v64
	v_exp_f32_e32 v83, v65
	v_fmamk_f32 v65, v163, 0x3fb8aa3b, v64
	v_exp_f32_e32 v84, v65
	v_fmamk_f32 v65, v164, 0x3fb8aa3b, v64
	v_exp_f32_e32 v85, v65
	v_fmamk_f32 v65, v165, 0x3fb8aa3b, v64
	v_exp_f32_e32 v86, v65
	v_fmamk_f32 v65, v166, 0x3fb8aa3b, v64
	v_exp_f32_e32 v87, v65
	v_fmamk_f32 v65, v167, 0x3fb8aa3b, v64
	v_exp_f32_e32 v88, v65
	v_fmamk_f32 v65, v168, 0x3fb8aa3b, v64
	v_exp_f32_e32 v89, v65
	v_fmamk_f32 v65, v169, 0x3fb8aa3b, v64
	v_exp_f32_e32 v90, v65
	v_fmamk_f32 v65, v170, 0x3fb8aa3b, v64
	v_exp_f32_e32 v91, v65
	v_fmamk_f32 v65, v171, 0x3fb8aa3b, v64
	v_exp_f32_e32 v92, v65
	v_fmamk_f32 v65, v172, 0x3fb8aa3b, v64
	v_exp_f32_e32 v93, v65
	v_fmamk_f32 v65, v173, 0x3fb8aa3b, v64
	v_exp_f32_e32 v94, v65
	v_fmamk_f32 v65, v174, 0x3fb8aa3b, v64
	v_exp_f32_e32 v95, v65
	v_fmamk_f32 v65, v175, 0x3fb8aa3b, v64
	v_exp_f32_e32 v160, v65
	v_fmamk_f32 v65, v176, 0x3fb8aa3b, v64
	v_exp_f32_e32 v161, v65
	v_fmamk_f32 v65, v177, 0x3fb8aa3b, v64
	v_exp_f32_e32 v162, v65
	v_fmamk_f32 v65, v178, 0x3fb8aa3b, v64
	v_exp_f32_e32 v163, v65
	v_fmamk_f32 v65, v179, 0x3fb8aa3b, v64
	v_exp_f32_e32 v164, v65
	v_fmamk_f32 v65, v180, 0x3fb8aa3b, v64
	v_exp_f32_e32 v165, v65
	v_fmamk_f32 v65, v181, 0x3fb8aa3b, v64
	v_exp_f32_e32 v166, v65
	v_fmamk_f32 v65, v182, 0x3fb8aa3b, v64
	v_exp_f32_e32 v167, v65
	v_fmamk_f32 v65, v183, 0x3fb8aa3b, v64
	v_exp_f32_e32 v168, v65
	v_fmamk_f32 v65, v184, 0x3fb8aa3b, v64
	v_exp_f32_e32 v169, v65
	v_fmamk_f32 v65, v185, 0x3fb8aa3b, v64
	v_exp_f32_e32 v170, v65
	v_fmamk_f32 v65, v186, 0x3fb8aa3b, v64
	v_exp_f32_e32 v171, v65
	v_fmamk_f32 v65, v187, 0x3fb8aa3b, v64
	v_exp_f32_e32 v172, v65
	v_fmamk_f32 v65, v188, 0x3fb8aa3b, v64
	v_exp_f32_e32 v173, v65
	v_fmamk_f32 v65, v189, 0x3fb8aa3b, v64
	v_exp_f32_e32 v174, v65
	v_fmamk_f32 v65, v190, 0x3fb8aa3b, v64
	v_fmac_f32_e32 v64, 0x3fb8aa3b, v191
	v_exp_f32_e32 v175, v65
	v_exp_f32_e32 v176, v64
	s_mul_i32 s54, s85, 0x5000
	v_cvt_pk_bf16_f32 v76, v81, v82
	v_cvt_pk_bf16_f32 v77, v83, v84
	v_cvt_pk_bf16_f32 v78, v85, v86
	v_cvt_pk_bf16_f32 v79, v87, v88
	v_cvt_pk_bf16_f32 v72, v89, v90
	v_cvt_pk_bf16_f32 v73, v91, v92
	v_cvt_pk_bf16_f32 v74, v93, v94
	v_cvt_pk_bf16_f32 v75, v95, v160
	v_cvt_pk_bf16_f32 v68, v161, v162
	v_cvt_pk_bf16_f32 v69, v163, v164
	v_cvt_pk_bf16_f32 v70, v165, v166
	v_cvt_pk_bf16_f32 v71, v167, v168
	v_cvt_pk_bf16_f32 v64, v169, v170
	v_cvt_pk_bf16_f32 v65, v171, v172
	v_cvt_pk_bf16_f32 v66, v173, v174
	v_cvt_pk_bf16_f32 v67, v175, v176
	s_and_b64 vcc, exec, s[4:5]
	v_add_u32_e32 v177, s54, v230
	ds_read_b64_tr_b16 v[178:179], v177 offset:34816
	ds_read_b64_tr_b16 v[182:183], v177 offset:34880
	ds_read_b64_tr_b16 v[186:187], v177 offset:34944
	ds_read_b64_tr_b16 v[194:195], v177 offset:35008
	ds_read_b64_tr_b16 v[180:181], v177 offset:37376
	ds_read_b64_tr_b16 v[184:185], v177 offset:37440
	ds_read_b64_tr_b16 v[188:189], v177 offset:37504
	ds_read_b64_tr_b16 v[196:197], v177 offset:37568
	s_waitcnt lgkmcnt(3)
	v_mfma_f32_32x32x16_bf16 v[48:63], v[178:181], v[76:79], v[48:63]
	s_waitcnt lgkmcnt(2)
	v_mfma_f32_32x32x16_bf16 v[32:47], v[182:185], v[76:79], v[32:47]
	s_waitcnt lgkmcnt(1)
	v_mfma_f32_32x32x16_bf16 v[16:31], v[186:189], v[76:79], v[16:31]
	ds_read_b64_tr_b16 v[178:179], v177 offset:39936
	ds_read_b64_tr_b16 v[182:183], v177 offset:40000
	ds_read_b64_tr_b16 v[186:187], v177 offset:40064
	ds_read_b64_tr_b16 v[198:199], v177 offset:40128
	ds_read_b64_tr_b16 v[180:181], v177 offset:42496
	ds_read_b64_tr_b16 v[184:185], v177 offset:42560
	ds_read_b64_tr_b16 v[188:189], v177 offset:42624
	ds_read_b64_tr_b16 v[200:201], v177 offset:42688
	s_waitcnt lgkmcnt(8)
	v_mfma_f32_32x32x16_bf16 v[0:15], v[194:197], v[76:79], v[0:15]
	s_waitcnt lgkmcnt(3)
	v_mfma_f32_32x32x16_bf16 v[48:63], v[178:181], v[72:75], v[48:63]
	s_waitcnt lgkmcnt(2)
	v_mfma_f32_32x32x16_bf16 v[32:47], v[182:185], v[72:75], v[32:47]
	s_waitcnt lgkmcnt(1)
	v_mfma_f32_32x32x16_bf16 v[16:31], v[186:189], v[72:75], v[16:31]
	ds_read_b64_tr_b16 v[178:179], v177 offset:45056
	ds_read_b64_tr_b16 v[182:183], v177 offset:45120
	ds_read_b64_tr_b16 v[186:187], v177 offset:45184
	ds_read_b64_tr_b16 v[194:195], v177 offset:45248
	ds_read_b64_tr_b16 v[180:181], v177 offset:47616
	ds_read_b64_tr_b16 v[184:185], v177 offset:47680
	ds_read_b64_tr_b16 v[188:189], v177 offset:47744
	ds_read_b64_tr_b16 v[196:197], v177 offset:47808
	s_waitcnt lgkmcnt(8)
	v_mfma_f32_32x32x16_bf16 v[0:15], v[198:201], v[72:75], v[0:15]
	s_waitcnt lgkmcnt(3)
	v_mfma_f32_32x32x16_bf16 v[48:63], v[178:181], v[68:71], v[48:63]
	s_waitcnt lgkmcnt(2)
	v_mfma_f32_32x32x16_bf16 v[32:47], v[182:185], v[68:71], v[32:47]
	s_waitcnt lgkmcnt(1)
	v_mfma_f32_32x32x16_bf16 v[16:31], v[186:189], v[68:71], v[16:31]
	ds_read_b64_tr_b16 v[178:179], v177 offset:50176
	ds_read_b64_tr_b16 v[182:183], v177 offset:50240
	ds_read_b64_tr_b16 v[186:187], v177 offset:50304
	ds_read_b64_tr_b16 v[198:199], v177 offset:50368
	ds_read_b64_tr_b16 v[180:181], v177 offset:52736
	ds_read_b64_tr_b16 v[184:185], v177 offset:52800
	ds_read_b64_tr_b16 v[188:189], v177 offset:52864
	ds_read_b64_tr_b16 v[200:201], v177 offset:52928
	s_waitcnt lgkmcnt(8)
	v_mfma_f32_32x32x16_bf16 v[0:15], v[194:197], v[68:71], v[0:15]
	s_waitcnt lgkmcnt(3)
	v_mfma_f32_32x32x16_bf16 v[48:63], v[178:181], v[64:67], v[48:63]
	s_waitcnt lgkmcnt(2)
	v_mfma_f32_32x32x16_bf16 v[32:47], v[182:185], v[64:67], v[32:47]
	s_waitcnt lgkmcnt(1)
	v_mfma_f32_32x32x16_bf16 v[16:31], v[186:189], v[64:67], v[16:31]
	s_waitcnt lgkmcnt(0)
	v_mfma_f32_32x32x16_bf16 v[0:15], v[198:201], v[64:67], v[0:15]

.Lattn2_tail:
	v_fmac_f32_e32 v176, v159, v80
	v_subrev_u32_e32 v192, 64, v192
	s_cmp_eq_u32 s82, s76
	v_lshl_add_u64 v[134:135], v[134:135], 0, s[50:51]
	s_cbranch_scc1 .LBB0_617
	s_mov_b32 s86, s76
	v_mov_b32_e32 v159, v176
	v_mov_b32_e32 v194, v193
	s_mov_b32 s55, s85
	s_mov_b32 s54, s33
	s_branch .LBB0_605
.LBB0_617:
	s_add_i32 s55, s84, 1
	s_cmp_lg_u32 s84, 2
	s_cselect_b32 s82, s55, 0
	s_add_i32 s84, 0, 0x4400
	s_mulk_i32 s82, 0x5000
	s_add_i32 s55, s82, 0
	v_add3_u32 v80, s84, v218, v220
	s_barrier
	s_waitcnt vmcnt(3)
	ds_write_b128 v80, v[108:111]
	v_add3_u32 v80, s55, v221, v220
	s_waitcnt vmcnt(2)
	ds_write_b128 v80, v[104:107] offset:34816
	v_add3_u32 v80, s84, v223, v220
	s_waitcnt vmcnt(1)
	ds_write_b128 v80, v[100:103]
	v_add3_u32 v80, s55, v224, v220
	s_and_b64 vcc, exec, s[6:7]
	s_waitcnt vmcnt(0)
	ds_write_b128 v80, v[96:99] offset:34816
	s_branch .LBB0_619
	v_add_u32_e32 v100, s54, v230
	ds_read_b64_tr_b16 v[80:81], v100 offset:34816
	ds_read_b64_tr_b16 v[84:85], v100 offset:34880
	ds_read_b64_tr_b16 v[88:89], v100 offset:34944
	ds_read_b64_tr_b16 v[92:93], v100 offset:35008
	ds_read_b64_tr_b16 v[82:83], v100 offset:37376
	ds_read_b64_tr_b16 v[86:87], v100 offset:37440
	ds_read_b64_tr_b16 v[90:91], v100 offset:37504
	ds_read_b64_tr_b16 v[94:95], v100 offset:37568
	s_waitcnt lgkmcnt(3)
	v_mfma_f32_32x32x16_bf16 v[48:63], v[80:83], v[76:79], v[48:63]
	s_waitcnt lgkmcnt(2)
	v_mfma_f32_32x32x16_bf16 v[32:47], v[84:87], v[76:79], v[32:47]
	s_waitcnt lgkmcnt(1)
	v_mfma_f32_32x32x16_bf16 v[16:31], v[88:91], v[76:79], v[16:31]
	ds_read_b64_tr_b16 v[80:81], v100 offset:39936
	ds_read_b64_tr_b16 v[84:85], v100 offset:40000
	ds_read_b64_tr_b16 v[88:89], v100 offset:40064
	ds_read_b64_tr_b16 v[96:97], v100 offset:40128
	ds_read_b64_tr_b16 v[82:83], v100 offset:42496
	ds_read_b64_tr_b16 v[86:87], v100 offset:42560
	ds_read_b64_tr_b16 v[90:91], v100 offset:42624
	ds_read_b64_tr_b16 v[98:99], v100 offset:42688
	s_waitcnt lgkmcnt(8)
	v_mfma_f32_32x32x16_bf16 v[0:15], v[92:95], v[76:79], v[0:15]
	s_waitcnt lgkmcnt(3)
	v_mfma_f32_32x32x16_bf16 v[48:63], v[80:83], v[72:75], v[48:63]
	s_waitcnt lgkmcnt(2)
	v_mfma_f32_32x32x16_bf16 v[32:47], v[84:87], v[72:75], v[32:47]
	s_waitcnt lgkmcnt(1)
	v_mfma_f32_32x32x16_bf16 v[16:31], v[88:91], v[72:75], v[16:31]
	ds_read_b64_tr_b16 v[76:77], v100 offset:45056
	ds_read_b64_tr_b16 v[80:81], v100 offset:45120
	ds_read_b64_tr_b16 v[84:85], v100 offset:45184
	ds_read_b64_tr_b16 v[88:89], v100 offset:45248
	ds_read_b64_tr_b16 v[78:79], v100 offset:47616
	ds_read_b64_tr_b16 v[82:83], v100 offset:47680
	ds_read_b64_tr_b16 v[86:87], v100 offset:47744
	ds_read_b64_tr_b16 v[90:91], v100 offset:47808
	s_waitcnt lgkmcnt(8)
	v_mfma_f32_32x32x16_bf16 v[0:15], v[96:99], v[72:75], v[0:15]
	s_waitcnt lgkmcnt(3)
	v_mfma_f32_32x32x16_bf16 v[48:63], v[76:79], v[68:71], v[48:63]
	s_waitcnt lgkmcnt(2)
	v_mfma_f32_32x32x16_bf16 v[32:47], v[80:83], v[68:71], v[32:47]
	s_waitcnt lgkmcnt(1)
	v_mfma_f32_32x32x16_bf16 v[16:31], v[84:87], v[68:71], v[16:31]
	ds_read_b64_tr_b16 v[72:73], v100 offset:50176
	ds_read_b64_tr_b16 v[76:77], v100 offset:50240
	ds_read_b64_tr_b16 v[80:81], v100 offset:50304
	ds_read_b64_tr_b16 v[84:85], v100 offset:50368
	ds_read_b64_tr_b16 v[74:75], v100 offset:52736
	ds_read_b64_tr_b16 v[78:79], v100 offset:52800
	ds_read_b64_tr_b16 v[82:83], v100 offset:52864
	ds_read_b64_tr_b16 v[86:87], v100 offset:52928
	s_waitcnt lgkmcnt(8)
	v_mfma_f32_32x32x16_bf16 v[0:15], v[88:91], v[68:71], v[0:15]
	s_waitcnt lgkmcnt(3)
	v_mfma_f32_32x32x16_bf16 v[48:63], v[72:75], v[64:67], v[48:63]
	s_waitcnt lgkmcnt(2)
	v_mfma_f32_32x32x16_bf16 v[32:47], v[76:79], v[64:67], v[32:47]
	s_waitcnt lgkmcnt(1)
	v_mfma_f32_32x32x16_bf16 v[16:31], v[80:83], v[64:67], v[16:31]
	s_waitcnt lgkmcnt(0)
	v_mfma_f32_32x32x16_bf16 v[0:15], v[84:87], v[64:67], v[0:15]

.LBB0_625:
	v_sub_f32_e32 v64, v97, v206
	v_fmamk_f32 v65, v98, 0x3fb8aa3b, v64
	v_exp_f32_e32 v97, v65
	v_fmamk_f32 v65, v99, 0x3fb8aa3b, v64
	v_exp_f32_e32 v177, v65
	v_fmamk_f32 v65, v100, 0x3fb8aa3b, v64
	v_exp_f32_e32 v178, v65
	v_fmamk_f32 v65, v101, 0x3fb8aa3b, v64
	v_exp_f32_e32 v179, v65
	v_fmamk_f32 v65, v102, 0x3fb8aa3b, v64
	v_exp_f32_e32 v180, v65
	v_fmamk_f32 v65, v103, 0x3fb8aa3b, v64
	v_exp_f32_e32 v181, v65
	v_fmamk_f32 v65, v104, 0x3fb8aa3b, v64
	v_exp_f32_e32 v182, v65
	v_fmamk_f32 v65, v105, 0x3fb8aa3b, v64
	v_exp_f32_e32 v183, v65
	v_fmamk_f32 v65, v106, 0x3fb8aa3b, v64
	v_exp_f32_e32 v184, v65
	v_fmamk_f32 v65, v107, 0x3fb8aa3b, v64
	v_exp_f32_e32 v185, v65
	v_fmamk_f32 v65, v108, 0x3fb8aa3b, v64
	v_exp_f32_e32 v186, v65
	v_fmamk_f32 v65, v109, 0x3fb8aa3b, v64
	v_exp_f32_e32 v187, v65
	v_fmamk_f32 v65, v110, 0x3fb8aa3b, v64
	v_exp_f32_e32 v188, v65
	v_fmamk_f32 v65, v111, 0x3fb8aa3b, v64
	v_exp_f32_e32 v189, v65
	v_fmamk_f32 v65, v134, 0x3fb8aa3b, v64
	v_exp_f32_e32 v190, v65
	v_fmamk_f32 v65, v135, 0x3fb8aa3b, v64
	v_exp_f32_e32 v191, v65
	v_fmamk_f32 v65, v160, 0x3fb8aa3b, v64
	v_exp_f32_e32 v192, v65
	v_fmamk_f32 v65, v161, 0x3fb8aa3b, v64
	v_exp_f32_e32 v193, v65
	v_fmamk_f32 v65, v162, 0x3fb8aa3b, v64
	v_exp_f32_e32 v194, v65
	v_fmamk_f32 v65, v163, 0x3fb8aa3b, v64
	v_exp_f32_e32 v195, v65
	v_fmamk_f32 v65, v164, 0x3fb8aa3b, v64
	v_exp_f32_e32 v196, v65
	v_fmamk_f32 v65, v165, 0x3fb8aa3b, v64
	v_exp_f32_e32 v197, v65
	v_fmamk_f32 v65, v166, 0x3fb8aa3b, v64
	v_exp_f32_e32 v198, v65
	v_fmamk_f32 v65, v167, 0x3fb8aa3b, v64
	v_exp_f32_e32 v199, v65
	v_fmamk_f32 v65, v168, 0x3fb8aa3b, v64
	v_exp_f32_e32 v200, v65
	v_fmamk_f32 v65, v169, 0x3fb8aa3b, v64
	v_exp_f32_e32 v201, v65
	v_fmamk_f32 v65, v170, 0x3fb8aa3b, v64
	v_exp_f32_e32 v202, v65
	v_fmamk_f32 v65, v171, 0x3fb8aa3b, v64
	v_exp_f32_e32 v203, v65
	v_fmamk_f32 v65, v172, 0x3fb8aa3b, v64
	v_exp_f32_e32 v204, v65
	v_fmamk_f32 v65, v173, 0x3fb8aa3b, v64
	v_exp_f32_e32 v205, v65
	v_fmamk_f32 v65, v174, 0x3fb8aa3b, v64
	v_fmac_f32_e32 v64, 0x3fb8aa3b, v175
	v_exp_f32_e32 v174, v65
	v_exp_f32_e32 v175, v64
	v_cvt_pk_bf16_f32 v76, v97, v177
	v_cvt_pk_bf16_f32 v77, v178, v179
	v_cvt_pk_bf16_f32 v78, v180, v181
	v_cvt_pk_bf16_f32 v79, v182, v183
	v_cvt_pk_bf16_f32 v72, v184, v185
	v_cvt_pk_bf16_f32 v73, v186, v187
	v_cvt_pk_bf16_f32 v74, v188, v189
	v_cvt_pk_bf16_f32 v75, v190, v191
	v_cvt_pk_bf16_f32 v68, v192, v193
	v_cvt_pk_bf16_f32 v69, v194, v195
	v_cvt_pk_bf16_f32 v70, v196, v197
	v_cvt_pk_bf16_f32 v71, v198, v199
	v_cvt_pk_bf16_f32 v64, v200, v201
	v_cvt_pk_bf16_f32 v65, v202, v203
	v_cvt_pk_bf16_f32 v66, v204, v205
	v_cvt_pk_bf16_f32 v67, v174, v175
	s_and_b64 vcc, exec, s[4:5]
	v_add_u32_e32 v80, s81, v230
	ds_read_b64_tr_b16 v[82:83], v80 offset:34816
	ds_read_b64_tr_b16 v[86:87], v80 offset:34880
	ds_read_b64_tr_b16 v[90:91], v80 offset:34944
	ds_read_b64_tr_b16 v[98:99], v80 offset:35008
	ds_read_b64_tr_b16 v[84:85], v80 offset:37376
	ds_read_b64_tr_b16 v[88:89], v80 offset:37440
	ds_read_b64_tr_b16 v[92:93], v80 offset:37504
	ds_read_b64_tr_b16 v[100:101], v80 offset:37568
	s_waitcnt lgkmcnt(3)
	v_mfma_f32_32x32x16_bf16 v[48:63], v[82:85], v[76:79], v[48:63]
	s_waitcnt lgkmcnt(2)
	v_mfma_f32_32x32x16_bf16 v[32:47], v[86:89], v[76:79], v[32:47]
	s_waitcnt lgkmcnt(1)
	v_mfma_f32_32x32x16_bf16 v[16:31], v[90:93], v[76:79], v[16:31]
	ds_read_b64_tr_b16 v[82:83], v80 offset:39936
	ds_read_b64_tr_b16 v[86:87], v80 offset:40000
	ds_read_b64_tr_b16 v[90:91], v80 offset:40064
	ds_read_b64_tr_b16 v[102:103], v80 offset:40128
	ds_read_b64_tr_b16 v[84:85], v80 offset:42496
	ds_read_b64_tr_b16 v[88:89], v80 offset:42560
	ds_read_b64_tr_b16 v[92:93], v80 offset:42624
	ds_read_b64_tr_b16 v[104:105], v80 offset:42688
	s_waitcnt lgkmcnt(8)
	v_mfma_f32_32x32x16_bf16 v[0:15], v[98:101], v[76:79], v[0:15]
	s_waitcnt lgkmcnt(3)
	v_mfma_f32_32x32x16_bf16 v[48:63], v[82:85], v[72:75], v[48:63]
	s_waitcnt lgkmcnt(2)
	v_mfma_f32_32x32x16_bf16 v[32:47], v[86:89], v[72:75], v[32:47]
	s_waitcnt lgkmcnt(1)
	v_mfma_f32_32x32x16_bf16 v[16:31], v[90:93], v[72:75], v[16:31]
	ds_read_b64_tr_b16 v[82:83], v80 offset:45056
	ds_read_b64_tr_b16 v[86:87], v80 offset:45120
	ds_read_b64_tr_b16 v[90:91], v80 offset:45184
	ds_read_b64_tr_b16 v[98:99], v80 offset:45248
	ds_read_b64_tr_b16 v[84:85], v80 offset:47616
	ds_read_b64_tr_b16 v[88:89], v80 offset:47680
	ds_read_b64_tr_b16 v[92:93], v80 offset:47744
	ds_read_b64_tr_b16 v[100:101], v80 offset:47808
	s_waitcnt lgkmcnt(8)
	v_mfma_f32_32x32x16_bf16 v[0:15], v[102:105], v[72:75], v[0:15]
	s_waitcnt lgkmcnt(3)
	v_mfma_f32_32x32x16_bf16 v[48:63], v[82:85], v[68:71], v[48:63]
	s_waitcnt lgkmcnt(2)
	v_mfma_f32_32x32x16_bf16 v[32:47], v[86:89], v[68:71], v[32:47]
	s_waitcnt lgkmcnt(1)
	v_mfma_f32_32x32x16_bf16 v[16:31], v[90:93], v[68:71], v[16:31]
	ds_read_b64_tr_b16 v[82:83], v80 offset:50176
	ds_read_b64_tr_b16 v[86:87], v80 offset:50240
	ds_read_b64_tr_b16 v[90:91], v80 offset:50304
	ds_read_b64_tr_b16 v[102:103], v80 offset:50368
	ds_read_b64_tr_b16 v[84:85], v80 offset:52736
	ds_read_b64_tr_b16 v[88:89], v80 offset:52800
	ds_read_b64_tr_b16 v[92:93], v80 offset:52864
	ds_read_b64_tr_b16 v[104:105], v80 offset:52928
	s_waitcnt lgkmcnt(8)
	v_mfma_f32_32x32x16_bf16 v[0:15], v[98:101], v[68:71], v[0:15]
	s_waitcnt lgkmcnt(3)
	v_mfma_f32_32x32x16_bf16 v[48:63], v[82:85], v[64:67], v[48:63]
	s_waitcnt lgkmcnt(2)
	v_mfma_f32_32x32x16_bf16 v[32:47], v[86:89], v[64:67], v[32:47]
	s_waitcnt lgkmcnt(1)
	v_mfma_f32_32x32x16_bf16 v[16:31], v[90:93], v[64:67], v[16:31]
	s_waitcnt lgkmcnt(0)
	v_mfma_f32_32x32x16_bf16 v[0:15], v[102:105], v[64:67], v[0:15]
.LBB0_627:
	s_and_b64 vcc, exec, s[6:7]
	s_barrier
	s_branch .LBB0_629
	ds_read_b64_tr_b16 v[82:83], v80 offset:34816
	ds_read_b64_tr_b16 v[86:87], v80 offset:34880
	ds_read_b64_tr_b16 v[90:91], v80 offset:34944
	ds_read_b64_tr_b16 v[98:99], v80 offset:35008
	ds_read_b64_tr_b16 v[84:85], v80 offset:37376
	ds_read_b64_tr_b16 v[88:89], v80 offset:37440
	ds_read_b64_tr_b16 v[92:93], v80 offset:37504
	ds_read_b64_tr_b16 v[100:101], v80 offset:37568
	s_waitcnt lgkmcnt(3)
	v_mfma_f32_32x32x16_bf16 v[48:63], v[82:85], v[76:79], v[48:63]
	s_waitcnt lgkmcnt(2)
	v_mfma_f32_32x32x16_bf16 v[32:47], v[86:89], v[76:79], v[32:47]
	s_waitcnt lgkmcnt(1)
	v_mfma_f32_32x32x16_bf16 v[16:31], v[90:93], v[76:79], v[16:31]
	ds_read_b64_tr_b16 v[82:83], v80 offset:39936
	ds_read_b64_tr_b16 v[86:87], v80 offset:40000
	ds_read_b64_tr_b16 v[90:91], v80 offset:40064
	ds_read_b64_tr_b16 v[102:103], v80 offset:40128
	ds_read_b64_tr_b16 v[84:85], v80 offset:42496
	ds_read_b64_tr_b16 v[88:89], v80 offset:42560
	ds_read_b64_tr_b16 v[92:93], v80 offset:42624
	ds_read_b64_tr_b16 v[104:105], v80 offset:42688
	s_waitcnt lgkmcnt(8)
	v_mfma_f32_32x32x16_bf16 v[0:15], v[98:101], v[76:79], v[0:15]
	s_waitcnt lgkmcnt(3)
	v_mfma_f32_32x32x16_bf16 v[48:63], v[82:85], v[72:75], v[48:63]
	s_waitcnt lgkmcnt(2)
	v_mfma_f32_32x32x16_bf16 v[32:47], v[86:89], v[72:75], v[32:47]
	s_waitcnt lgkmcnt(1)
	v_mfma_f32_32x32x16_bf16 v[16:31], v[90:93], v[72:75], v[16:31]
	ds_read_b64_tr_b16 v[76:77], v80 offset:45056
	ds_read_b64_tr_b16 v[82:83], v80 offset:45120
	ds_read_b64_tr_b16 v[86:87], v80 offset:45184
	ds_read_b64_tr_b16 v[90:91], v80 offset:45248
	ds_read_b64_tr_b16 v[78:79], v80 offset:47616
	ds_read_b64_tr_b16 v[84:85], v80 offset:47680
	ds_read_b64_tr_b16 v[88:89], v80 offset:47744
	ds_read_b64_tr_b16 v[92:93], v80 offset:47808
	s_waitcnt lgkmcnt(8)
	v_mfma_f32_32x32x16_bf16 v[0:15], v[102:105], v[72:75], v[0:15]
	s_waitcnt lgkmcnt(3)
	v_mfma_f32_32x32x16_bf16 v[48:63], v[76:79], v[68:71], v[48:63]
	s_waitcnt lgkmcnt(2)
	v_mfma_f32_32x32x16_bf16 v[32:47], v[82:85], v[68:71], v[32:47]
	s_waitcnt lgkmcnt(1)
	v_mfma_f32_32x32x16_bf16 v[16:31], v[86:89], v[68:71], v[16:31]
	ds_read_b64_tr_b16 v[72:73], v80 offset:50176
	ds_read_b64_tr_b16 v[76:77], v80 offset:50240
	ds_read_b64_tr_b16 v[82:83], v80 offset:50304
	ds_read_b64_tr_b16 v[86:87], v80 offset:50368
	ds_read_b64_tr_b16 v[74:75], v80 offset:52736
	ds_read_b64_tr_b16 v[78:79], v80 offset:52800
	ds_read_b64_tr_b16 v[84:85], v80 offset:52864
	ds_read_b64_tr_b16 v[88:89], v80 offset:52928
	s_waitcnt lgkmcnt(8)
	v_mfma_f32_32x32x16_bf16 v[0:15], v[90:93], v[68:71], v[0:15]
	s_waitcnt lgkmcnt(3)
	v_mfma_f32_32x32x16_bf16 v[48:63], v[72:75], v[64:67], v[48:63]
	s_waitcnt lgkmcnt(2)
	v_mfma_f32_32x32x16_bf16 v[32:47], v[76:79], v[64:67], v[32:47]
	s_waitcnt lgkmcnt(1)
	v_mfma_f32_32x32x16_bf16 v[16:31], v[82:85], v[64:67], v[16:31]
	s_waitcnt lgkmcnt(0)
	v_mfma_f32_32x32x16_bf16 v[0:15], v[86:89], v[64:67], v[0:15]

.LBB0_635:
	v_sub_f32_e32 v64, v116, v64
	v_fmamk_f32 v65, v98, 0x3fb8aa3b, v64
	v_exp_f32_e32 v81, v65
	v_fmamk_f32 v65, v99, 0x3fb8aa3b, v64
	v_exp_f32_e32 v82, v65
	v_fmamk_f32 v65, v100, 0x3fb8aa3b, v64
	v_exp_f32_e32 v83, v65
	v_fmamk_f32 v65, v101, 0x3fb8aa3b, v64
	v_exp_f32_e32 v84, v65
	v_fmamk_f32 v65, v102, 0x3fb8aa3b, v64
	v_exp_f32_e32 v85, v65
	v_fmamk_f32 v65, v103, 0x3fb8aa3b, v64
	v_exp_f32_e32 v86, v65
	v_fmamk_f32 v65, v104, 0x3fb8aa3b, v64
	v_exp_f32_e32 v87, v65
	v_fmamk_f32 v65, v105, 0x3fb8aa3b, v64
	v_exp_f32_e32 v88, v65
	v_fmamk_f32 v65, v106, 0x3fb8aa3b, v64
	v_exp_f32_e32 v89, v65
	v_fmamk_f32 v65, v107, 0x3fb8aa3b, v64
	v_exp_f32_e32 v90, v65
	v_fmamk_f32 v65, v108, 0x3fb8aa3b, v64
	v_exp_f32_e32 v91, v65
	v_fmamk_f32 v65, v109, 0x3fb8aa3b, v64
	v_exp_f32_e32 v92, v65
	v_fmamk_f32 v65, v110, 0x3fb8aa3b, v64
	v_exp_f32_e32 v93, v65
	v_fmamk_f32 v65, v111, 0x3fb8aa3b, v64
	v_exp_f32_e32 v94, v65
	v_fmamk_f32 v65, v134, 0x3fb8aa3b, v64
	v_exp_f32_e32 v95, v65
	v_fmamk_f32 v65, v135, 0x3fb8aa3b, v64
	v_exp_f32_e32 v98, v65
	v_fmamk_f32 v65, v158, 0x3fb8aa3b, v64
	v_exp_f32_e32 v99, v65
	v_fmamk_f32 v65, v159, 0x3fb8aa3b, v64
	v_exp_f32_e32 v100, v65
	v_fmamk_f32 v65, v160, 0x3fb8aa3b, v64
	v_exp_f32_e32 v101, v65
	v_fmamk_f32 v65, v161, 0x3fb8aa3b, v64
	v_exp_f32_e32 v102, v65
	v_fmamk_f32 v65, v162, 0x3fb8aa3b, v64
	v_exp_f32_e32 v103, v65
	v_fmamk_f32 v65, v163, 0x3fb8aa3b, v64
	v_exp_f32_e32 v104, v65
	v_fmamk_f32 v65, v164, 0x3fb8aa3b, v64
	v_exp_f32_e32 v105, v65
	v_fmamk_f32 v65, v165, 0x3fb8aa3b, v64
	v_exp_f32_e32 v106, v65
	v_fmamk_f32 v65, v166, 0x3fb8aa3b, v64
	v_exp_f32_e32 v107, v65
	v_fmamk_f32 v65, v167, 0x3fb8aa3b, v64
	v_exp_f32_e32 v108, v65
	v_fmamk_f32 v65, v168, 0x3fb8aa3b, v64
	v_exp_f32_e32 v109, v65
	v_fmamk_f32 v65, v169, 0x3fb8aa3b, v64
	v_exp_f32_e32 v110, v65
	v_fmamk_f32 v65, v170, 0x3fb8aa3b, v64
	v_exp_f32_e32 v111, v65
	v_fmamk_f32 v65, v171, 0x3fb8aa3b, v64
	v_exp_f32_e32 v116, v65
	v_fmamk_f32 v65, v172, 0x3fb8aa3b, v64
	v_fmac_f32_e32 v64, 0x3fb8aa3b, v173
	v_exp_f32_e32 v125, v65
	v_exp_f32_e32 v126, v64
	v_cvt_pk_bf16_f32 v76, v81, v82
	v_cvt_pk_bf16_f32 v77, v83, v84
	v_cvt_pk_bf16_f32 v78, v85, v86
	v_cvt_pk_bf16_f32 v79, v87, v88
	v_cvt_pk_bf16_f32 v72, v89, v90
	v_cvt_pk_bf16_f32 v73, v91, v92
	v_cvt_pk_bf16_f32 v74, v93, v94
	v_cvt_pk_bf16_f32 v75, v95, v98
	v_cvt_pk_bf16_f32 v68, v99, v100
	v_cvt_pk_bf16_f32 v69, v101, v102
	v_cvt_pk_bf16_f32 v70, v103, v104
	v_cvt_pk_bf16_f32 v71, v105, v106
	v_cvt_pk_bf16_f32 v64, v107, v108
	v_cvt_pk_bf16_f32 v65, v109, v110
	v_cvt_pk_bf16_f32 v66, v111, v116
	v_cvt_pk_bf16_f32 v67, v125, v126
	s_and_b64 vcc, exec, s[4:5]
	v_add_u32_e32 v133, s82, v230
	ds_read_b64_tr_b16 v[134:135], v133 offset:34816
	ds_read_b64_tr_b16 v[138:139], v133 offset:34880
	ds_read_b64_tr_b16 v[142:143], v133 offset:34944
	ds_read_b64_tr_b16 v[146:147], v133 offset:35008
	ds_read_b64_tr_b16 v[136:137], v133 offset:37376
	ds_read_b64_tr_b16 v[140:141], v133 offset:37440
	ds_read_b64_tr_b16 v[144:145], v133 offset:37504
	ds_read_b64_tr_b16 v[148:149], v133 offset:37568
	s_waitcnt lgkmcnt(3)
	v_mfma_f32_32x32x16_bf16 v[48:63], v[134:137], v[76:79], v[48:63]
	s_waitcnt lgkmcnt(2)
	v_mfma_f32_32x32x16_bf16 v[32:47], v[138:141], v[76:79], v[32:47]
	s_waitcnt lgkmcnt(1)
	v_mfma_f32_32x32x16_bf16 v[16:31], v[142:145], v[76:79], v[16:31]
	ds_read_b64_tr_b16 v[134:135], v133 offset:39936
	ds_read_b64_tr_b16 v[138:139], v133 offset:40000
	ds_read_b64_tr_b16 v[142:143], v133 offset:40064
	ds_read_b64_tr_b16 v[150:151], v133 offset:40128
	ds_read_b64_tr_b16 v[136:137], v133 offset:42496
	ds_read_b64_tr_b16 v[140:141], v133 offset:42560
	ds_read_b64_tr_b16 v[144:145], v133 offset:42624
	ds_read_b64_tr_b16 v[152:153], v133 offset:42688
	s_waitcnt lgkmcnt(8)
	v_mfma_f32_32x32x16_bf16 v[0:15], v[146:149], v[76:79], v[0:15]
	s_waitcnt lgkmcnt(3)
	v_mfma_f32_32x32x16_bf16 v[48:63], v[134:137], v[72:75], v[48:63]
	s_waitcnt lgkmcnt(2)
	v_mfma_f32_32x32x16_bf16 v[32:47], v[138:141], v[72:75], v[32:47]
	s_waitcnt lgkmcnt(1)
	v_mfma_f32_32x32x16_bf16 v[16:31], v[142:145], v[72:75], v[16:31]
	ds_read_b64_tr_b16 v[134:135], v133 offset:45056
	ds_read_b64_tr_b16 v[138:139], v133 offset:45120
	ds_read_b64_tr_b16 v[142:143], v133 offset:45184
	ds_read_b64_tr_b16 v[146:147], v133 offset:45248
	ds_read_b64_tr_b16 v[136:137], v133 offset:47616
	ds_read_b64_tr_b16 v[140:141], v133 offset:47680
	ds_read_b64_tr_b16 v[144:145], v133 offset:47744
	ds_read_b64_tr_b16 v[148:149], v133 offset:47808
	s_waitcnt lgkmcnt(8)
	v_mfma_f32_32x32x16_bf16 v[0:15], v[150:153], v[72:75], v[0:15]
	s_waitcnt lgkmcnt(3)
	v_mfma_f32_32x32x16_bf16 v[48:63], v[134:137], v[68:71], v[48:63]
	s_waitcnt lgkmcnt(2)
	v_mfma_f32_32x32x16_bf16 v[32:47], v[138:141], v[68:71], v[32:47]
	s_waitcnt lgkmcnt(1)
	v_mfma_f32_32x32x16_bf16 v[16:31], v[142:145], v[68:71], v[16:31]
	ds_read_b64_tr_b16 v[134:135], v133 offset:50176
	ds_read_b64_tr_b16 v[138:139], v133 offset:50240
	ds_read_b64_tr_b16 v[142:143], v133 offset:50304
	ds_read_b64_tr_b16 v[150:151], v133 offset:50368
	ds_read_b64_tr_b16 v[136:137], v133 offset:52736
	ds_read_b64_tr_b16 v[140:141], v133 offset:52800
	ds_read_b64_tr_b16 v[144:145], v133 offset:52864
	ds_read_b64_tr_b16 v[152:153], v133 offset:52928
	s_waitcnt lgkmcnt(8)
	v_mfma_f32_32x32x16_bf16 v[0:15], v[146:149], v[68:71], v[0:15]
	s_waitcnt lgkmcnt(3)
	v_mfma_f32_32x32x16_bf16 v[48:63], v[134:137], v[64:67], v[48:63]
	s_waitcnt lgkmcnt(2)
	v_mfma_f32_32x32x16_bf16 v[32:47], v[138:141], v[64:67], v[32:47]
	s_waitcnt lgkmcnt(1)
	v_mfma_f32_32x32x16_bf16 v[16:31], v[142:145], v[64:67], v[16:31]
	s_waitcnt lgkmcnt(0)
	v_mfma_f32_32x32x16_bf16 v[0:15], v[150:153], v[64:67], v[0:15]
.LBB0_637:
	s_and_b64 vcc, exec, s[14:15]
	s_branch .LBB0_639
	ds_read_b64_tr_b16 v[134:135], v133 offset:34816
	ds_read_b64_tr_b16 v[138:139], v133 offset:34880
	ds_read_b64_tr_b16 v[142:143], v133 offset:34944
	ds_read_b64_tr_b16 v[146:147], v133 offset:35008
	ds_read_b64_tr_b16 v[136:137], v133 offset:37376
	ds_read_b64_tr_b16 v[140:141], v133 offset:37440
	ds_read_b64_tr_b16 v[144:145], v133 offset:37504
	ds_read_b64_tr_b16 v[148:149], v133 offset:37568
	s_waitcnt lgkmcnt(3)
	v_mfma_f32_32x32x16_bf16 v[48:63], v[134:137], v[76:79], v[48:63]
	s_waitcnt lgkmcnt(2)
	v_mfma_f32_32x32x16_bf16 v[32:47], v[138:141], v[76:79], v[32:47]
	s_waitcnt lgkmcnt(1)
	v_mfma_f32_32x32x16_bf16 v[16:31], v[142:145], v[76:79], v[16:31]
	ds_read_b64_tr_b16 v[134:135], v133 offset:39936
	ds_read_b64_tr_b16 v[138:139], v133 offset:40000
	ds_read_b64_tr_b16 v[142:143], v133 offset:40064
	ds_read_b64_tr_b16 v[150:151], v133 offset:40128
	ds_read_b64_tr_b16 v[136:137], v133 offset:42496
	ds_read_b64_tr_b16 v[140:141], v133 offset:42560
	ds_read_b64_tr_b16 v[144:145], v133 offset:42624
	ds_read_b64_tr_b16 v[152:153], v133 offset:42688
	s_waitcnt lgkmcnt(8)
	v_mfma_f32_32x32x16_bf16 v[0:15], v[146:149], v[76:79], v[0:15]
	s_waitcnt lgkmcnt(3)
	v_mfma_f32_32x32x16_bf16 v[48:63], v[134:137], v[72:75], v[48:63]
	s_waitcnt lgkmcnt(2)
	v_mfma_f32_32x32x16_bf16 v[32:47], v[138:141], v[72:75], v[32:47]
	s_waitcnt lgkmcnt(1)
	v_mfma_f32_32x32x16_bf16 v[16:31], v[142:145], v[72:75], v[16:31]
	ds_read_b64_tr_b16 v[76:77], v133 offset:45056
	ds_read_b64_tr_b16 v[134:135], v133 offset:45120
	ds_read_b64_tr_b16 v[138:139], v133 offset:45184
	ds_read_b64_tr_b16 v[142:143], v133 offset:45248
	ds_read_b64_tr_b16 v[78:79], v133 offset:47616
	ds_read_b64_tr_b16 v[136:137], v133 offset:47680
	ds_read_b64_tr_b16 v[140:141], v133 offset:47744
	ds_read_b64_tr_b16 v[144:145], v133 offset:47808
	s_waitcnt lgkmcnt(8)
	v_mfma_f32_32x32x16_bf16 v[0:15], v[150:153], v[72:75], v[0:15]
	s_waitcnt lgkmcnt(3)
	v_mfma_f32_32x32x16_bf16 v[48:63], v[76:79], v[68:71], v[48:63]
	s_waitcnt lgkmcnt(2)
	v_mfma_f32_32x32x16_bf16 v[32:47], v[134:137], v[68:71], v[32:47]
	s_waitcnt lgkmcnt(1)
	v_mfma_f32_32x32x16_bf16 v[16:31], v[138:141], v[68:71], v[16:31]
	ds_read_b64_tr_b16 v[72:73], v133 offset:50176
	ds_read_b64_tr_b16 v[76:77], v133 offset:50240
	ds_read_b64_tr_b16 v[134:135], v133 offset:50304
	ds_read_b64_tr_b16 v[138:139], v133 offset:50368
	ds_read_b64_tr_b16 v[74:75], v133 offset:52736
	ds_read_b64_tr_b16 v[78:79], v133 offset:52800
	ds_read_b64_tr_b16 v[136:137], v133 offset:52864
	ds_read_b64_tr_b16 v[140:141], v133 offset:52928
	s_waitcnt lgkmcnt(8)
	v_mfma_f32_32x32x16_bf16 v[0:15], v[142:145], v[68:71], v[0:15]
	s_waitcnt lgkmcnt(3)
	v_mfma_f32_32x32x16_bf16 v[48:63], v[72:75], v[64:67], v[48:63]
	s_waitcnt lgkmcnt(2)
	v_mfma_f32_32x32x16_bf16 v[32:47], v[76:79], v[64:67], v[32:47]
	s_waitcnt lgkmcnt(1)
	v_mfma_f32_32x32x16_bf16 v[16:31], v[134:137], v[64:67], v[16:31]
	s_waitcnt lgkmcnt(0)
	v_mfma_f32_32x32x16_bf16 v[0:15], v[138:141], v[64:67], v[0:15]

.LBB0_893:
	v_lshl_add_u32 v148, s38, 8, v150
	v_lshl_or_b32 v146, s33, 8, v152
	v_ashrrev_i32_e32 v149, 31, v148
	v_ashrrev_i32_e32 v147, 31, v146
	v_lshlrev_b64 v[144:145], 11, v[148:149]
	v_lshl_add_u64 v[144:145], v[144:145], 0, v[146:147]
	v_lshlrev_b64 v[144:145], 1, v[144:145]
	v_lshl_add_u64 v[160:161], s[10:11], 0, v[144:145]
	global_load_dwordx4 v[168:171], v[160:161], off
	global_load_dwordx4 v[172:175], v[160:161], off offset:256
	s_mov_b64 s[98:99], 0x10000
	v_lshl_add_u64 v[236:237], v[160:161], 0, s[98:99]
	global_load_dwordx4 v[176:179], v[236:237], off
	global_load_dwordx4 v[180:183], v[236:237], off offset:256
	s_mov_b64 s[98:99], 0x20000
	v_lshl_add_u64 v[234:235], v[160:161], 0, s[98:99]
	global_load_dwordx4 v[184:187], v[234:235], off
	global_load_dwordx4 v[188:191], v[234:235], off offset:256
	s_mov_b64 s[98:99], 0x30000
	v_lshl_add_u64 v[236:237], v[160:161], 0, s[98:99]
	global_load_dwordx4 v[192:195], v[236:237], off
	global_load_dwordx4 v[196:199], v[236:237], off offset:256
	s_mov_b64 s[98:99], 0x80000
	v_lshl_add_u64 v[234:235], v[160:161], 0, s[98:99]
	global_load_dwordx4 v[200:203], v[234:235], off
	global_load_dwordx4 v[204:207], v[234:235], off offset:256
	s_mov_b64 s[98:99], 0x90000
	v_lshl_add_u64 v[236:237], v[160:161], 0, s[98:99]
	global_load_dwordx4 v[208:211], v[236:237], off
	global_load_dwordx4 v[214:217], v[236:237], off offset:256
	s_mov_b64 s[98:99], 0xa0000
	v_lshl_add_u64 v[234:235], v[160:161], 0, s[98:99]
	global_load_dwordx4 v[218:221], v[234:235], off
	global_load_dwordx4 v[222:225], v[234:235], off offset:256
	s_mov_b64 s[98:99], 0xb0000
	v_lshl_add_u64 v[236:237], v[160:161], 0, s[98:99]
	global_load_dwordx4 v[226:229], v[236:237], off
	global_load_dwordx4 v[230:233], v[236:237], off offset:256
	s_nop 1
	s_waitcnt vmcnt(15)
	v_mov_b32_e32 v156, v168
	v_mov_b32_e32 v157, v169
	v_mov_b32_e32 v158, v170
	v_mov_b32_e32 v159, v171
	v_lshl_add_u64 v[162:163], s[12:13], 0, v[144:145]
	s_andn2_b64 vcc, exec, s[0:1]
	s_mov_b64 s[0:1], -1
	v_lshlrev_b32_e32 v164, 16, v156
	v_and_b32_e32 v165, 0xffff0000, v156
	v_lshlrev_b32_e32 v156, 16, v157
	v_and_b32_e32 v157, 0xffff0000, v157
	v_lshlrev_b32_e32 v166, 16, v158
	v_and_b32_e32 v167, 0xffff0000, v158
	v_lshlrev_b32_e32 v158, 16, v159
	v_and_b32_e32 v159, 0xffff0000, v159
	v_pk_fma_f32 v[126:127], v[156:157], s[18:19], v[126:127] op_sel_hi:[1,0,1]
	v_pk_fma_f32 v[156:157], v[158:159], s[18:19], v[122:123] op_sel_hi:[1,0,1]
	v_pk_fma_f32 v[122:123], v[166:167], s[18:19], v[120:121] op_sel_hi:[1,0,1]
	v_pk_fma_f32 v[124:125], v[164:165], s[18:19], v[124:125] op_sel_hi:[1,0,1]
	s_nop 0
	v_cvt_pk_bf16_f32 v120, v124, v125
	v_cvt_pk_bf16_f32 v121, v126, v127
	v_cvt_pk_bf16_f32 v122, v122, v123
	v_cvt_pk_bf16_f32 v123, v156, v157
	global_store_dwordx4 v[162:163], v[120:123], off
	s_nop 1
	s_waitcnt vmcnt(15)
	v_mov_b32_e32 v120, v172
	v_mov_b32_e32 v121, v173
	v_mov_b32_e32 v122, v174
	v_mov_b32_e32 v123, v175
	v_or_b32_e32 v124, 16, v148
	v_ashrrev_i32_e32 v125, 31, v124
	v_lshlrev_b64 v[124:125], 11, v[124:125]
	v_lshl_add_u64 v[124:125], v[124:125], 0, v[146:147]
	v_lshlrev_b64 v[124:125], 1, v[124:125]
	v_lshl_add_u64 v[126:127], s[10:11], 0, v[124:125]
	v_lshlrev_b32_e32 v156, 16, v120
	v_and_b32_e32 v157, 0xffff0000, v120
	v_lshlrev_b32_e32 v120, 16, v121
	v_and_b32_e32 v121, 0xffff0000, v121
	v_lshlrev_b32_e32 v158, 16, v122
	v_and_b32_e32 v159, 0xffff0000, v122
	v_lshlrev_b32_e32 v122, 16, v123
	v_and_b32_e32 v123, 0xffff0000, v123
	v_pk_fma_f32 v[118:119], v[120:121], s[18:19], v[118:119] op_sel_hi:[1,0,1]
	v_pk_fma_f32 v[120:121], v[122:123], s[18:19], v[114:115] op_sel_hi:[1,0,1]
	v_pk_fma_f32 v[114:115], v[158:159], s[18:19], v[112:113] op_sel_hi:[1,0,1]
	v_pk_fma_f32 v[116:117], v[156:157], s[18:19], v[116:117] op_sel_hi:[1,0,1]
	s_nop 0
	v_cvt_pk_bf16_f32 v112, v116, v117
	v_cvt_pk_bf16_f32 v113, v118, v119
	v_cvt_pk_bf16_f32 v114, v114, v115
	v_cvt_pk_bf16_f32 v115, v120, v121
	global_store_dwordx4 v[162:163], v[112:115], off offset:256
	s_nop 1
	s_waitcnt vmcnt(15)
	v_mov_b32_e32 v112, v176
	v_mov_b32_e32 v113, v177
	v_mov_b32_e32 v114, v178
	v_mov_b32_e32 v115, v179
	v_lshl_add_u64 v[116:117], s[12:13], 0, v[124:125]
	v_lshlrev_b32_e32 v118, 16, v112
	v_and_b32_e32 v119, 0xffff0000, v112
	v_lshlrev_b32_e32 v112, 16, v113
	v_and_b32_e32 v113, 0xffff0000, v113
	v_lshlrev_b32_e32 v120, 16, v114
	v_and_b32_e32 v121, 0xffff0000, v114
	v_lshlrev_b32_e32 v114, 16, v115
	v_and_b32_e32 v115, 0xffff0000, v115
	v_pk_fma_f32 v[110:111], v[112:113], s[18:19], v[110:111] op_sel_hi:[1,0,1]
	v_pk_fma_f32 v[112:113], v[114:115], s[18:19], v[106:107] op_sel_hi:[1,0,1]
	v_pk_fma_f32 v[106:107], v[120:121], s[18:19], v[104:105] op_sel_hi:[1,0,1]
	v_pk_fma_f32 v[108:109], v[118:119], s[18:19], v[108:109] op_sel_hi:[1,0,1]
	s_nop 0
	v_cvt_pk_bf16_f32 v104, v108, v109
	v_cvt_pk_bf16_f32 v105, v110, v111
	v_cvt_pk_bf16_f32 v106, v106, v107
	v_cvt_pk_bf16_f32 v107, v112, v113
	global_store_dwordx4 v[116:117], v[104:107], off
	s_nop 1
	s_waitcnt vmcnt(15)
	v_mov_b32_e32 v104, v180
	v_mov_b32_e32 v105, v181
	v_mov_b32_e32 v106, v182
	v_mov_b32_e32 v107, v183
	v_or_b32_e32 v108, 32, v148
	v_ashrrev_i32_e32 v109, 31, v108
	v_lshlrev_b64 v[108:109], 11, v[108:109]
	v_lshl_add_u64 v[108:109], v[108:109], 0, v[146:147]
	v_lshlrev_b64 v[108:109], 1, v[108:109]
	v_lshl_add_u64 v[110:111], s[10:11], 0, v[108:109]
	v_lshlrev_b32_e32 v112, 16, v104
	v_and_b32_e32 v113, 0xffff0000, v104
	v_lshlrev_b32_e32 v104, 16, v105
	v_and_b32_e32 v105, 0xffff0000, v105
	v_lshlrev_b32_e32 v114, 16, v106
	v_and_b32_e32 v115, 0xffff0000, v106
	v_lshlrev_b32_e32 v106, 16, v107
	v_and_b32_e32 v107, 0xffff0000, v107
	v_pk_fma_f32 v[102:103], v[104:105], s[18:19], v[102:103] op_sel_hi:[1,0,1]
	v_pk_fma_f32 v[104:105], v[106:107], s[18:19], v[98:99] op_sel_hi:[1,0,1]
	v_pk_fma_f32 v[98:99], v[114:115], s[18:19], v[96:97] op_sel_hi:[1,0,1]
	v_pk_fma_f32 v[100:101], v[112:113], s[18:19], v[100:101] op_sel_hi:[1,0,1]
	s_nop 0
	v_cvt_pk_bf16_f32 v96, v100, v101
	v_cvt_pk_bf16_f32 v97, v102, v103
	v_cvt_pk_bf16_f32 v98, v98, v99
	v_cvt_pk_bf16_f32 v99, v104, v105
	global_store_dwordx4 v[116:117], v[96:99], off offset:256
	s_nop 1
	s_waitcnt vmcnt(15)
	v_mov_b32_e32 v96, v184
	v_mov_b32_e32 v97, v185
	v_mov_b32_e32 v98, v186
	v_mov_b32_e32 v99, v187
	v_lshl_add_u64 v[100:101], s[12:13], 0, v[108:109]
	v_lshlrev_b32_e32 v102, 16, v96
	v_and_b32_e32 v103, 0xffff0000, v96
	v_lshlrev_b32_e32 v96, 16, v97
	v_and_b32_e32 v97, 0xffff0000, v97
	v_lshlrev_b32_e32 v104, 16, v98
	v_and_b32_e32 v105, 0xffff0000, v98
	v_lshlrev_b32_e32 v98, 16, v99
	v_and_b32_e32 v99, 0xffff0000, v99
	v_pk_fma_f32 v[94:95], v[96:97], s[18:19], v[94:95] op_sel_hi:[1,0,1]
	v_pk_fma_f32 v[96:97], v[98:99], s[18:19], v[90:91] op_sel_hi:[1,0,1]
	v_pk_fma_f32 v[90:91], v[104:105], s[18:19], v[88:89] op_sel_hi:[1,0,1]
	v_pk_fma_f32 v[92:93], v[102:103], s[18:19], v[92:93] op_sel_hi:[1,0,1]
	s_nop 0
	v_cvt_pk_bf16_f32 v88, v92, v93
	v_cvt_pk_bf16_f32 v89, v94, v95
	v_cvt_pk_bf16_f32 v90, v90, v91
	v_cvt_pk_bf16_f32 v91, v96, v97
	global_store_dwordx4 v[100:101], v[88:91], off
	s_nop 1
	s_waitcnt vmcnt(15)
	v_mov_b32_e32 v88, v188
	v_mov_b32_e32 v89, v189
	v_mov_b32_e32 v90, v190
	v_mov_b32_e32 v91, v191
	v_or_b32_e32 v92, 48, v148
	v_ashrrev_i32_e32 v93, 31, v92
	v_lshlrev_b64 v[92:93], 11, v[92:93]
	v_lshl_add_u64 v[92:93], v[92:93], 0, v[146:147]
	v_lshlrev_b64 v[92:93], 1, v[92:93]
	v_lshl_add_u64 v[94:95], s[10:11], 0, v[92:93]
	v_lshlrev_b32_e32 v96, 16, v88
	v_and_b32_e32 v97, 0xffff0000, v88
	v_lshlrev_b32_e32 v88, 16, v89
	v_and_b32_e32 v89, 0xffff0000, v89
	v_lshlrev_b32_e32 v98, 16, v90
	v_and_b32_e32 v99, 0xffff0000, v90
	v_lshlrev_b32_e32 v90, 16, v91
	v_and_b32_e32 v91, 0xffff0000, v91
	v_pk_fma_f32 v[86:87], v[88:89], s[18:19], v[86:87] op_sel_hi:[1,0,1]
	v_pk_fma_f32 v[88:89], v[90:91], s[18:19], v[82:83] op_sel_hi:[1,0,1]
	v_pk_fma_f32 v[82:83], v[98:99], s[18:19], v[80:81] op_sel_hi:[1,0,1]
	v_pk_fma_f32 v[84:85], v[96:97], s[18:19], v[84:85] op_sel_hi:[1,0,1]
	s_nop 0
	v_cvt_pk_bf16_f32 v80, v84, v85
	v_cvt_pk_bf16_f32 v81, v86, v87
	v_cvt_pk_bf16_f32 v82, v82, v83
	v_cvt_pk_bf16_f32 v83, v88, v89
	global_store_dwordx4 v[100:101], v[80:83], off offset:256
	s_nop 1
	s_waitcnt vmcnt(15)
	v_mov_b32_e32 v80, v192
	v_mov_b32_e32 v81, v193
	v_mov_b32_e32 v82, v194
	v_mov_b32_e32 v83, v195
	v_lshl_add_u64 v[84:85], s[12:13], 0, v[92:93]
	v_lshlrev_b32_e32 v86, 16, v80
	v_and_b32_e32 v87, 0xffff0000, v80
	v_lshlrev_b32_e32 v80, 16, v81
	v_and_b32_e32 v81, 0xffff0000, v81
	v_lshlrev_b32_e32 v88, 16, v82
	v_and_b32_e32 v89, 0xffff0000, v82
	v_lshlrev_b32_e32 v82, 16, v83
	v_and_b32_e32 v83, 0xffff0000, v83
	v_pk_fma_f32 v[78:79], v[80:81], s[18:19], v[78:79] op_sel_hi:[1,0,1]
	v_pk_fma_f32 v[80:81], v[82:83], s[18:19], v[74:75] op_sel_hi:[1,0,1]
	v_pk_fma_f32 v[74:75], v[88:89], s[18:19], v[72:73] op_sel_hi:[1,0,1]
	v_pk_fma_f32 v[76:77], v[86:87], s[18:19], v[76:77] op_sel_hi:[1,0,1]
	s_nop 0
	v_cvt_pk_bf16_f32 v72, v76, v77
	v_cvt_pk_bf16_f32 v73, v78, v79
	v_cvt_pk_bf16_f32 v74, v74, v75
	v_cvt_pk_bf16_f32 v75, v80, v81
	global_store_dwordx4 v[84:85], v[72:75], off
	s_nop 1
	s_waitcnt vmcnt(15)
	v_mov_b32_e32 v72, v196
	v_mov_b32_e32 v73, v197
	v_mov_b32_e32 v74, v198
	v_mov_b32_e32 v75, v199
	v_lshl_add_u64 v[76:77], v[144:145], 0, s[6:7]
	v_lshl_add_u64 v[78:79], s[10:11], 0, v[76:77]
	v_lshlrev_b32_e32 v80, 16, v72
	v_and_b32_e32 v81, 0xffff0000, v72
	v_lshlrev_b32_e32 v72, 16, v73
	v_and_b32_e32 v73, 0xffff0000, v73
	v_lshlrev_b32_e32 v82, 16, v74
	v_and_b32_e32 v83, 0xffff0000, v74
	v_lshlrev_b32_e32 v74, 16, v75
	v_and_b32_e32 v75, 0xffff0000, v75
	v_pk_fma_f32 v[70:71], v[72:73], s[18:19], v[70:71] op_sel_hi:[1,0,1]
	v_pk_fma_f32 v[72:73], v[74:75], s[18:19], v[66:67] op_sel_hi:[1,0,1]
	v_pk_fma_f32 v[66:67], v[82:83], s[18:19], v[64:65] op_sel_hi:[1,0,1]
	v_pk_fma_f32 v[68:69], v[80:81], s[18:19], v[68:69] op_sel_hi:[1,0,1]
	s_nop 0
	v_cvt_pk_bf16_f32 v64, v68, v69
	v_cvt_pk_bf16_f32 v65, v70, v71
	v_cvt_pk_bf16_f32 v66, v66, v67
	v_cvt_pk_bf16_f32 v67, v72, v73
	global_store_dwordx4 v[84:85], v[64:67], off offset:256
	s_nop 1
	s_waitcnt vmcnt(15)
	v_mov_b32_e32 v64, v200
	v_mov_b32_e32 v65, v201
	v_mov_b32_e32 v66, v202
	v_mov_b32_e32 v67, v203
	v_lshl_add_u64 v[68:69], s[12:13], 0, v[76:77]
	v_lshlrev_b32_e32 v70, 16, v64
	v_and_b32_e32 v71, 0xffff0000, v64
	v_lshlrev_b32_e32 v64, 16, v65
	v_and_b32_e32 v65, 0xffff0000, v65
	v_lshlrev_b32_e32 v72, 16, v66
	v_and_b32_e32 v73, 0xffff0000, v66
	v_lshlrev_b32_e32 v66, 16, v67
	v_and_b32_e32 v67, 0xffff0000, v67
	v_pk_fma_f32 v[62:63], v[64:65], s[18:19], v[62:63] op_sel_hi:[1,0,1]
	v_pk_fma_f32 v[64:65], v[66:67], s[18:19], v[58:59] op_sel_hi:[1,0,1]
	v_pk_fma_f32 v[58:59], v[72:73], s[18:19], v[56:57] op_sel_hi:[1,0,1]
	v_pk_fma_f32 v[60:61], v[70:71], s[18:19], v[60:61] op_sel_hi:[1,0,1]
	s_nop 0
	v_cvt_pk_bf16_f32 v56, v60, v61
	v_cvt_pk_bf16_f32 v57, v62, v63
	v_cvt_pk_bf16_f32 v58, v58, v59
	v_cvt_pk_bf16_f32 v59, v64, v65
	global_store_dwordx4 v[68:69], v[56:59], off
	s_nop 1
	s_waitcnt vmcnt(15)
	v_mov_b32_e32 v56, v204
	v_mov_b32_e32 v57, v205
	v_mov_b32_e32 v58, v206
	v_mov_b32_e32 v59, v207
	v_lshl_add_u64 v[60:61], v[144:145], 0, s[20:21]
	v_lshl_add_u64 v[62:63], s[10:11], 0, v[60:61]
	v_lshlrev_b32_e32 v64, 16, v56
	v_and_b32_e32 v65, 0xffff0000, v56
	v_lshlrev_b32_e32 v56, 16, v57
	v_and_b32_e32 v57, 0xffff0000, v57
	v_lshlrev_b32_e32 v66, 16, v58
	v_and_b32_e32 v67, 0xffff0000, v58
	v_lshlrev_b32_e32 v58, 16, v59
	v_and_b32_e32 v59, 0xffff0000, v59
	v_pk_fma_f32 v[54:55], v[56:57], s[18:19], v[54:55] op_sel_hi:[1,0,1]
	v_pk_fma_f32 v[56:57], v[58:59], s[18:19], v[50:51] op_sel_hi:[1,0,1]
	v_pk_fma_f32 v[50:51], v[66:67], s[18:19], v[48:49] op_sel_hi:[1,0,1]
	v_pk_fma_f32 v[52:53], v[64:65], s[18:19], v[52:53] op_sel_hi:[1,0,1]
	s_nop 0
	v_cvt_pk_bf16_f32 v48, v52, v53
	v_cvt_pk_bf16_f32 v49, v54, v55
	v_cvt_pk_bf16_f32 v50, v50, v51
	v_cvt_pk_bf16_f32 v51, v56, v57
	global_store_dwordx4 v[68:69], v[48:51], off offset:256
	s_nop 1
	s_waitcnt vmcnt(15)
	v_mov_b32_e32 v48, v208
	v_mov_b32_e32 v49, v209
	v_mov_b32_e32 v50, v210
	v_mov_b32_e32 v51, v211
	v_lshl_add_u64 v[52:53], s[12:13], 0, v[60:61]
	v_lshlrev_b32_e32 v54, 16, v48
	v_and_b32_e32 v55, 0xffff0000, v48
	v_lshlrev_b32_e32 v48, 16, v49
	v_and_b32_e32 v49, 0xffff0000, v49
	v_lshlrev_b32_e32 v56, 16, v50
	v_and_b32_e32 v57, 0xffff0000, v50
	v_lshlrev_b32_e32 v50, 16, v51
	v_and_b32_e32 v51, 0xffff0000, v51
	v_pk_fma_f32 v[46:47], v[48:49], s[18:19], v[46:47] op_sel_hi:[1,0,1]
	v_pk_fma_f32 v[48:49], v[50:51], s[18:19], v[42:43] op_sel_hi:[1,0,1]
	v_pk_fma_f32 v[42:43], v[56:57], s[18:19], v[40:41] op_sel_hi:[1,0,1]
	v_pk_fma_f32 v[44:45], v[54:55], s[18:19], v[44:45] op_sel_hi:[1,0,1]
	s_nop 0
	v_cvt_pk_bf16_f32 v40, v44, v45
	v_cvt_pk_bf16_f32 v41, v46, v47
	v_cvt_pk_bf16_f32 v42, v42, v43
	v_cvt_pk_bf16_f32 v43, v48, v49
	global_store_dwordx4 v[52:53], v[40:43], off
	s_nop 1
	s_waitcnt vmcnt(15)
	v_mov_b32_e32 v40, v214
	v_mov_b32_e32 v41, v215
	v_mov_b32_e32 v42, v216
	v_mov_b32_e32 v43, v217
	v_lshl_add_u64 v[44:45], v[144:145], 0, s[22:23]
	v_lshl_add_u64 v[46:47], s[10:11], 0, v[44:45]
	v_lshlrev_b32_e32 v48, 16, v40
	v_and_b32_e32 v49, 0xffff0000, v40
	v_lshlrev_b32_e32 v40, 16, v41
	v_and_b32_e32 v41, 0xffff0000, v41
	v_lshlrev_b32_e32 v50, 16, v42
	v_and_b32_e32 v51, 0xffff0000, v42
	v_lshlrev_b32_e32 v42, 16, v43
	v_and_b32_e32 v43, 0xffff0000, v43
	v_pk_fma_f32 v[38:39], v[40:41], s[18:19], v[38:39] op_sel_hi:[1,0,1]
	v_pk_fma_f32 v[40:41], v[42:43], s[18:19], v[34:35] op_sel_hi:[1,0,1]
	v_pk_fma_f32 v[34:35], v[50:51], s[18:19], v[32:33] op_sel_hi:[1,0,1]
	v_pk_fma_f32 v[36:37], v[48:49], s[18:19], v[36:37] op_sel_hi:[1,0,1]
	s_nop 0
	v_cvt_pk_bf16_f32 v32, v36, v37
	v_cvt_pk_bf16_f32 v33, v38, v39
	v_cvt_pk_bf16_f32 v34, v34, v35
	v_cvt_pk_bf16_f32 v35, v40, v41
	global_store_dwordx4 v[52:53], v[32:35], off offset:256
	s_nop 1
	s_waitcnt vmcnt(15)
	v_mov_b32_e32 v32, v218
	v_mov_b32_e32 v33, v219
	v_mov_b32_e32 v34, v220
	v_mov_b32_e32 v35, v221
	v_lshl_add_u64 v[36:37], s[12:13], 0, v[44:45]
	v_lshlrev_b32_e32 v38, 16, v32
	v_and_b32_e32 v39, 0xffff0000, v32
	v_lshlrev_b32_e32 v32, 16, v33
	v_and_b32_e32 v33, 0xffff0000, v33
	v_lshlrev_b32_e32 v40, 16, v34
	v_and_b32_e32 v41, 0xffff0000, v34
	v_lshlrev_b32_e32 v34, 16, v35
	v_and_b32_e32 v35, 0xffff0000, v35
	v_pk_fma_f32 v[30:31], v[32:33], s[18:19], v[30:31] op_sel_hi:[1,0,1]
	v_pk_fma_f32 v[32:33], v[34:35], s[18:19], v[26:27] op_sel_hi:[1,0,1]
	v_pk_fma_f32 v[26:27], v[40:41], s[18:19], v[24:25] op_sel_hi:[1,0,1]
	v_pk_fma_f32 v[28:29], v[38:39], s[18:19], v[28:29] op_sel_hi:[1,0,1]
	s_nop 0
	v_cvt_pk_bf16_f32 v24, v28, v29
	v_cvt_pk_bf16_f32 v25, v30, v31
	v_cvt_pk_bf16_f32 v26, v26, v27
	v_cvt_pk_bf16_f32 v27, v32, v33
	global_store_dwordx4 v[36:37], v[24:27], off
	s_nop 1
	s_waitcnt vmcnt(15)
	v_mov_b32_e32 v24, v222
	v_mov_b32_e32 v25, v223
	v_mov_b32_e32 v26, v224
	v_mov_b32_e32 v27, v225
	v_lshl_add_u64 v[28:29], v[144:145], 0, s[24:25]
	v_lshl_add_u64 v[30:31], s[10:11], 0, v[28:29]
	v_lshlrev_b32_e32 v32, 16, v24
	v_and_b32_e32 v33, 0xffff0000, v24
	v_lshlrev_b32_e32 v24, 16, v25
	v_and_b32_e32 v25, 0xffff0000, v25
	v_lshlrev_b32_e32 v34, 16, v26
	v_and_b32_e32 v35, 0xffff0000, v26
	v_lshlrev_b32_e32 v26, 16, v27
	v_and_b32_e32 v27, 0xffff0000, v27
	v_pk_fma_f32 v[22:23], v[24:25], s[18:19], v[22:23] op_sel_hi:[1,0,1]
	v_pk_fma_f32 v[24:25], v[26:27], s[18:19], v[18:19] op_sel_hi:[1,0,1]
	v_pk_fma_f32 v[18:19], v[34:35], s[18:19], v[16:17] op_sel_hi:[1,0,1]
	v_pk_fma_f32 v[20:21], v[32:33], s[18:19], v[20:21] op_sel_hi:[1,0,1]
	s_nop 0
	v_cvt_pk_bf16_f32 v16, v20, v21
	v_cvt_pk_bf16_f32 v17, v22, v23
	v_cvt_pk_bf16_f32 v18, v18, v19
	v_cvt_pk_bf16_f32 v19, v24, v25
	global_store_dwordx4 v[36:37], v[16:19], off offset:256
	s_nop 1
	s_waitcnt vmcnt(15)
	v_mov_b32_e32 v16, v226
	v_mov_b32_e32 v17, v227
	v_mov_b32_e32 v18, v228
	v_mov_b32_e32 v19, v229
	v_lshl_add_u64 v[20:21], s[12:13], 0, v[28:29]
	v_lshlrev_b32_e32 v22, 16, v16
	v_and_b32_e32 v23, 0xffff0000, v16
	v_lshlrev_b32_e32 v16, 16, v17
	v_and_b32_e32 v17, 0xffff0000, v17
	v_lshlrev_b32_e32 v24, 16, v18
	v_and_b32_e32 v25, 0xffff0000, v18
	v_lshlrev_b32_e32 v18, 16, v19
	v_and_b32_e32 v19, 0xffff0000, v19
	v_pk_fma_f32 v[14:15], v[16:17], s[18:19], v[14:15] op_sel_hi:[1,0,1]
	v_pk_fma_f32 v[16:17], v[18:19], s[18:19], v[10:11] op_sel_hi:[1,0,1]
	v_pk_fma_f32 v[10:11], v[24:25], s[18:19], v[8:9] op_sel_hi:[1,0,1]
	v_pk_fma_f32 v[12:13], v[22:23], s[18:19], v[12:13] op_sel_hi:[1,0,1]
	s_nop 0
	v_cvt_pk_bf16_f32 v8, v12, v13
	v_cvt_pk_bf16_f32 v9, v14, v15
	v_cvt_pk_bf16_f32 v10, v10, v11
	v_cvt_pk_bf16_f32 v11, v16, v17
	global_store_dwordx4 v[20:21], v[8:11], off
	s_nop 1
	s_waitcnt vmcnt(15)
	v_mov_b32_e32 v8, v230
	v_mov_b32_e32 v9, v231
	v_mov_b32_e32 v10, v232
	v_mov_b32_e32 v11, v233
	v_lshlrev_b32_e32 v12, 16, v8
	v_and_b32_e32 v13, 0xffff0000, v8
	v_lshlrev_b32_e32 v8, 16, v9
	v_and_b32_e32 v9, 0xffff0000, v9
	v_lshlrev_b32_e32 v14, 16, v10
	v_and_b32_e32 v15, 0xffff0000, v10
	v_lshlrev_b32_e32 v10, 16, v11
	v_and_b32_e32 v11, 0xffff0000, v11
	v_pk_fma_f32 v[6:7], v[8:9], s[18:19], v[6:7] op_sel_hi:[1,0,1]
	v_pk_fma_f32 v[8:9], v[10:11], s[18:19], v[2:3] op_sel_hi:[1,0,1]
	v_pk_fma_f32 v[2:3], v[14:15], s[18:19], v[0:1] op_sel_hi:[1,0,1]
	v_pk_fma_f32 v[4:5], v[12:13], s[18:19], v[4:5] op_sel_hi:[1,0,1]
	s_nop 0
	v_cvt_pk_bf16_f32 v0, v4, v5
	v_cvt_pk_bf16_f32 v1, v6, v7
	v_cvt_pk_bf16_f32 v2, v2, v3
	v_cvt_pk_bf16_f32 v3, v8, v9
	global_store_dwordx4 v[20:21], v[0:3], off offset:256
	s_cbranch_vccnz .LBB0_882
	s_andn2_b64 vcc, exec, s[8:9]
	s_cbranch_vccnz .LBB0_881
	s_barrier
	s_branch .LBB0_881

.LBB0_1107:
	v_lshl_add_u32 v148, s33, 8, v150
	v_lshl_or_b32 v146, s57, 8, v152
	v_ashrrev_i32_e32 v149, 31, v148
	v_ashrrev_i32_e32 v147, 31, v146
	v_lshlrev_b64 v[144:145], 11, v[148:149]
	v_lshl_add_u64 v[144:145], v[144:145], 0, v[146:147]
	v_lshlrev_b64 v[144:145], 1, v[144:145]
	v_lshl_add_u64 v[160:161], s[10:11], 0, v[144:145]
	global_load_dwordx4 v[168:171], v[160:161], off
	global_load_dwordx4 v[172:175], v[160:161], off offset:256
	s_mov_b64 s[98:99], 0x10000
	v_lshl_add_u64 v[236:237], v[160:161], 0, s[98:99]
	global_load_dwordx4 v[176:179], v[236:237], off
	global_load_dwordx4 v[180:183], v[236:237], off offset:256
	s_mov_b64 s[98:99], 0x20000
	v_lshl_add_u64 v[234:235], v[160:161], 0, s[98:99]
	global_load_dwordx4 v[184:187], v[234:235], off
	global_load_dwordx4 v[188:191], v[234:235], off offset:256
	s_mov_b64 s[98:99], 0x30000
	v_lshl_add_u64 v[236:237], v[160:161], 0, s[98:99]
	global_load_dwordx4 v[192:195], v[236:237], off
	global_load_dwordx4 v[196:199], v[236:237], off offset:256
	s_mov_b64 s[98:99], 0x80000
	v_lshl_add_u64 v[234:235], v[160:161], 0, s[98:99]
	global_load_dwordx4 v[200:203], v[234:235], off
	global_load_dwordx4 v[204:207], v[234:235], off offset:256
	s_mov_b64 s[98:99], 0x90000
	v_lshl_add_u64 v[236:237], v[160:161], 0, s[98:99]
	global_load_dwordx4 v[208:211], v[236:237], off
	global_load_dwordx4 v[214:217], v[236:237], off offset:256
	s_mov_b64 s[98:99], 0xa0000
	v_lshl_add_u64 v[234:235], v[160:161], 0, s[98:99]
	global_load_dwordx4 v[218:221], v[234:235], off
	global_load_dwordx4 v[222:225], v[234:235], off offset:256
	s_mov_b64 s[98:99], 0xb0000
	v_lshl_add_u64 v[236:237], v[160:161], 0, s[98:99]
	global_load_dwordx4 v[226:229], v[236:237], off
	global_load_dwordx4 v[230:233], v[236:237], off offset:256
	s_nop 1
	s_waitcnt vmcnt(15)
	v_mov_b32_e32 v156, v168
	v_mov_b32_e32 v157, v169
	v_mov_b32_e32 v158, v170
	v_mov_b32_e32 v159, v171
	v_lshl_add_u64 v[162:163], s[12:13], 0, v[144:145]
	s_and_b64 vcc, exec, s[0:1]
	s_mov_b64 s[0:1], -1
	v_lshlrev_b32_e32 v164, 16, v156
	v_and_b32_e32 v165, 0xffff0000, v156
	v_lshlrev_b32_e32 v156, 16, v157
	v_and_b32_e32 v157, 0xffff0000, v157
	v_lshlrev_b32_e32 v166, 16, v158
	v_and_b32_e32 v167, 0xffff0000, v158
	v_lshlrev_b32_e32 v158, 16, v159
	v_and_b32_e32 v159, 0xffff0000, v159
	v_pk_mul_f32 v[156:157], v[156:157], s[18:19] op_sel_hi:[1,0]
	v_pk_mul_f32 v[166:167], v[166:167], s[18:19] op_sel_hi:[1,0]
	v_pk_mul_f32 v[158:159], v[158:159], s[18:19] op_sel_hi:[1,0]
	v_pk_mul_f32 v[164:165], v[164:165], s[18:19] op_sel_hi:[1,0]
	v_pk_fma_f32 v[126:127], v[126:127], 0.5, v[156:157] op_sel_hi:[1,0,1]
	v_pk_fma_f32 v[156:157], v[122:123], 0.5, v[158:159] op_sel_hi:[1,0,1]
	v_pk_fma_f32 v[122:123], v[120:121], 0.5, v[166:167] op_sel_hi:[1,0,1]
	v_pk_fma_f32 v[124:125], v[124:125], 0.5, v[164:165] op_sel_hi:[1,0,1]
	s_nop 0
	v_cvt_pk_bf16_f32 v120, v124, v125
	v_cvt_pk_bf16_f32 v121, v126, v127
	v_cvt_pk_bf16_f32 v122, v122, v123
	v_cvt_pk_bf16_f32 v123, v156, v157
	global_store_dwordx4 v[162:163], v[120:123], off
	s_nop 1
	s_waitcnt vmcnt(15)
	v_mov_b32_e32 v120, v172
	v_mov_b32_e32 v121, v173
	v_mov_b32_e32 v122, v174
	v_mov_b32_e32 v123, v175
	v_or_b32_e32 v124, 16, v148
	v_ashrrev_i32_e32 v125, 31, v124
	v_lshlrev_b64 v[124:125], 11, v[124:125]
	v_lshl_add_u64 v[124:125], v[124:125], 0, v[146:147]
	v_lshlrev_b64 v[124:125], 1, v[124:125]
	v_lshl_add_u64 v[126:127], s[10:11], 0, v[124:125]
	v_lshlrev_b32_e32 v156, 16, v120
	v_and_b32_e32 v157, 0xffff0000, v120
	v_lshlrev_b32_e32 v120, 16, v121
	v_and_b32_e32 v121, 0xffff0000, v121
	v_lshlrev_b32_e32 v158, 16, v122
	v_and_b32_e32 v159, 0xffff0000, v122
	v_lshlrev_b32_e32 v122, 16, v123
	v_and_b32_e32 v123, 0xffff0000, v123
	v_pk_mul_f32 v[120:121], v[120:121], s[18:19] op_sel_hi:[1,0]
	v_pk_mul_f32 v[158:159], v[158:159], s[18:19] op_sel_hi:[1,0]
	v_pk_mul_f32 v[122:123], v[122:123], s[18:19] op_sel_hi:[1,0]
	v_pk_mul_f32 v[156:157], v[156:157], s[18:19] op_sel_hi:[1,0]
	v_pk_fma_f32 v[118:119], v[118:119], 0.5, v[120:121] op_sel_hi:[1,0,1]
	v_pk_fma_f32 v[120:121], v[114:115], 0.5, v[122:123] op_sel_hi:[1,0,1]
	v_pk_fma_f32 v[114:115], v[112:113], 0.5, v[158:159] op_sel_hi:[1,0,1]
	v_pk_fma_f32 v[116:117], v[116:117], 0.5, v[156:157] op_sel_hi:[1,0,1]
	s_nop 0
	v_cvt_pk_bf16_f32 v112, v116, v117
	v_cvt_pk_bf16_f32 v113, v118, v119
	v_cvt_pk_bf16_f32 v114, v114, v115
	v_cvt_pk_bf16_f32 v115, v120, v121
	global_store_dwordx4 v[162:163], v[112:115], off offset:256
	s_nop 1
	s_waitcnt vmcnt(15)
	v_mov_b32_e32 v112, v176
	v_mov_b32_e32 v113, v177
	v_mov_b32_e32 v114, v178
	v_mov_b32_e32 v115, v179
	v_lshl_add_u64 v[116:117], s[12:13], 0, v[124:125]
	v_lshlrev_b32_e32 v118, 16, v112
	v_and_b32_e32 v119, 0xffff0000, v112
	v_lshlrev_b32_e32 v112, 16, v113
	v_and_b32_e32 v113, 0xffff0000, v113
	v_lshlrev_b32_e32 v120, 16, v114
	v_and_b32_e32 v121, 0xffff0000, v114
	v_lshlrev_b32_e32 v114, 16, v115
	v_and_b32_e32 v115, 0xffff0000, v115
	v_pk_mul_f32 v[112:113], v[112:113], s[18:19] op_sel_hi:[1,0]
	v_pk_mul_f32 v[120:121], v[120:121], s[18:19] op_sel_hi:[1,0]
	v_pk_mul_f32 v[114:115], v[114:115], s[18:19] op_sel_hi:[1,0]
	v_pk_mul_f32 v[118:119], v[118:119], s[18:19] op_sel_hi:[1,0]
	v_pk_fma_f32 v[110:111], v[110:111], 0.5, v[112:113] op_sel_hi:[1,0,1]
	v_pk_fma_f32 v[112:113], v[106:107], 0.5, v[114:115] op_sel_hi:[1,0,1]
	v_pk_fma_f32 v[106:107], v[104:105], 0.5, v[120:121] op_sel_hi:[1,0,1]
	v_pk_fma_f32 v[108:109], v[108:109], 0.5, v[118:119] op_sel_hi:[1,0,1]
	s_nop 0
	v_cvt_pk_bf16_f32 v104, v108, v109
	v_cvt_pk_bf16_f32 v105, v110, v111
	v_cvt_pk_bf16_f32 v106, v106, v107
	v_cvt_pk_bf16_f32 v107, v112, v113
	global_store_dwordx4 v[116:117], v[104:107], off
	s_nop 1
	s_waitcnt vmcnt(15)
	v_mov_b32_e32 v104, v180
	v_mov_b32_e32 v105, v181
	v_mov_b32_e32 v106, v182
	v_mov_b32_e32 v107, v183
	v_or_b32_e32 v108, 32, v148
	v_ashrrev_i32_e32 v109, 31, v108
	v_lshlrev_b64 v[108:109], 11, v[108:109]
	v_lshl_add_u64 v[108:109], v[108:109], 0, v[146:147]
	v_lshlrev_b64 v[108:109], 1, v[108:109]
	v_lshl_add_u64 v[110:111], s[10:11], 0, v[108:109]
	v_lshlrev_b32_e32 v112, 16, v104
	v_and_b32_e32 v113, 0xffff0000, v104
	v_lshlrev_b32_e32 v104, 16, v105
	v_and_b32_e32 v105, 0xffff0000, v105
	v_lshlrev_b32_e32 v114, 16, v106
	v_and_b32_e32 v115, 0xffff0000, v106
	v_lshlrev_b32_e32 v106, 16, v107
	v_and_b32_e32 v107, 0xffff0000, v107
	v_pk_mul_f32 v[104:105], v[104:105], s[18:19] op_sel_hi:[1,0]
	v_pk_mul_f32 v[114:115], v[114:115], s[18:19] op_sel_hi:[1,0]
	v_pk_mul_f32 v[106:107], v[106:107], s[18:19] op_sel_hi:[1,0]
	v_pk_mul_f32 v[112:113], v[112:113], s[18:19] op_sel_hi:[1,0]
	v_pk_fma_f32 v[102:103], v[102:103], 0.5, v[104:105] op_sel_hi:[1,0,1]
	v_pk_fma_f32 v[104:105], v[98:99], 0.5, v[106:107] op_sel_hi:[1,0,1]
	v_pk_fma_f32 v[98:99], v[96:97], 0.5, v[114:115] op_sel_hi:[1,0,1]
	v_pk_fma_f32 v[100:101], v[100:101], 0.5, v[112:113] op_sel_hi:[1,0,1]
	s_nop 0
	v_cvt_pk_bf16_f32 v96, v100, v101
	v_cvt_pk_bf16_f32 v97, v102, v103
	v_cvt_pk_bf16_f32 v98, v98, v99
	v_cvt_pk_bf16_f32 v99, v104, v105
	global_store_dwordx4 v[116:117], v[96:99], off offset:256
	s_nop 1
	s_waitcnt vmcnt(15)
	v_mov_b32_e32 v96, v184
	v_mov_b32_e32 v97, v185
	v_mov_b32_e32 v98, v186
	v_mov_b32_e32 v99, v187
	v_lshl_add_u64 v[100:101], s[12:13], 0, v[108:109]
	v_lshlrev_b32_e32 v102, 16, v96
	v_and_b32_e32 v103, 0xffff0000, v96
	v_lshlrev_b32_e32 v96, 16, v97
	v_and_b32_e32 v97, 0xffff0000, v97
	v_lshlrev_b32_e32 v104, 16, v98
	v_and_b32_e32 v105, 0xffff0000, v98
	v_lshlrev_b32_e32 v98, 16, v99
	v_and_b32_e32 v99, 0xffff0000, v99
	v_pk_mul_f32 v[96:97], v[96:97], s[18:19] op_sel_hi:[1,0]
	v_pk_mul_f32 v[104:105], v[104:105], s[18:19] op_sel_hi:[1,0]
	v_pk_mul_f32 v[98:99], v[98:99], s[18:19] op_sel_hi:[1,0]
	v_pk_mul_f32 v[102:103], v[102:103], s[18:19] op_sel_hi:[1,0]
	v_pk_fma_f32 v[94:95], v[94:95], 0.5, v[96:97] op_sel_hi:[1,0,1]
	v_pk_fma_f32 v[96:97], v[90:91], 0.5, v[98:99] op_sel_hi:[1,0,1]
	v_pk_fma_f32 v[90:91], v[88:89], 0.5, v[104:105] op_sel_hi:[1,0,1]
	v_pk_fma_f32 v[92:93], v[92:93], 0.5, v[102:103] op_sel_hi:[1,0,1]
	s_nop 0
	v_cvt_pk_bf16_f32 v88, v92, v93
	v_cvt_pk_bf16_f32 v89, v94, v95
	v_cvt_pk_bf16_f32 v90, v90, v91
	v_cvt_pk_bf16_f32 v91, v96, v97
	global_store_dwordx4 v[100:101], v[88:91], off
	s_nop 1
	s_waitcnt vmcnt(15)
	v_mov_b32_e32 v88, v188
	v_mov_b32_e32 v89, v189
	v_mov_b32_e32 v90, v190
	v_mov_b32_e32 v91, v191
	v_or_b32_e32 v92, 48, v148
	v_ashrrev_i32_e32 v93, 31, v92
	v_lshlrev_b64 v[92:93], 11, v[92:93]
	v_lshl_add_u64 v[92:93], v[92:93], 0, v[146:147]
	v_lshlrev_b64 v[92:93], 1, v[92:93]
	v_lshl_add_u64 v[94:95], s[10:11], 0, v[92:93]
	v_lshlrev_b32_e32 v96, 16, v88
	v_and_b32_e32 v97, 0xffff0000, v88
	v_lshlrev_b32_e32 v88, 16, v89
	v_and_b32_e32 v89, 0xffff0000, v89
	v_lshlrev_b32_e32 v98, 16, v90
	v_and_b32_e32 v99, 0xffff0000, v90
	v_lshlrev_b32_e32 v90, 16, v91
	v_and_b32_e32 v91, 0xffff0000, v91
	v_pk_mul_f32 v[88:89], v[88:89], s[18:19] op_sel_hi:[1,0]
	v_pk_mul_f32 v[98:99], v[98:99], s[18:19] op_sel_hi:[1,0]
	v_pk_mul_f32 v[90:91], v[90:91], s[18:19] op_sel_hi:[1,0]
	v_pk_mul_f32 v[96:97], v[96:97], s[18:19] op_sel_hi:[1,0]
	v_pk_fma_f32 v[86:87], v[86:87], 0.5, v[88:89] op_sel_hi:[1,0,1]
	v_pk_fma_f32 v[88:89], v[82:83], 0.5, v[90:91] op_sel_hi:[1,0,1]
	v_pk_fma_f32 v[82:83], v[80:81], 0.5, v[98:99] op_sel_hi:[1,0,1]
	v_pk_fma_f32 v[84:85], v[84:85], 0.5, v[96:97] op_sel_hi:[1,0,1]
	s_nop 0
	v_cvt_pk_bf16_f32 v80, v84, v85
	v_cvt_pk_bf16_f32 v81, v86, v87
	v_cvt_pk_bf16_f32 v82, v82, v83
	v_cvt_pk_bf16_f32 v83, v88, v89
	global_store_dwordx4 v[100:101], v[80:83], off offset:256
	s_nop 1
	s_waitcnt vmcnt(15)
	v_mov_b32_e32 v80, v192
	v_mov_b32_e32 v81, v193
	v_mov_b32_e32 v82, v194
	v_mov_b32_e32 v83, v195
	v_lshl_add_u64 v[84:85], s[12:13], 0, v[92:93]
	v_lshlrev_b32_e32 v86, 16, v80
	v_and_b32_e32 v87, 0xffff0000, v80
	v_lshlrev_b32_e32 v80, 16, v81
	v_and_b32_e32 v81, 0xffff0000, v81
	v_lshlrev_b32_e32 v88, 16, v82
	v_and_b32_e32 v89, 0xffff0000, v82
	v_lshlrev_b32_e32 v82, 16, v83
	v_and_b32_e32 v83, 0xffff0000, v83
	v_pk_mul_f32 v[80:81], v[80:81], s[18:19] op_sel_hi:[1,0]
	v_pk_mul_f32 v[88:89], v[88:89], s[18:19] op_sel_hi:[1,0]
	v_pk_mul_f32 v[82:83], v[82:83], s[18:19] op_sel_hi:[1,0]
	v_pk_mul_f32 v[86:87], v[86:87], s[18:19] op_sel_hi:[1,0]
	v_pk_fma_f32 v[78:79], v[78:79], 0.5, v[80:81] op_sel_hi:[1,0,1]
	v_pk_fma_f32 v[80:81], v[74:75], 0.5, v[82:83] op_sel_hi:[1,0,1]
	v_pk_fma_f32 v[74:75], v[72:73], 0.5, v[88:89] op_sel_hi:[1,0,1]
	v_pk_fma_f32 v[76:77], v[76:77], 0.5, v[86:87] op_sel_hi:[1,0,1]
	s_nop 0
	v_cvt_pk_bf16_f32 v72, v76, v77
	v_cvt_pk_bf16_f32 v73, v78, v79
	v_cvt_pk_bf16_f32 v74, v74, v75
	v_cvt_pk_bf16_f32 v75, v80, v81
	global_store_dwordx4 v[84:85], v[72:75], off
	s_nop 1
	s_waitcnt vmcnt(15)
	v_mov_b32_e32 v72, v196
	v_mov_b32_e32 v73, v197
	v_mov_b32_e32 v74, v198
	v_mov_b32_e32 v75, v199
	v_lshl_add_u64 v[76:77], v[144:145], 0, s[20:21]
	v_lshl_add_u64 v[78:79], s[10:11], 0, v[76:77]
	v_lshlrev_b32_e32 v80, 16, v72
	v_and_b32_e32 v81, 0xffff0000, v72
	v_lshlrev_b32_e32 v72, 16, v73
	v_and_b32_e32 v73, 0xffff0000, v73
	v_lshlrev_b32_e32 v82, 16, v74
	v_and_b32_e32 v83, 0xffff0000, v74
	v_lshlrev_b32_e32 v74, 16, v75
	v_and_b32_e32 v75, 0xffff0000, v75
	v_pk_mul_f32 v[72:73], v[72:73], s[18:19] op_sel_hi:[1,0]
	v_pk_mul_f32 v[82:83], v[82:83], s[18:19] op_sel_hi:[1,0]
	v_pk_mul_f32 v[74:75], v[74:75], s[18:19] op_sel_hi:[1,0]
	v_pk_mul_f32 v[80:81], v[80:81], s[18:19] op_sel_hi:[1,0]
	v_pk_fma_f32 v[70:71], v[70:71], 0.5, v[72:73] op_sel_hi:[1,0,1]
	v_pk_fma_f32 v[72:73], v[66:67], 0.5, v[74:75] op_sel_hi:[1,0,1]
	v_pk_fma_f32 v[66:67], v[64:65], 0.5, v[82:83] op_sel_hi:[1,0,1]
	v_pk_fma_f32 v[68:69], v[68:69], 0.5, v[80:81] op_sel_hi:[1,0,1]
	s_nop 0
	v_cvt_pk_bf16_f32 v64, v68, v69
	v_cvt_pk_bf16_f32 v65, v70, v71
	v_cvt_pk_bf16_f32 v66, v66, v67
	v_cvt_pk_bf16_f32 v67, v72, v73
	global_store_dwordx4 v[84:85], v[64:67], off offset:256
	s_nop 1
	s_waitcnt vmcnt(15)
	v_mov_b32_e32 v64, v200
	v_mov_b32_e32 v65, v201
	v_mov_b32_e32 v66, v202
	v_mov_b32_e32 v67, v203
	v_lshl_add_u64 v[68:69], s[12:13], 0, v[76:77]
	v_lshlrev_b32_e32 v70, 16, v64
	v_and_b32_e32 v71, 0xffff0000, v64
	v_lshlrev_b32_e32 v64, 16, v65
	v_and_b32_e32 v65, 0xffff0000, v65
	v_lshlrev_b32_e32 v72, 16, v66
	v_and_b32_e32 v73, 0xffff0000, v66
	v_lshlrev_b32_e32 v66, 16, v67
	v_and_b32_e32 v67, 0xffff0000, v67
	v_pk_mul_f32 v[64:65], v[64:65], s[18:19] op_sel_hi:[1,0]
	v_pk_mul_f32 v[72:73], v[72:73], s[18:19] op_sel_hi:[1,0]
	v_pk_mul_f32 v[66:67], v[66:67], s[18:19] op_sel_hi:[1,0]
	v_pk_mul_f32 v[70:71], v[70:71], s[18:19] op_sel_hi:[1,0]
	v_pk_fma_f32 v[62:63], v[62:63], 0.5, v[64:65] op_sel_hi:[1,0,1]
	v_pk_fma_f32 v[64:65], v[58:59], 0.5, v[66:67] op_sel_hi:[1,0,1]
	v_pk_fma_f32 v[58:59], v[56:57], 0.5, v[72:73] op_sel_hi:[1,0,1]
	v_pk_fma_f32 v[60:61], v[60:61], 0.5, v[70:71] op_sel_hi:[1,0,1]
	s_nop 0
	v_cvt_pk_bf16_f32 v56, v60, v61
	v_cvt_pk_bf16_f32 v57, v62, v63
	v_cvt_pk_bf16_f32 v58, v58, v59
	v_cvt_pk_bf16_f32 v59, v64, v65
	global_store_dwordx4 v[68:69], v[56:59], off
	s_nop 1
	s_waitcnt vmcnt(15)
	v_mov_b32_e32 v56, v204
	v_mov_b32_e32 v57, v205
	v_mov_b32_e32 v58, v206
	v_mov_b32_e32 v59, v207
	v_lshl_add_u64 v[60:61], v[144:145], 0, s[22:23]
	v_lshl_add_u64 v[62:63], s[10:11], 0, v[60:61]
	v_lshlrev_b32_e32 v64, 16, v56
	v_and_b32_e32 v65, 0xffff0000, v56
	v_lshlrev_b32_e32 v56, 16, v57
	v_and_b32_e32 v57, 0xffff0000, v57
	v_lshlrev_b32_e32 v66, 16, v58
	v_and_b32_e32 v67, 0xffff0000, v58
	v_lshlrev_b32_e32 v58, 16, v59
	v_and_b32_e32 v59, 0xffff0000, v59
	v_pk_mul_f32 v[56:57], v[56:57], s[18:19] op_sel_hi:[1,0]
	v_pk_mul_f32 v[66:67], v[66:67], s[18:19] op_sel_hi:[1,0]
	v_pk_mul_f32 v[58:59], v[58:59], s[18:19] op_sel_hi:[1,0]
	v_pk_mul_f32 v[64:65], v[64:65], s[18:19] op_sel_hi:[1,0]
	v_pk_fma_f32 v[54:55], v[54:55], 0.5, v[56:57] op_sel_hi:[1,0,1]
	v_pk_fma_f32 v[56:57], v[50:51], 0.5, v[58:59] op_sel_hi:[1,0,1]
	v_pk_fma_f32 v[50:51], v[48:49], 0.5, v[66:67] op_sel_hi:[1,0,1]
	v_pk_fma_f32 v[52:53], v[52:53], 0.5, v[64:65] op_sel_hi:[1,0,1]
	s_nop 0
	v_cvt_pk_bf16_f32 v48, v52, v53
	v_cvt_pk_bf16_f32 v49, v54, v55
	v_cvt_pk_bf16_f32 v50, v50, v51
	v_cvt_pk_bf16_f32 v51, v56, v57
	global_store_dwordx4 v[68:69], v[48:51], off offset:256
	s_nop 1
	s_waitcnt vmcnt(15)
	v_mov_b32_e32 v48, v208
	v_mov_b32_e32 v49, v209
	v_mov_b32_e32 v50, v210
	v_mov_b32_e32 v51, v211
	v_lshl_add_u64 v[52:53], s[12:13], 0, v[60:61]
	v_lshlrev_b32_e32 v54, 16, v48
	v_and_b32_e32 v55, 0xffff0000, v48
	v_lshlrev_b32_e32 v48, 16, v49
	v_and_b32_e32 v49, 0xffff0000, v49
	v_lshlrev_b32_e32 v56, 16, v50
	v_and_b32_e32 v57, 0xffff0000, v50
	v_lshlrev_b32_e32 v50, 16, v51
	v_and_b32_e32 v51, 0xffff0000, v51
	v_pk_mul_f32 v[48:49], v[48:49], s[18:19] op_sel_hi:[1,0]
	v_pk_mul_f32 v[56:57], v[56:57], s[18:19] op_sel_hi:[1,0]
	v_pk_mul_f32 v[50:51], v[50:51], s[18:19] op_sel_hi:[1,0]
	v_pk_mul_f32 v[54:55], v[54:55], s[18:19] op_sel_hi:[1,0]
	v_pk_fma_f32 v[46:47], v[46:47], 0.5, v[48:49] op_sel_hi:[1,0,1]
	v_pk_fma_f32 v[48:49], v[42:43], 0.5, v[50:51] op_sel_hi:[1,0,1]
	v_pk_fma_f32 v[42:43], v[40:41], 0.5, v[56:57] op_sel_hi:[1,0,1]
	v_pk_fma_f32 v[44:45], v[44:45], 0.5, v[54:55] op_sel_hi:[1,0,1]
	s_nop 0
	v_cvt_pk_bf16_f32 v40, v44, v45
	v_cvt_pk_bf16_f32 v41, v46, v47
	v_cvt_pk_bf16_f32 v42, v42, v43
	v_cvt_pk_bf16_f32 v43, v48, v49
	global_store_dwordx4 v[52:53], v[40:43], off
	s_nop 1
	s_waitcnt vmcnt(15)
	v_mov_b32_e32 v40, v214
	v_mov_b32_e32 v41, v215
	v_mov_b32_e32 v42, v216
	v_mov_b32_e32 v43, v217
	v_lshl_add_u64 v[44:45], v[144:145], 0, s[24:25]
	v_lshl_add_u64 v[46:47], s[10:11], 0, v[44:45]
	v_lshlrev_b32_e32 v48, 16, v40
	v_and_b32_e32 v49, 0xffff0000, v40
	v_lshlrev_b32_e32 v40, 16, v41
	v_and_b32_e32 v41, 0xffff0000, v41
	v_lshlrev_b32_e32 v50, 16, v42
	v_and_b32_e32 v51, 0xffff0000, v42
	v_lshlrev_b32_e32 v42, 16, v43
	v_and_b32_e32 v43, 0xffff0000, v43
	v_pk_mul_f32 v[40:41], v[40:41], s[18:19] op_sel_hi:[1,0]
	v_pk_mul_f32 v[50:51], v[50:51], s[18:19] op_sel_hi:[1,0]
	v_pk_mul_f32 v[42:43], v[42:43], s[18:19] op_sel_hi:[1,0]
	v_pk_mul_f32 v[48:49], v[48:49], s[18:19] op_sel_hi:[1,0]
	v_pk_fma_f32 v[38:39], v[38:39], 0.5, v[40:41] op_sel_hi:[1,0,1]
	v_pk_fma_f32 v[40:41], v[34:35], 0.5, v[42:43] op_sel_hi:[1,0,1]
	v_pk_fma_f32 v[34:35], v[32:33], 0.5, v[50:51] op_sel_hi:[1,0,1]
	v_pk_fma_f32 v[36:37], v[36:37], 0.5, v[48:49] op_sel_hi:[1,0,1]
	s_nop 0
	v_cvt_pk_bf16_f32 v32, v36, v37
	v_cvt_pk_bf16_f32 v33, v38, v39
	v_cvt_pk_bf16_f32 v34, v34, v35
	v_cvt_pk_bf16_f32 v35, v40, v41
	global_store_dwordx4 v[52:53], v[32:35], off offset:256
	s_nop 1
	s_waitcnt vmcnt(15)
	v_mov_b32_e32 v32, v218
	v_mov_b32_e32 v33, v219
	v_mov_b32_e32 v34, v220
	v_mov_b32_e32 v35, v221
	v_lshl_add_u64 v[36:37], s[12:13], 0, v[44:45]
	v_lshlrev_b32_e32 v38, 16, v32
	v_and_b32_e32 v39, 0xffff0000, v32
	v_lshlrev_b32_e32 v32, 16, v33
	v_and_b32_e32 v33, 0xffff0000, v33
	v_lshlrev_b32_e32 v40, 16, v34
	v_and_b32_e32 v41, 0xffff0000, v34
	v_lshlrev_b32_e32 v34, 16, v35
	v_and_b32_e32 v35, 0xffff0000, v35
	v_pk_mul_f32 v[32:33], v[32:33], s[18:19] op_sel_hi:[1,0]
	v_pk_mul_f32 v[40:41], v[40:41], s[18:19] op_sel_hi:[1,0]
	v_pk_mul_f32 v[34:35], v[34:35], s[18:19] op_sel_hi:[1,0]
	v_pk_mul_f32 v[38:39], v[38:39], s[18:19] op_sel_hi:[1,0]
	v_pk_fma_f32 v[30:31], v[30:31], 0.5, v[32:33] op_sel_hi:[1,0,1]
	v_pk_fma_f32 v[32:33], v[26:27], 0.5, v[34:35] op_sel_hi:[1,0,1]
	v_pk_fma_f32 v[26:27], v[24:25], 0.5, v[40:41] op_sel_hi:[1,0,1]
	v_pk_fma_f32 v[28:29], v[28:29], 0.5, v[38:39] op_sel_hi:[1,0,1]
	s_nop 0
	v_cvt_pk_bf16_f32 v24, v28, v29
	v_cvt_pk_bf16_f32 v25, v30, v31
	v_cvt_pk_bf16_f32 v26, v26, v27
	v_cvt_pk_bf16_f32 v27, v32, v33
	global_store_dwordx4 v[36:37], v[24:27], off
	s_nop 1
	s_waitcnt vmcnt(15)
	v_mov_b32_e32 v24, v222
	v_mov_b32_e32 v25, v223
	v_mov_b32_e32 v26, v224
	v_mov_b32_e32 v27, v225
	v_lshl_add_u64 v[28:29], v[144:145], 0, s[26:27]
	v_lshl_add_u64 v[30:31], s[10:11], 0, v[28:29]
	v_lshlrev_b32_e32 v32, 16, v24
	v_and_b32_e32 v33, 0xffff0000, v24
	v_lshlrev_b32_e32 v24, 16, v25
	v_and_b32_e32 v25, 0xffff0000, v25
	v_lshlrev_b32_e32 v34, 16, v26
	v_and_b32_e32 v35, 0xffff0000, v26
	v_lshlrev_b32_e32 v26, 16, v27
	v_and_b32_e32 v27, 0xffff0000, v27
	v_pk_mul_f32 v[24:25], v[24:25], s[18:19] op_sel_hi:[1,0]
	v_pk_mul_f32 v[34:35], v[34:35], s[18:19] op_sel_hi:[1,0]
	v_pk_mul_f32 v[26:27], v[26:27], s[18:19] op_sel_hi:[1,0]
	v_pk_mul_f32 v[32:33], v[32:33], s[18:19] op_sel_hi:[1,0]
	v_pk_fma_f32 v[22:23], v[22:23], 0.5, v[24:25] op_sel_hi:[1,0,1]
	v_pk_fma_f32 v[24:25], v[18:19], 0.5, v[26:27] op_sel_hi:[1,0,1]
	v_pk_fma_f32 v[18:19], v[16:17], 0.5, v[34:35] op_sel_hi:[1,0,1]
	v_pk_fma_f32 v[20:21], v[20:21], 0.5, v[32:33] op_sel_hi:[1,0,1]
	s_nop 0
	v_cvt_pk_bf16_f32 v16, v20, v21
	v_cvt_pk_bf16_f32 v17, v22, v23
	v_cvt_pk_bf16_f32 v18, v18, v19
	v_cvt_pk_bf16_f32 v19, v24, v25
	global_store_dwordx4 v[36:37], v[16:19], off offset:256
	s_nop 1
	s_waitcnt vmcnt(15)
	v_mov_b32_e32 v16, v226
	v_mov_b32_e32 v17, v227
	v_mov_b32_e32 v18, v228
	v_mov_b32_e32 v19, v229
	v_lshl_add_u64 v[20:21], s[12:13], 0, v[28:29]
	v_lshlrev_b32_e32 v22, 16, v16
	v_and_b32_e32 v23, 0xffff0000, v16
	v_lshlrev_b32_e32 v16, 16, v17
	v_and_b32_e32 v17, 0xffff0000, v17
	v_lshlrev_b32_e32 v24, 16, v18
	v_and_b32_e32 v25, 0xffff0000, v18
	v_lshlrev_b32_e32 v18, 16, v19
	v_and_b32_e32 v19, 0xffff0000, v19
	v_pk_mul_f32 v[16:17], v[16:17], s[18:19] op_sel_hi:[1,0]
	v_pk_mul_f32 v[24:25], v[24:25], s[18:19] op_sel_hi:[1,0]
	v_pk_mul_f32 v[18:19], v[18:19], s[18:19] op_sel_hi:[1,0]
	v_pk_mul_f32 v[22:23], v[22:23], s[18:19] op_sel_hi:[1,0]
	v_pk_fma_f32 v[14:15], v[14:15], 0.5, v[16:17] op_sel_hi:[1,0,1]
	v_pk_fma_f32 v[16:17], v[10:11], 0.5, v[18:19] op_sel_hi:[1,0,1]
	v_pk_fma_f32 v[10:11], v[8:9], 0.5, v[24:25] op_sel_hi:[1,0,1]
	v_pk_fma_f32 v[12:13], v[12:13], 0.5, v[22:23] op_sel_hi:[1,0,1]
	s_nop 0
	v_cvt_pk_bf16_f32 v8, v12, v13
	v_cvt_pk_bf16_f32 v9, v14, v15
	v_cvt_pk_bf16_f32 v10, v10, v11
	v_cvt_pk_bf16_f32 v11, v16, v17
	global_store_dwordx4 v[20:21], v[8:11], off
	s_nop 1
	s_waitcnt vmcnt(15)
	v_mov_b32_e32 v8, v230
	v_mov_b32_e32 v9, v231
	v_mov_b32_e32 v10, v232
	v_mov_b32_e32 v11, v233
	v_lshlrev_b32_e32 v12, 16, v8
	v_and_b32_e32 v13, 0xffff0000, v8
	v_lshlrev_b32_e32 v8, 16, v9
	v_and_b32_e32 v9, 0xffff0000, v9
	v_lshlrev_b32_e32 v14, 16, v10
	v_and_b32_e32 v15, 0xffff0000, v10
	v_lshlrev_b32_e32 v10, 16, v11
	v_and_b32_e32 v11, 0xffff0000, v11
	v_pk_mul_f32 v[8:9], v[8:9], s[18:19] op_sel_hi:[1,0]
	v_pk_mul_f32 v[14:15], v[14:15], s[18:19] op_sel_hi:[1,0]
	v_pk_mul_f32 v[10:11], v[10:11], s[18:19] op_sel_hi:[1,0]
	v_pk_mul_f32 v[12:13], v[12:13], s[18:19] op_sel_hi:[1,0]
	v_pk_fma_f32 v[6:7], v[6:7], 0.5, v[8:9] op_sel_hi:[1,0,1]
	v_pk_fma_f32 v[8:9], v[2:3], 0.5, v[10:11] op_sel_hi:[1,0,1]
	v_pk_fma_f32 v[2:3], v[0:1], 0.5, v[14:15] op_sel_hi:[1,0,1]
	v_pk_fma_f32 v[4:5], v[4:5], 0.5, v[12:13] op_sel_hi:[1,0,1]
	s_nop 0
	v_cvt_pk_bf16_f32 v0, v4, v5
	v_cvt_pk_bf16_f32 v1, v6, v7
	v_cvt_pk_bf16_f32 v2, v2, v3
	v_cvt_pk_bf16_f32 v3, v8, v9
	global_store_dwordx4 v[20:21], v[0:3], off offset:256
	s_cbranch_vccnz .LBB0_1092
	s_andn2_b64 vcc, exec, s[8:9]
	s_cbranch_vccnz .LBB0_1091
	s_barrier
	s_branch .LBB0_1091

	.amdhsa_kernel _Z8mega_fwd4Args
		.amdhsa_group_segment_fixed_size 0
		.amdhsa_private_segment_fixed_size 0
		.amdhsa_kernarg_size 488
		.amdhsa_user_sgpr_count 2
		.amdhsa_user_sgpr_dispatch_ptr 0
		.amdhsa_user_sgpr_queue_ptr 0
		.amdhsa_user_sgpr_kernarg_segment_ptr 1
		.amdhsa_user_sgpr_dispatch_id 0
		.amdhsa_user_sgpr_kernarg_preload_length 0
		.amdhsa_user_sgpr_kernarg_preload_offset 0
		.amdhsa_user_sgpr_private_segment_size 0
		.amdhsa_uses_dynamic_stack 0
		.amdhsa_enable_private_segment 0
		.amdhsa_system_sgpr_workgroup_id_x 1
		.amdhsa_system_sgpr_workgroup_id_y 0
		.amdhsa_system_sgpr_workgroup_id_z 0
		.amdhsa_system_sgpr_workgroup_info 0
		.amdhsa_system_vgpr_workitem_id 2
		.amdhsa_next_free_vgpr 255
		.amdhsa_next_free_sgpr 102
		.amdhsa_accum_offset 256
		.amdhsa_reserve_vcc 1
		.amdhsa_float_round_mode_32 0
		.amdhsa_float_round_mode_16_64 0
		.amdhsa_float_denorm_mode_32 3
		.amdhsa_float_denorm_mode_16_64 3
		.amdhsa_dx10_clamp 1
		.amdhsa_ieee_mode 1
		.amdhsa_fp16_overflow 0
		.amdhsa_tg_split 0
		.amdhsa_exception_fp_ieee_invalid_op 0
		.amdhsa_exception_fp_denorm_src 0
		.amdhsa_exception_fp_ieee_div_zero 0
		.amdhsa_exception_fp_ieee_overflow 0
		.amdhsa_exception_fp_ieee_underflow 0
		.amdhsa_exception_fp_ieee_inexact 0
		.amdhsa_exception_int_div_zero 0
	.end_amdhsa_kernel

amdhsa.kernels:
  - .agpr_count:     0
    .args:
      - .offset:         0
        .size:           232
        .value_kind:     by_value
      - .offset:         232
        .size:           4
        .value_kind:     hidden_block_count_x
      - .offset:         236
        .size:           4
        .value_kind:     hidden_block_count_y
      - .offset:         240
        .size:           4
        .value_kind:     hidden_block_count_z
      - .offset:         244
        .size:           2
        .value_kind:     hidden_group_size_x
      - .offset:         246
        .size:           2
        .value_kind:     hidden_group_size_y
      - .offset:         248
        .size:           2
        .value_kind:     hidden_group_size_z
      - .offset:         250
        .size:           2
        .value_kind:     hidden_remainder_x
      - .offset:         252
        .size:           2
        .value_kind:     hidden_remainder_y
      - .offset:         254
        .size:           2
        .value_kind:     hidden_remainder_z
      - .offset:         272
        .size:           8
        .value_kind:     hidden_global_offset_x
      - .offset:         280
        .size:           8
        .value_kind:     hidden_global_offset_y
      - .offset:         288
        .size:           8
        .value_kind:     hidden_global_offset_z
      - .offset:         296
        .size:           2
        .value_kind:     hidden_grid_dims
      - .offset:         320
        .size:           8
        .value_kind:     hidden_multigrid_sync_arg
      - .offset:         352
        .size:           4
        .value_kind:     hidden_dynamic_lds_size
    .group_segment_fixed_size: 0
    .kernarg_segment_align: 8
    .kernarg_segment_size: 488
    .language:       OpenCL C
    .language_version:
      - 2
      - 0
    .max_flat_workgroup_size: 512
    .name:           _Z8mega_fwd4Args
    .private_segment_fixed_size: 0
    .sgpr_count:     108
    .sgpr_spill_count: 4
    .symbol:         _Z8mega_fwd4Args.kd
    .uniform_work_group_size: 1
    .uses_dynamic_stack: false
    .vgpr_count:     255
    .vgpr_spill_count: 0
    .wavefront_size: 64
